# v10 + per-half K loops: leading half stages 4/4 DMAs per load segment with vmcnt waits deferred to the end of the MFMA blocks
# baseline (speedup 1.0000x reference)
; template <class Epi, class Sched, bool ALIGN_EPI = false, bool SP2 = false>
; __device__ __forceinline__ void gemm_phase(PG8_LAS unsigned char* lds, const Gemm g, const Sched& S, const Epi& E) {
;     ...
;         PG8_STAGE(PG8_SB(0, 0), cB, voffB); PG8_STAGE(PG8_SB(0, 1), cB + hB, voffB); PG8_STAGE(PG8_SA(0, 0), cA, voffA); PG8_STAGE(PG8_SA(0, 1), cA + hA, voffA);
;         if (wr == 1) PG8_BAR;
;         PG8_WAIT_V(2); PG8_BAR;
;         PG8_STAGE(PG8_SB(1, 0), cB + kstep, voffB); PG8_STAGE(PG8_SA(1, 0), cA + kstep, voffA); PG8_STAGE(PG8_SB(1, 1), cB + hB + kstep, voffB);
;         PG8_WAIT_V(6); PG8_BAR;
;     __device__ __forceinline__ void operator()(AccRef acc, const pg8::Unit& u, int wr, int wc, int fr, int fq) const {
;         const int pn = u.pn, row0 = u.pm * 256 + wr * 64 + fr, cl = wc * 32 + 8 * fq;
;         if (pn < 16) {
;             const bool isk = pn >= 8; const int h = pn & 7; bf16* dst = isk ? k : q;
;             const float lg2 = head_lg2(h);
; #pragma unroll
;             for (int ai = 0; ai < 2; ++ai) {
;                 f32x4 tcv[4][2], tsv[4][2];
; #pragma unroll
;                 for (int m = 0; m < 4; ++m) { const int pos_ = (row0 + ai * 128 + m * 16) & 4095; const float* tc = tcos + pos_ * 128 + cl; const float* ts = tsin + pos_ * 128 + cl;
;                     tcv[m][0] = *(const f32x4*)tc; tcv[m][1] = *(const f32x4*)(tc + 4); tsv[m][0] = *(const f32x4*)ts; tsv[m][1] = *(const f32x4*)(ts + 4); }
; #pragma unroll
;                 for (int m = 0; m < 4; ++m) {
;                     int r = row0 + ai * 128 + m * 16; asm volatile("" : "+v"(r)); const int pos = r & 4095;
;                     const f32x4 c0 = tcv[m][0], c1 = tcv[m][1], s0 = tsv[m][0], s1 = tsv[m][1];
;                     const f32x4 a0 = acc[ai][0][m][0], a1 = acc[ai][0][m][1], b0 = acc[ai][1][m][0], b1 = acc[ai][1][m][1];
;                     const f32x4 o10 = (a0 * c0 - b0 * s0) * 0.0625f, o11 = (a1 * c1 - b1 * s1) * 0.0625f;
;                     const f32x4 o20 = (a0 * s0 + b0 * c0) * 0.0625f, o21 = (a1 * s1 + b1 * c1) * 0.0625f;
;                     const size_t blk = ((size_t)(((r >> 12) * 8 + h) * 64 + (pos >> 6))) * 16384;
;                     const int nn = r & 63;
;                     bf16* rp = dst + blk + (size_t)(((((cl >> 5) * 2 + (nn >> 5)) * 2 + ((cl >> 4) & 1)) * 64 + ((cl >> 3) & 1) * 32 + (nn & 31)) * 8);
.LBB0_184:
	s_add_u32 s14, s0, 0x15800000
	s_waitcnt vmcnt(0)
	v_bfe_u32 v19, v10, 4, 2
	s_addc_u32 s15, s1, 0
	v_and_b32_e32 v18, 15, v10
	v_lshlrev_b32_e32 v20, 3, v19
	v_lshlrev_b32_e32 v19, 4, v19
	s_add_u32 s16, s0, 0x1d800000
	v_lshl_or_b32 v1, s5, 6, v18
	v_lshl_or_b32 v19, v18, 6, v19
	v_lshlrev_b32_e32 v18, 2, v18
	s_mov_b64 s[38:39], 0x80
	s_addc_u32 s17, s1, 0
	s_and_b32 s8, s4, 3
	s_lshl_b32 s4, s5, 13
	v_and_b32_e32 v21, 32, v18
	s_add_i32 m0, s74, 0x18000
	v_lshl_add_u64 v[8:9], v[8:9], 0, s[38:39]
	v_bitop3_b32 v22, v19, s4, v21 bitop3:0xde
	s_lshl_b32 s4, s8, 12
	s_waitcnt vmcnt(2)
	s_barrier
	global_load_lds_dwordx4 v[8:9], off
	v_lshl_add_u64 v[6:7], v[6:7], 0, s[38:39]
	s_add_i32 m0, s74, 0x1a000
	s_add_i32 s81, s74, 0x8000
	s_add_i32 s82, s74, 0xa000
	v_bitop3_b32 v223, v19, s4, v21 bitop3:0xde
	global_load_lds_dwordx4 v[6:7], off
	v_lshl_add_u64 v[4:5], v[4:5], 0, s[38:39]
	s_mov_b32 m0, s81
	s_add_u32 s4, s64, 0x80080
	global_load_lds_dwordx4 v[4:5], off
	v_lshl_add_u64 v[2:3], v[2:3], 0, s[38:39]
	s_mov_b32 m0, s82
	s_addc_u32 s5, s65, 0
	global_load_lds_dwordx4 v[2:3], off
	s_add_i32 m0, s74, 0x1c000
	v_lshl_add_u64 v[2:3], s[4:5], 0, v[196:197]
	global_load_lds_dwordx4 v[2:3], off
	v_lshl_add_u64 v[2:3], s[4:5], 0, v[200:201]
	s_add_i32 m0, s74, 0x1e000
	v_lshrrev_b32_e32 v17, 4, v10
	global_load_lds_dwordx4 v[2:3], off
	v_and_b32_e32 v2, 3, v10
	s_cmpk_lt_u32 s6, 0x100
	v_lshlrev_b32_e32 v3, 1, v2
	v_cmp_gt_u32_e64 s[6:7], 2, v2
	v_bfe_u32 v2, v17, 1, 1
	v_lshl_or_b32 v227, s8, 2, v2
	v_lshlrev_b32_e32 v2, 1, v10
	v_or_b32_e32 v5, v20, v3
	v_and_b32_e32 v228, 32, v2
	v_bitop3_b32 v2, v20, 18, v3 bitop3:0xc8
	v_lshrrev_b32_e32 v3, 2, v10
	s_cselect_b64 s[40:41], -1, 0
	s_lshl_b32 s9, s8, 8
	v_and_b32_e32 v6, 4, v10
	v_and_b32_e32 v3, 4, v3
	v_or3_b32 v5, v21, s9, v5
	v_and_b32_e32 v7, 1, v10
	v_and_or_b32 v3, v18, 40, v3
	v_lshlrev_b32_e32 v6, 1, v6
	v_cmp_eq_u32_e64 s[4:5], 0, v7
	v_or3_b32 v7, v3, v2, s9
	v_lshl_or_b32 v202, v5, 4, v6
	v_lshl_or_b32 v4, s8, 5, v20
	v_lshl_add_u64 v[2:3], s[0:1], 0, v[202:203]
	s_mov_b64 s[8:9], 0xd800000
	v_lshl_or_b32 v202, v7, 4, v6
	v_lshl_add_u64 v[204:205], v[2:3], 0, s[8:9]
	v_lshl_add_u64 v[2:3], s[0:1], 0, v[202:203]
	s_mov_b64 s[8:9], 0x11800000
	v_lshlrev_b32_e32 v202, 2, v4
	v_lshl_add_u64 v[206:207], v[2:3], 0, s[8:9]
	v_lshl_add_u64 v[2:3], s[0:1], 0, v[202:203]
	s_mov_b64 s[42:43], 0x100000
	s_mov_b64 s[8:9], 0x300000
	v_lshl_add_u64 v[208:209], v[2:3], 0, s[42:43]
	v_lshl_add_u64 v[210:211], v[2:3], 0, s[8:9]
	v_lshlrev_b32_e32 v2, 15, v11
	v_and_b32_e32 v2, 0xffff0000, v2
	v_lshl_add_u32 v2, v12, 12, v2
	v_and_b32_e32 v3, 1, v11
	v_lshl_or_b32 v2, v3, 6, v2
	v_lshl_add_u32 v212, v13, 1, v2
	v_lshlrev_b32_e32 v2, 15, v14
	v_and_b32_e32 v2, 0xffff0000, v2
	s_waitcnt vmcnt(6)
	v_lshl_add_u32 v2, v15, 12, v2
	v_and_b32_e32 v3, 1, v14
	v_lshl_or_b32 v2, v3, 6, v2
	s_add_i32 s84, 0, 0x10000
	s_add_i32 s85, 0, 0x14000
	v_or_b32_e32 v224, 0xffffdc00, v4
	v_or_b32_e32 v225, 0xffffe000, v4
	v_or_b32_e32 v226, 0xffffe800, v4
	s_waitcnt lgkmcnt(0)
	s_ashr_i32 s83, s78, 31
	v_mov_b32_e32 v213, v203
	v_lshl_add_u32 v214, v16, 1, v2
	v_mov_b32_e32 v215, v203
	v_mov_b64_e32 v[216:217], 0xd00
	v_mov_b64_e32 v[218:219], 0xcff
	v_add_u32_e32 v229, s84, v223
	v_add_u32_e32 v230, s85, v223
	v_add_u32_e32 v231, 0, v22
	s_mov_b32 s18, 0x58000
	s_mov_b32 s87, 0x80000
	s_mov_b64 s[44:45], 0x90000
	s_mov_b32 s88, 0x90000
	s_mov_b64 s[46:47], 0xa0000
	s_mov_b32 s89, 0xa0000
	s_mov_b64 s[48:49], 0xb0000
	s_mov_b32 s90, 0xb0000
	s_mov_b32 s91, 0x5040100
	s_mov_b32 s92, 0x7060302
	s_mov_b32 s93, 0x9800000
	s_mov_b32 s94, 0xc2fc0000
	s_mov_b32 s95, 0x800000
	s_mov_b32 s50, 0x3d800000
	v_mov_b32_e32 v232, 0x42800000
	v_mov_b32_e32 v233, 0x42000000
	v_not_b32_e32 v234, 63
	s_barrier
	v_readfirstlane_b32 s101, v0
	s_nop 3
	s_lshr_b32 s101, s101, 8
	s_branch .LBB0_187

; #define PG8_STAGE(bufoff, gbase, voff) do { _Pragma("unroll") for (int _i = 0; _i < 2; ++_i) \
;         __builtin_amdgcn_global_load_lds((const unsigned*)((const char*)(gbase) + (voff)[_i]), (PG8_LAS unsigned*)(lds + (bufoff) + ldsw + _i * 8192), 16, 0, 0); } while (0)
; #define PG8_LDA(dst, b, h) do { _Pragma("unroll") for (int m = 0; m < 4; ++m) _Pragma("unroll") for (int k = 0; k < 2; ++k) dst[m][k] = *(const PG8_LAS bf16x8*)(lds + PG8_SA(b, h) + aoff + m * 2048 + k * 1024); } while (0)
; #define PG8_LDB(dst, b, h) do { _Pragma("unroll") for (int n = 0; n < 2; ++n) _Pragma("unroll") for (int k = 0; k < 2; ++k) dst[n][k] = *(const PG8_LAS bf16x8*)(lds + PG8_SB(b, h) + boff + n * 2048 + k * 1024); } while (0)
; #define PG8_WAIT_V(n) asm volatile("s_waitcnt vmcnt(" #n ")" ::: "memory")
; #define PG8_WAIT_L(n) asm volatile("s_waitcnt lgkmcnt(" #n ")" ::: "memory")
; template <class Epi, class Sched, bool ALIGN_EPI = false, bool SP2 = false>
; __device__ __forceinline__ void gemm_phase(PG8_LAS unsigned char* lds, const Gemm g, const Sched& S, const Epi& E) {
;     ...
;     for (;;) {
;         const bool has_next = S.next(ui + 1, nxt);
;         const char* nA = has_next ? (const char*)g.A + (size_t)nxt.pm * tA + (size_t)nxt.pn * pnA : cA; const char* nB = has_next ? (const char*)g.Bt + (size_t)nxt.pn * tB : cB;
; #pragma nounroll
;         for (int t = 0; t < nt; t += 2) {
;             const bool last = (t == nt - 2);
;             const char* a1 = cA + (size_t)(t + 1) * kstep;
;             const char* a2 = last ? nA : cA + (size_t)(t + 2) * kstep; const char* b2 = last ? nB : cB + (size_t)(t + 2) * kstep;
;             const char* a3 = a2 + kstep; const char* b3 = b2 + kstep;
;             if (last && has_next) S.a_ready(nxt);
;             if constexpr (SP2) {
;             PG8_LDB(B0, 0, 0); PG8_LDB(B1, 0, 1); PG8_SCHED; PG8_LDA(At, 0, 0); PG8_STAGE(PG8_SA(1, 1), a1 + hA, voffA);
;             PG8_WAIT_V(8); PG8_WAIT_L(0); PG8_BAR; PG8_MMA(0, 0, At, B0); PG8_MMA(0, 1, At, B1); PG8_BAR; PG8_SCHED;
;     ...
; #pragma unroll
;         for (int a = 0; a < 2; ++a)
; #pragma unroll
;             for (int b = 0; b < 2; ++b)
; #pragma unroll
;                 for (int m = 0; m < 4; ++m)
; #pragma unroll
;                     for (int n = 0; n < 2; ++n) acc[a][b][m][n] = (f32x4){0.f, 0.f, 0.f, 0.f};
;         cur = nxt; cA = nA; cB = nB; ++ui;
.LBB0_189:
	s_ashr_i32 s55, s54, 31
	s_lshl_b64 s[56:57], s[54:55], 20
	s_add_u32 s56, s69, s56
	s_addc_u32 s57, s70, s57
	s_and_b64 s[58:59], s[8:9], exec
	s_cselect_b32 s11, s57, s63
	s_cselect_b32 s33, s56, s62
	s_ashr_i32 s53, s52, 31
	s_lshl_b64 s[58:59], s[52:53], 20
	s_add_u32 s58, s71, s58
	s_addc_u32 s59, s72, s59
	s_and_b64 s[66:67], s[8:9], exec
	s_cselect_b32 s53, s59, s65
	s_cselect_b32 s55, s58, s64
	s_add_u32 s62, s62, 0x80080
	s_addc_u32 s63, s63, 0
	s_add_u32 s61, s64, 0x100
	v_mov_b32_e32 v2, 0
	s_addc_u32 s96, s65, 0
	s_mov_b32 s97, -2
	v_mov_b32_e32 v3, v2
	v_mov_b64_e32 v[4:5], 0
	v_mov_b64_e32 v[6:7], 0
	v_mov_b64_e32 v[8:9], 0
	v_mov_b64_e32 v[10:11], 0
	v_mov_b64_e32 v[12:13], 0
	v_mov_b64_e32 v[14:15], 0
	v_mov_b64_e32 v[16:17], 0
	v_mov_b64_e32 v[18:19], 0
	v_mov_b64_e32 v[20:21], 0
	v_mov_b64_e32 v[22:23], 0
	v_mov_b64_e32 v[24:25], 0
	v_mov_b64_e32 v[26:27], 0
	v_mov_b64_e32 v[28:29], 0
	v_mov_b64_e32 v[30:31], 0
	v_mov_b64_e32 v[32:33], 0
	v_mov_b64_e32 v[34:35], 0
	v_mov_b64_e32 v[36:37], 0
	v_mov_b64_e32 v[38:39], 0
	v_mov_b64_e32 v[40:41], 0
	v_mov_b64_e32 v[42:43], 0
	v_mov_b64_e32 v[44:45], 0
	v_mov_b64_e32 v[46:47], 0
	v_mov_b64_e32 v[48:49], 0
	v_mov_b64_e32 v[50:51], 0
	v_mov_b64_e32 v[52:53], 0
	v_mov_b64_e32 v[54:55], 0
	v_mov_b64_e32 v[56:57], 0
	v_mov_b64_e32 v[58:59], 0
	v_mov_b64_e32 v[60:61], 0
	v_mov_b64_e32 v[62:63], 0
	v_mov_b64_e32 v[64:65], 0
	v_mov_b64_e32 v[66:67], 0
	v_mov_b64_e32 v[68:69], 0
	v_mov_b64_e32 v[70:71], 0
	v_mov_b64_e32 v[72:73], 0
	v_mov_b64_e32 v[74:75], 0
	v_mov_b64_e32 v[76:77], 0
	v_mov_b64_e32 v[78:79], 0
	v_mov_b64_e32 v[80:81], 0
	v_mov_b64_e32 v[82:83], 0
	v_mov_b64_e32 v[84:85], 0
	v_mov_b64_e32 v[86:87], 0
	v_mov_b64_e32 v[88:89], 0
	v_mov_b64_e32 v[90:91], 0
	v_mov_b64_e32 v[92:93], 0
	v_mov_b64_e32 v[94:95], 0
	v_mov_b64_e32 v[96:97], 0
	v_mov_b64_e32 v[98:99], 0
	v_mov_b64_e32 v[100:101], 0
	v_mov_b64_e32 v[102:103], 0
	v_mov_b64_e32 v[104:105], 0
	v_mov_b64_e32 v[106:107], 0
	v_mov_b64_e32 v[108:109], 0
	v_mov_b64_e32 v[110:111], 0
	v_mov_b64_e32 v[112:113], 0
	v_mov_b64_e32 v[114:115], 0
	v_mov_b64_e32 v[116:117], 0
	v_mov_b64_e32 v[118:119], 0
	v_mov_b64_e32 v[120:121], 0
	v_mov_b64_e32 v[122:123], 0
	v_mov_b64_e32 v[124:125], 0
	v_mov_b64_e32 v[126:127], 0
	v_mov_b64_e32 v[128:129], 0
	s_add_u32 s98, s62, 0xfff80000
	s_addc_u32 s99, s63, -1
	s_cmp_eq_u32 s101, 0
	s_cbranch_scc0 .Lkt_0
.LBB0_190:
	ds_read_b128 v[130:133], v229
	ds_read_b128 v[134:137], v229 offset:1024
	ds_read_b128 v[138:141], v229 offset:2048
	ds_read_b128 v[142:145], v229 offset:3072
	ds_read_b128 v[146:149], v230
	ds_read_b128 v[150:153], v230 offset:1024
	ds_read_b128 v[154:157], v230 offset:2048
	ds_read_b128 v[158:161], v230 offset:3072
	s_add_u32 s64, s62, 0xfff80080
	s_addc_u32 s65, s63, -1
	s_cmp_eq_u32 s97, 28
	s_cselect_b32 s67, s11, s65
	s_cselect_b32 s66, s33, s64
	s_cselect_b32 s65, s53, s96
	s_cselect_b32 s64, s55, s61
	s_add_i32 m0, s74, 0xc000
	ds_read_b128 v[162:165], v231
	ds_read_b128 v[166:169], v231 offset:1024
	ds_read_b128 v[170:173], v231 offset:2048
	ds_read_b128 v[174:177], v231 offset:3072
	ds_read_b128 v[178:181], v231 offset:4096
	ds_read_b128 v[182:185], v231 offset:5120
	ds_read_b128 v[186:189], v231 offset:6144
	ds_read_b128 v[190:193], v231 offset:7168
	global_load_lds_dwordx4 v212, s[62:63]
	s_add_i32 m0, s74, 0xe000
	s_nop 0
	global_load_lds_dwordx4 v214, s[62:63]
	s_mov_b32 m0, s81
	s_nop 0
	global_load_lds_dwordx4 v194, s[98:99]
	s_mov_b32 m0, s82
	s_nop 0
	global_load_lds_dwordx4 v198, s[98:99]
	s_waitcnt lgkmcnt(0)
	s_barrier
	s_waitcnt lgkmcnt(0)
	v_mfma_f32_16x16x32_bf16 v[126:129], v[130:133], v[162:165], v[126:129]
	v_mfma_f32_16x16x32_bf16 v[122:125], v[138:141], v[162:165], v[122:125]
	v_mfma_f32_16x16x32_bf16 v[110:113], v[130:133], v[170:173], v[110:113]
	v_mfma_f32_16x16x32_bf16 v[106:109], v[138:141], v[170:173], v[106:109]
	v_mfma_f32_16x16x32_bf16 v[94:97], v[130:133], v[178:181], v[94:97]
	v_mfma_f32_16x16x32_bf16 v[90:93], v[138:141], v[178:181], v[90:93]
	v_mfma_f32_16x16x32_bf16 v[78:81], v[130:133], v[186:189], v[78:81]
	v_mfma_f32_16x16x32_bf16 v[74:77], v[138:141], v[186:189], v[74:77]
	v_mfma_f32_16x16x32_bf16 v[126:129], v[134:137], v[166:169], v[126:129]
	v_mfma_f32_16x16x32_bf16 v[122:125], v[142:145], v[166:169], v[122:125]
	v_mfma_f32_16x16x32_bf16 v[110:113], v[134:137], v[174:177], v[110:113]
	v_mfma_f32_16x16x32_bf16 v[106:109], v[142:145], v[174:177], v[106:109]
	v_mfma_f32_16x16x32_bf16 v[94:97], v[134:137], v[182:185], v[94:97]
	v_mfma_f32_16x16x32_bf16 v[90:93], v[142:145], v[182:185], v[90:93]
	v_mfma_f32_16x16x32_bf16 v[78:81], v[134:137], v[190:193], v[78:81]
	v_mfma_f32_16x16x32_bf16 v[74:77], v[142:145], v[190:193], v[74:77]
	v_mfma_f32_16x16x32_bf16 v[118:121], v[146:149], v[162:165], v[118:121]
	v_mfma_f32_16x16x32_bf16 v[114:117], v[154:157], v[162:165], v[114:117]
	v_mfma_f32_16x16x32_bf16 v[102:105], v[146:149], v[170:173], v[102:105]
	v_mfma_f32_16x16x32_bf16 v[98:101], v[154:157], v[170:173], v[98:101]
	v_mfma_f32_16x16x32_bf16 v[86:89], v[146:149], v[178:181], v[86:89]
	v_mfma_f32_16x16x32_bf16 v[82:85], v[154:157], v[178:181], v[82:85]
	v_mfma_f32_16x16x32_bf16 v[70:73], v[146:149], v[186:189], v[70:73]
	v_mfma_f32_16x16x32_bf16 v[66:69], v[154:157], v[186:189], v[66:69]
	v_mfma_f32_16x16x32_bf16 v[118:121], v[150:153], v[166:169], v[118:121]
	v_mfma_f32_16x16x32_bf16 v[114:117], v[158:161], v[166:169], v[114:117]
	v_mfma_f32_16x16x32_bf16 v[102:105], v[150:153], v[174:177], v[102:105]
	v_mfma_f32_16x16x32_bf16 v[98:101], v[158:161], v[174:177], v[98:101]
	v_mfma_f32_16x16x32_bf16 v[86:89], v[150:153], v[182:185], v[86:89]
	v_mfma_f32_16x16x32_bf16 v[82:85], v[158:161], v[182:185], v[82:85]
	v_mfma_f32_16x16x32_bf16 v[70:73], v[150:153], v[190:193], v[70:73]
	v_mfma_f32_16x16x32_bf16 v[66:69], v[158:161], v[190:193], v[66:69]
	s_waitcnt vmcnt(8)
	s_barrier
; #define PG8_STAGE(bufoff, gbase, voff) do { _Pragma("unroll") for (int _i = 0; _i < 2; ++_i) \
;         __builtin_amdgcn_global_load_lds((const unsigned*)((const char*)(gbase) + (voff)[_i]), (PG8_LAS unsigned*)(lds + (bufoff) + ldsw + _i * 8192), 16, 0, 0); } while (0)
; #define PG8_LDA(dst, b, h) do { _Pragma("unroll") for (int m = 0; m < 4; ++m) _Pragma("unroll") for (int k = 0; k < 2; ++k) dst[m][k] = *(const PG8_LAS bf16x8*)(lds + PG8_SA(b, h) + aoff + m * 2048 + k * 1024); } while (0)
; #define PG8_LDB(dst, b, h) do { _Pragma("unroll") for (int n = 0; n < 2; ++n) _Pragma("unroll") for (int k = 0; k < 2; ++k) dst[n][k] = *(const PG8_LAS bf16x8*)(lds + PG8_SB(b, h) + boff + n * 2048 + k * 1024); } while (0)
; #define PG8_MMA(ai, bj, At, Bt) do { __builtin_amdgcn_s_setprio(1); _Pragma("unroll") for (int m = 0; m < 4; ++m) _Pragma("unroll") for (int n = 0; n < 2; ++n) _Pragma("unroll") for (int k = 0; k < 2; ++k) \
;         acc[ai][bj][m][n] = __builtin_amdgcn_mfma_f32_16x16x32_bf16(Bt[n][k], At[m][k], acc[ai][bj][m][n], 0, 0, 0); __builtin_amdgcn_s_setprio(0); } while (0)
; #define PG8_WAIT_V(n) asm volatile("s_waitcnt vmcnt(" #n ")" ::: "memory")
; #define PG8_WAIT_L(n) asm volatile("s_waitcnt lgkmcnt(" #n ")" ::: "memory")
; #define PG8_BAR __builtin_amdgcn_s_barrier()
; #define PG8_SCHED __builtin_amdgcn_sched_barrier(0)
; template <class Epi, class Sched, bool ALIGN_EPI = false, bool SP2 = false>
; __device__ __forceinline__ void gemm_phase(PG8_LAS unsigned char* lds, const Gemm g, const Sched& S, const Epi& E) {
;     ...
;             PG8_LDA(At, 0, 1); PG8_STAGE(PG8_SB(0, 0), b2, voffB); PG8_STAGE(PG8_SB(0, 1), b2 + hB, voffB); PG8_STAGE(PG8_SA(0, 0), a2, voffA);
;             PG8_WAIT_V(8); PG8_WAIT_L(0); PG8_BAR; PG8_MMA(1, 0, At, B0); PG8_MMA(1, 1, At, B1); PG8_BAR; PG8_SCHED;
;             PG8_LDB(B0, 1, 0); PG8_LDB(B1, 1, 1); PG8_SCHED; PG8_LDA(At, 1, 0); PG8_STAGE(PG8_SA(0, 1), a2 + hA, voffA);
;             PG8_WAIT_V(8); PG8_WAIT_L(0); PG8_BAR; PG8_MMA(0, 0, At, B0); PG8_MMA(0, 1, At, B1); PG8_BAR; PG8_SCHED;
	s_add_i32 vcc_lo, s84, s73
	s_add_u32 s34, s64, s38
	s_addc_u32 s35, s65, s39
	s_mov_b32 m0, vcc_lo
	ds_read_b128 v[162:165], v231 offset:16384
	ds_read_b128 v[166:169], v231 offset:17408
	ds_read_b128 v[170:173], v231 offset:18432
	ds_read_b128 v[174:177], v231 offset:19456
	ds_read_b128 v[178:181], v231 offset:20480
	ds_read_b128 v[182:185], v231 offset:21504
	ds_read_b128 v[186:189], v231 offset:22528
	ds_read_b128 v[190:193], v231 offset:23552
	global_load_lds_dwordx4 v196, s[64:65]
	s_add_i32 m0, vcc_lo, 0x2000
	s_add_u32 vcc_lo, s64, 0x80000
	s_addc_u32 vcc_hi, s65, 0
	s_add_i32 s86, s85, s73
	global_load_lds_dwordx4 v200, s[64:65]
	s_mov_b32 m0, s86
	s_nop 0
	global_load_lds_dwordx4 v196, vcc
	s_add_i32 m0, s86, 0x2000
	s_nop 0
	global_load_lds_dwordx4 v200, vcc
	s_add_u32 s98, s66, s38
	s_addc_u32 s99, s67, s39
	s_waitcnt lgkmcnt(0)
	s_barrier
	s_waitcnt lgkmcnt(0)
	v_mfma_f32_16x16x32_bf16 v[62:65], v[130:133], v[162:165], v[62:65]
	v_mfma_f32_16x16x32_bf16 v[58:61], v[138:141], v[162:165], v[58:61]
	v_mfma_f32_16x16x32_bf16 v[46:49], v[130:133], v[170:173], v[46:49]
	v_mfma_f32_16x16x32_bf16 v[42:45], v[138:141], v[170:173], v[42:45]
	v_mfma_f32_16x16x32_bf16 v[30:33], v[130:133], v[178:181], v[30:33]
	v_mfma_f32_16x16x32_bf16 v[26:29], v[138:141], v[178:181], v[26:29]
	v_mfma_f32_16x16x32_bf16 v[14:17], v[130:133], v[186:189], v[14:17]
	v_mfma_f32_16x16x32_bf16 v[10:13], v[138:141], v[186:189], v[10:13]
	v_mfma_f32_16x16x32_bf16 v[62:65], v[134:137], v[166:169], v[62:65]
	v_mfma_f32_16x16x32_bf16 v[58:61], v[142:145], v[166:169], v[58:61]
	v_mfma_f32_16x16x32_bf16 v[46:49], v[134:137], v[174:177], v[46:49]
	v_mfma_f32_16x16x32_bf16 v[42:45], v[142:145], v[174:177], v[42:45]
	v_mfma_f32_16x16x32_bf16 v[30:33], v[134:137], v[182:185], v[30:33]
	v_mfma_f32_16x16x32_bf16 v[26:29], v[142:145], v[182:185], v[26:29]
	v_mfma_f32_16x16x32_bf16 v[14:17], v[134:137], v[190:193], v[14:17]
	v_mfma_f32_16x16x32_bf16 v[10:13], v[142:145], v[190:193], v[10:13]
	v_mfma_f32_16x16x32_bf16 v[54:57], v[146:149], v[162:165], v[54:57]
	v_mfma_f32_16x16x32_bf16 v[50:53], v[154:157], v[162:165], v[50:53]
	v_mfma_f32_16x16x32_bf16 v[38:41], v[146:149], v[170:173], v[38:41]
	v_mfma_f32_16x16x32_bf16 v[34:37], v[154:157], v[170:173], v[34:37]
	v_mfma_f32_16x16x32_bf16 v[22:25], v[146:149], v[178:181], v[22:25]
	v_mfma_f32_16x16x32_bf16 v[18:21], v[154:157], v[178:181], v[18:21]
	v_mfma_f32_16x16x32_bf16 v[6:9], v[146:149], v[186:189], v[6:9]
	v_mfma_f32_16x16x32_bf16 v[2:5], v[154:157], v[186:189], v[2:5]
	v_mfma_f32_16x16x32_bf16 v[54:57], v[150:153], v[166:169], v[54:57]
	v_mfma_f32_16x16x32_bf16 v[50:53], v[158:161], v[166:169], v[50:53]
	v_mfma_f32_16x16x32_bf16 v[38:41], v[150:153], v[174:177], v[38:41]
	v_mfma_f32_16x16x32_bf16 v[34:37], v[158:161], v[174:177], v[34:37]
	v_mfma_f32_16x16x32_bf16 v[22:25], v[150:153], v[182:185], v[22:25]
	v_mfma_f32_16x16x32_bf16 v[18:21], v[158:161], v[182:185], v[18:21]
	v_mfma_f32_16x16x32_bf16 v[6:9], v[150:153], v[190:193], v[6:9]
	v_mfma_f32_16x16x32_bf16 v[2:5], v[158:161], v[190:193], v[2:5]
	s_waitcnt vmcnt(4)
	s_barrier
	s_add_i32 s86, 0, 0x18000
	s_add_i32 vcc_lo, 0, 0x1c000
	v_add_u32_e32 v142, s86, v223
	v_add_u32_e32 v158, vcc_lo, v223
	ds_read_b128 v[130:133], v142
	ds_read_b128 v[134:137], v142 offset:1024
	ds_read_b128 v[138:141], v142 offset:2048
	ds_read_b128 v[142:145], v142 offset:3072
	ds_read_b128 v[146:149], v158
	ds_read_b128 v[150:153], v158 offset:1024
	ds_read_b128 v[154:157], v158 offset:2048
	ds_read_b128 v[158:161], v158 offset:3072
	ds_read_b128 v[162:165], v231 offset:32768
	ds_read_b128 v[166:169], v231 offset:33792
	ds_read_b128 v[170:173], v231 offset:34816
	ds_read_b128 v[174:177], v231 offset:35840
	ds_read_b128 v[178:181], v231 offset:36864
	ds_read_b128 v[182:185], v231 offset:37888
	ds_read_b128 v[186:189], v231 offset:38912
	ds_read_b128 v[190:193], v231 offset:39936
	s_mov_b32 m0, s74
	s_nop 0
	global_load_lds_dwordx4 v194, s[66:67]
	s_mov_b32 m0, s75
	s_nop 0
	global_load_lds_dwordx4 v198, s[66:67]
	s_add_u32 s66, s66, 0x80000
	s_addc_u32 s67, s67, 0
	s_mov_b32 m0, s76
	s_nop 0
	global_load_lds_dwordx4 v194, s[66:67]
	s_mov_b32 m0, s77
	s_nop 0
	global_load_lds_dwordx4 v198, s[66:67]
	s_waitcnt lgkmcnt(0)
	s_barrier
; #define PG8_STAGE(bufoff, gbase, voff) do { _Pragma("unroll") for (int _i = 0; _i < 2; ++_i) \
;         __builtin_amdgcn_global_load_lds((const unsigned*)((const char*)(gbase) + (voff)[_i]), (PG8_LAS unsigned*)(lds + (bufoff) + ldsw + _i * 8192), 16, 0, 0); } while (0)
; #define PG8_LDA(dst, b, h) do { _Pragma("unroll") for (int m = 0; m < 4; ++m) _Pragma("unroll") for (int k = 0; k < 2; ++k) dst[m][k] = *(const PG8_LAS bf16x8*)(lds + PG8_SA(b, h) + aoff + m * 2048 + k * 1024); } while (0)
; #define PG8_MMA(ai, bj, At, Bt) do { __builtin_amdgcn_s_setprio(1); _Pragma("unroll") for (int m = 0; m < 4; ++m) _Pragma("unroll") for (int n = 0; n < 2; ++n) _Pragma("unroll") for (int k = 0; k < 2; ++k) \
;         acc[ai][bj][m][n] = __builtin_amdgcn_mfma_f32_16x16x32_bf16(Bt[n][k], At[m][k], acc[ai][bj][m][n], 0, 0, 0); __builtin_amdgcn_s_setprio(0); } while (0)
; #define PG8_WAIT_V(n) asm volatile("s_waitcnt vmcnt(" #n ")" ::: "memory")
; #define PG8_WAIT_L(n) asm volatile("s_waitcnt lgkmcnt(" #n ")" ::: "memory")
; #define PG8_BAR __builtin_amdgcn_s_barrier()
; #define PG8_SCHED __builtin_amdgcn_sched_barrier(0)
; template <class Epi, class Sched, bool ALIGN_EPI = false, bool SP2 = false>
; __device__ __forceinline__ void gemm_phase(PG8_LAS unsigned char* lds, const Gemm g, const Sched& S, const Epi& E) {
;     ...
;             PG8_WAIT_V(8); PG8_WAIT_L(0); PG8_BAR; PG8_MMA(0, 0, At, B0); PG8_MMA(0, 1, At, B1); PG8_BAR; PG8_SCHED;
;             PG8_LDA(At, 1, 1); PG8_STAGE(PG8_SB(1, 0), b3, voffB); PG8_STAGE(PG8_SB(1, 1), b3 + hB, voffB); PG8_STAGE(PG8_SA(1, 0), a3, voffA);
;             PG8_WAIT_V(8); PG8_WAIT_L(0); PG8_BAR; PG8_MMA(1, 0, At, B0); PG8_MMA(1, 1, At, B1); PG8_BAR; PG8_SCHED;
	s_waitcnt lgkmcnt(0)
	v_mfma_f32_16x16x32_bf16 v[126:129], v[130:133], v[162:165], v[126:129]
	v_mfma_f32_16x16x32_bf16 v[122:125], v[138:141], v[162:165], v[122:125]
	v_mfma_f32_16x16x32_bf16 v[110:113], v[130:133], v[170:173], v[110:113]
	v_mfma_f32_16x16x32_bf16 v[106:109], v[138:141], v[170:173], v[106:109]
	v_mfma_f32_16x16x32_bf16 v[94:97], v[130:133], v[178:181], v[94:97]
	v_mfma_f32_16x16x32_bf16 v[90:93], v[138:141], v[178:181], v[90:93]
	v_mfma_f32_16x16x32_bf16 v[78:81], v[130:133], v[186:189], v[78:81]
	v_mfma_f32_16x16x32_bf16 v[74:77], v[138:141], v[186:189], v[74:77]
	v_mfma_f32_16x16x32_bf16 v[126:129], v[134:137], v[166:169], v[126:129]
	v_mfma_f32_16x16x32_bf16 v[122:125], v[142:145], v[166:169], v[122:125]
	v_mfma_f32_16x16x32_bf16 v[110:113], v[134:137], v[174:177], v[110:113]
	v_mfma_f32_16x16x32_bf16 v[106:109], v[142:145], v[174:177], v[106:109]
	v_mfma_f32_16x16x32_bf16 v[94:97], v[134:137], v[182:185], v[94:97]
	v_mfma_f32_16x16x32_bf16 v[90:93], v[142:145], v[182:185], v[90:93]
	v_mfma_f32_16x16x32_bf16 v[78:81], v[134:137], v[190:193], v[78:81]
	v_mfma_f32_16x16x32_bf16 v[74:77], v[142:145], v[190:193], v[74:77]
	v_mfma_f32_16x16x32_bf16 v[118:121], v[146:149], v[162:165], v[118:121]
	v_mfma_f32_16x16x32_bf16 v[114:117], v[154:157], v[162:165], v[114:117]
	v_mfma_f32_16x16x32_bf16 v[102:105], v[146:149], v[170:173], v[102:105]
	v_mfma_f32_16x16x32_bf16 v[98:101], v[154:157], v[170:173], v[98:101]
	v_mfma_f32_16x16x32_bf16 v[86:89], v[146:149], v[178:181], v[86:89]
	v_mfma_f32_16x16x32_bf16 v[82:85], v[154:157], v[178:181], v[82:85]
	v_mfma_f32_16x16x32_bf16 v[70:73], v[146:149], v[186:189], v[70:73]
	v_mfma_f32_16x16x32_bf16 v[66:69], v[154:157], v[186:189], v[66:69]
	v_mfma_f32_16x16x32_bf16 v[118:121], v[150:153], v[166:169], v[118:121]
	v_mfma_f32_16x16x32_bf16 v[114:117], v[158:161], v[166:169], v[114:117]
	v_mfma_f32_16x16x32_bf16 v[102:105], v[150:153], v[174:177], v[102:105]
	v_mfma_f32_16x16x32_bf16 v[98:101], v[158:161], v[174:177], v[98:101]
	v_mfma_f32_16x16x32_bf16 v[86:89], v[150:153], v[182:185], v[86:89]
	v_mfma_f32_16x16x32_bf16 v[82:85], v[158:161], v[182:185], v[82:85]
	v_mfma_f32_16x16x32_bf16 v[70:73], v[150:153], v[190:193], v[70:73]
	v_mfma_f32_16x16x32_bf16 v[66:69], v[158:161], v[190:193], v[66:69]
	s_barrier
	s_add_i32 s66, s86, s73
	s_mov_b32 m0, s66
	ds_read_b128 v[162:165], v231 offset:49152
	ds_read_b128 v[166:169], v231 offset:50176
	ds_read_b128 v[170:173], v231 offset:51200
	ds_read_b128 v[174:177], v231 offset:52224
	ds_read_b128 v[178:181], v231 offset:53248
	ds_read_b128 v[182:185], v231 offset:54272
	ds_read_b128 v[186:189], v231 offset:55296
	ds_read_b128 v[190:193], v231 offset:56320
	global_load_lds_dwordx4 v196, s[34:35]
	s_add_i32 m0, s66, 0x2000
	s_add_u32 s64, s64, 0x80080
	s_addc_u32 s65, s65, 0
	s_add_i32 s66, vcc_lo, s73
	global_load_lds_dwordx4 v200, s[34:35]
	s_mov_b32 m0, s66
	s_nop 0
	global_load_lds_dwordx4 v196, s[64:65]
	s_add_i32 m0, s66, 0x2000
	s_nop 0
	global_load_lds_dwordx4 v200, s[64:65]
	s_waitcnt lgkmcnt(0)
	s_barrier
	s_waitcnt lgkmcnt(0)
	v_mfma_f32_16x16x32_bf16 v[62:65], v[130:133], v[162:165], v[62:65]
	v_mfma_f32_16x16x32_bf16 v[58:61], v[138:141], v[162:165], v[58:61]
	v_mfma_f32_16x16x32_bf16 v[46:49], v[130:133], v[170:173], v[46:49]
	v_mfma_f32_16x16x32_bf16 v[42:45], v[138:141], v[170:173], v[42:45]
	v_mfma_f32_16x16x32_bf16 v[30:33], v[130:133], v[178:181], v[30:33]
	v_mfma_f32_16x16x32_bf16 v[26:29], v[138:141], v[178:181], v[26:29]
	v_mfma_f32_16x16x32_bf16 v[14:17], v[130:133], v[186:189], v[14:17]
	v_mfma_f32_16x16x32_bf16 v[10:13], v[138:141], v[186:189], v[10:13]
	v_mfma_f32_16x16x32_bf16 v[62:65], v[134:137], v[166:169], v[62:65]
	v_mfma_f32_16x16x32_bf16 v[58:61], v[142:145], v[166:169], v[58:61]
	v_mfma_f32_16x16x32_bf16 v[46:49], v[134:137], v[174:177], v[46:49]
	v_mfma_f32_16x16x32_bf16 v[42:45], v[142:145], v[174:177], v[42:45]
	v_mfma_f32_16x16x32_bf16 v[30:33], v[134:137], v[182:185], v[30:33]
	v_mfma_f32_16x16x32_bf16 v[26:29], v[142:145], v[182:185], v[26:29]
	v_mfma_f32_16x16x32_bf16 v[14:17], v[134:137], v[190:193], v[14:17]
	v_mfma_f32_16x16x32_bf16 v[10:13], v[142:145], v[190:193], v[10:13]
	v_mfma_f32_16x16x32_bf16 v[54:57], v[146:149], v[162:165], v[54:57]
	v_mfma_f32_16x16x32_bf16 v[50:53], v[154:157], v[162:165], v[50:53]
	v_mfma_f32_16x16x32_bf16 v[38:41], v[146:149], v[170:173], v[38:41]
	v_mfma_f32_16x16x32_bf16 v[34:37], v[154:157], v[170:173], v[34:37]
	v_mfma_f32_16x16x32_bf16 v[22:25], v[146:149], v[178:181], v[22:25]
	v_mfma_f32_16x16x32_bf16 v[18:21], v[154:157], v[178:181], v[18:21]
	v_mfma_f32_16x16x32_bf16 v[6:9], v[146:149], v[186:189], v[6:9]
	v_mfma_f32_16x16x32_bf16 v[2:5], v[154:157], v[186:189], v[2:5]
	v_mfma_f32_16x16x32_bf16 v[54:57], v[150:153], v[166:169], v[54:57]
	v_mfma_f32_16x16x32_bf16 v[50:53], v[158:161], v[166:169], v[50:53]
	v_mfma_f32_16x16x32_bf16 v[38:41], v[150:153], v[174:177], v[38:41]
	v_mfma_f32_16x16x32_bf16 v[34:37], v[158:161], v[174:177], v[34:37]
	v_mfma_f32_16x16x32_bf16 v[22:25], v[150:153], v[182:185], v[22:25]
	v_mfma_f32_16x16x32_bf16 v[18:21], v[158:161], v[182:185], v[18:21]
	v_mfma_f32_16x16x32_bf16 v[6:9], v[150:153], v[190:193], v[6:9]
	v_mfma_f32_16x16x32_bf16 v[2:5], v[158:161], v[190:193], v[2:5]
	s_waitcnt vmcnt(6)
	s_barrier
	s_add_i32 s97, s97, 2
	s_add_u32 s62, s62, 0x100
	s_addc_u32 s63, s63, 0
	s_add_u32 s61, s61, 0x100
	s_addc_u32 s96, s96, 0
	s_cmp_gt_u32 s97, 29
	s_cbranch_scc0 .LBB0_190
	s_branch .Lkafter_0

; #define PG8_BAR __builtin_amdgcn_s_barrier()
; template <class Epi, class Sched, bool ALIGN_EPI = false, bool SP2 = false>
; __device__ __forceinline__ void gemm_phase(PG8_LAS unsigned char* lds, const Gemm g, const Sched& S, const Epi& E) {
;     ...
;         if constexpr (ALIGN_EPI) { if (wr == 0) PG8_BAR; }
;         if constexpr (!Epi::AFTER_DRAIN) { E(acc, cur, wr, wc, fr, fq); S.done(cur); }
;     __device__ __forceinline__ void operator()(AccRef acc, const pg8::Unit& u, int wr, int wc, int fr, int fq) const {
;         const int pn = u.pn, row0 = u.pm * 256 + wr * 64 + fr, cl = wc * 32 + 8 * fq;
;         if (pn < 16) {
.Lkafter_0:
	s_and_b64 vcc, exec, s[40:41]
	s_cbranch_vccz .LBB0_211
	s_barrier
	v_lshl_add_u32 v220, s60, 8, v1
	s_cmp_gt_i32 s10, 15
	s_mov_b64 s[60:61], -1
	s_cbranch_scc1 .LBB0_212

; #define PG8_STAGE(bufoff, gbase, voff) do { _Pragma("unroll") for (int _i = 0; _i < 2; ++_i) \
;         __builtin_amdgcn_global_load_lds((const unsigned*)((const char*)(gbase) + (voff)[_i]), (PG8_LAS unsigned*)(lds + (bufoff) + ldsw + _i * 8192), 16, 0, 0); } while (0)
; #define PG8_WAIT_V(n) asm volatile("s_waitcnt vmcnt(" #n ")" ::: "memory")
; #define PG8_BAR __builtin_amdgcn_s_barrier()
; template <class Epi, class Sched, bool ALIGN_EPI = false, bool SP2 = false>
; __device__ __forceinline__ void gemm_phase(PG8_LAS unsigned char* lds, const Gemm g, const Sched& S, const Epi& E) {
;     ...
;     const int tid = tid_o, wid = __builtin_amdgcn_readfirstlane(tid >> 6), lane = tid & 63, wr = wid >> 2, wc = wid & 3, fr = lane & 15, fq = lane >> 4;
;     const int K = g.K, nt = K / BK;
;     unsigned voffA[2], voffB[2];
; #pragma unroll
;     for (int i = 0; i < 2; ++i) { int R, C; stage_rc(tid * 16 + i * 8192, R, C); const int Rb = Epi::PERM ? ((R & ~31) + perm32(R & 31)) : R;
;         voffA[i] = (unsigned)(R * g.lda + C) * 2u; voffB[i] = (unsigned)(Rb * g.ldb + C) * 2u; }
;     const size_t kstep = (size_t)(BK * 2);
;     const size_t hA = (size_t)HALF * g.lda * 2, hB = (size_t)HALF * g.ldb * 2;
;     const size_t tA = 2 * hA, tB = 2 * hB, pnA = (size_t)g.a_pn_off * 2;
;     const unsigned ldsw = (unsigned)wid * 1024u;
;     const int aoff = lds_byte(wr * 64 + fr, fq * 8), boff = lds_byte(wc * 32 + fr, fq * 8);
;     ...
;         PG8_STAGE(PG8_SB(1, 0), cB + kstep, voffB); PG8_STAGE(PG8_SA(1, 0), cA + kstep, voffA); PG8_STAGE(PG8_SB(1, 1), cB + hB + kstep, voffB);
;         PG8_WAIT_V(6); PG8_BAR;
.LBB0_858:
	s_add_u32 s6, s4, 0xd800000
	s_addc_u32 s7, s5, 0
	s_lshl_b32 s4, s8, 5
	s_mov_b64 s[8:9], 0x80
	s_and_b32 s18, s4, 0x60
	s_add_i32 m0, s41, 0x18000
	v_lshl_add_u64 v[8:9], v[8:9], 0, s[8:9]
	s_lshl_b32 s17, s16, 13
	s_lshl_b32 s19, s18, 7
	s_waitcnt vmcnt(2)
	s_barrier
	global_load_lds_dwordx4 v[8:9], off
	v_lshl_add_u64 v[6:7], v[6:7], 0, s[8:9]
	s_add_i32 m0, s41, 0x1a000
	s_add_i32 s60, s41, 0x8000
	s_add_i32 s61, s41, 0xa000
	global_load_lds_dwordx4 v[6:7], off
	v_lshl_add_u64 v[2:3], v[2:3], 0, s[8:9]
	s_mov_b32 m0, s60
	s_add_u32 s4, s44, 0x40080
	global_load_lds_dwordx4 v[2:3], off
	v_lshl_add_u64 v[2:3], v[4:5], 0, s[8:9]
	s_mov_b32 m0, s61
	s_addc_u32 s5, s45, 0
	global_load_lds_dwordx4 v[2:3], off
	s_add_i32 m0, s41, 0x1c000
	v_lshl_add_u64 v[2:3], s[4:5], 0, v[134:135]
	global_load_lds_dwordx4 v[2:3], off
	v_lshl_add_u64 v[2:3], s[4:5], 0, v[130:131]
	s_add_i32 m0, s41, 0x1e000
	s_cmpk_lt_u32 s15, 0x100
	global_load_lds_dwordx4 v[2:3], off
	v_lshrrev_b32_e32 v3, 1, v11
	v_and_b32_e32 v3, 24, v3
	v_and_b32_e32 v2, 15, v11
	v_lshlrev_b32_e32 v4, 1, v3
	v_lshl_or_b32 v1, s16, 6, v2
	v_lshl_or_b32 v2, v2, 6, v4
	v_lshlrev_b32_e32 v4, 2, v11
	v_and_b32_e32 v4, 32, v4
	v_bitop3_b32 v5, v2, s17, v4 bitop3:0xde
	v_bitop3_b32 v154, v2, s19, v4 bitop3:0xde
	v_lshlrev_b32_e32 v2, 14, v15
	v_and_b32_e32 v2, 0xffff8000, v2
	v_or_b32_e32 v155, s18, v3
	v_lshl_add_u32 v2, v14, 11, v2
	v_and_b32_e32 v3, 1, v15
	v_lshl_or_b32 v2, v3, 6, v2
	v_lshl_add_u32 v138, v16, 1, v2
	v_lshlrev_b32_e32 v2, 14, v10
	v_and_b32_e32 v2, 0xffff8000, v2
	s_waitcnt vmcnt(6)
	v_lshl_add_u32 v2, v12, 11, v2
	v_and_b32_e32 v3, 1, v10
	s_sext_i32_i8 s66, s14
	s_cselect_b64 s[14:15], -1, 0
	v_lshl_or_b32 v2, v3, 6, v2
	s_add_i32 s64, 0, 0x10000
	s_add_i32 s65, 0, 0x14000
	s_mov_b32 s62, 0
	s_waitcnt lgkmcnt(0)
	s_ashr_i32 s63, s50, 31
	v_mov_b32_e32 v139, v135
	v_lshl_add_u32 v140, v13, 1, v2
	v_mov_b32_e32 v141, v135
	v_mov_b64_e32 v[142:143], 0x200
	v_mov_b64_e32 v[144:145], 0x1ff
	v_add_u32_e32 v156, s64, v154
	v_add_u32_e32 v157, s65, v154
	v_add_u32_e32 v158, 0, v5
	s_mov_b64 s[16:17], 0x1000
	s_barrier
	v_readfirstlane_b32 s101, v0
	s_nop 3
	s_lshr_b32 s101, s101, 8
	s_branch .LBB0_861

; #define PG8_STAGE(bufoff, gbase, voff) do { _Pragma("unroll") for (int _i = 0; _i < 2; ++_i) \
;         __builtin_amdgcn_global_load_lds((const unsigned*)((const char*)(gbase) + (voff)[_i]), (PG8_LAS unsigned*)(lds + (bufoff) + ldsw + _i * 8192), 16, 0, 0); } while (0)
; #define PG8_LDA(dst, b, h) do { _Pragma("unroll") for (int m = 0; m < 4; ++m) _Pragma("unroll") for (int k = 0; k < 2; ++k) dst[m][k] = *(const PG8_LAS bf16x8*)(lds + PG8_SA(b, h) + aoff + m * 2048 + k * 1024); } while (0)
; #define PG8_LDB(dst, b, h) do { _Pragma("unroll") for (int n = 0; n < 2; ++n) _Pragma("unroll") for (int k = 0; k < 2; ++k) dst[n][k] = *(const PG8_LAS bf16x8*)(lds + PG8_SB(b, h) + boff + n * 2048 + k * 1024); } while (0)
; #define PG8_WAIT_V(n) asm volatile("s_waitcnt vmcnt(" #n ")" ::: "memory")
; #define PG8_WAIT_L(n) asm volatile("s_waitcnt lgkmcnt(" #n ")" ::: "memory")
; template <class Epi, class Sched, bool ALIGN_EPI = false, bool SP2 = false>
; __device__ __forceinline__ void gemm_phase(PG8_LAS unsigned char* lds, const Gemm g, const Sched& S, const Epi& E) {
;     ...
;     for (;;) {
;         const bool has_next = S.next(ui + 1, nxt);
;         const char* nA = has_next ? (const char*)g.A + (size_t)nxt.pm * tA + (size_t)nxt.pn * pnA : cA; const char* nB = has_next ? (const char*)g.Bt + (size_t)nxt.pn * tB : cB;
; #pragma nounroll
;         for (int t = 0; t < nt; t += 2) {
;             const bool last = (t == nt - 2);
;             const char* a1 = cA + (size_t)(t + 1) * kstep;
;             const char* a2 = last ? nA : cA + (size_t)(t + 2) * kstep; const char* b2 = last ? nB : cB + (size_t)(t + 2) * kstep;
;             const char* a3 = a2 + kstep; const char* b3 = b2 + kstep;
;             if (last && has_next) S.a_ready(nxt);
;             if constexpr (SP2) {
;             PG8_LDB(B0, 0, 0); PG8_LDB(B1, 0, 1); PG8_SCHED; PG8_LDA(At, 0, 0); PG8_STAGE(PG8_SA(1, 1), a1 + hA, voffA);
;             PG8_WAIT_V(8); PG8_WAIT_L(0); PG8_BAR; PG8_MMA(0, 0, At, B0); PG8_MMA(0, 1, At, B1); PG8_BAR; PG8_SCHED;
;     ...
; #pragma unroll
;         for (int a = 0; a < 2; ++a)
; #pragma unroll
;             for (int b = 0; b < 2; ++b)
; #pragma unroll
;                 for (int m = 0; m < 4; ++m)
; #pragma unroll
;                     for (int n = 0; n < 2; ++n) acc[a][b][m][n] = (f32x4){0.f, 0.f, 0.f, 0.f};
;         cur = nxt; cA = nA; cB = nB; ++ui;
.LBB0_867:
	s_ashr_i32 s23, s22, 31
	s_lshl_b64 s[24:25], s[22:23], 19
	s_add_u32 s24, s33, s24
	s_addc_u32 s25, s48, s25
	s_and_b64 s[38:39], s[4:5], exec
	s_cselect_b32 s23, s25, s43
	s_cselect_b32 s67, s24, s42
	s_ashr_i32 s21, s20, 31
	s_lshl_b64 s[38:39], s[20:21], 19
	s_add_u32 s38, s49, s38
	s_addc_u32 s39, s51, s39
	s_and_b64 s[46:47], s[4:5], exec
	s_cselect_b32 s21, s39, s45
	s_cselect_b32 s69, s38, s44
	s_add_u32 s42, s42, 0x40080
	s_addc_u32 s43, s43, 0
	s_add_u32 s70, s44, 0x100
	v_mov_b32_e32 v2, 0
	s_addc_u32 s71, s45, 0
	s_mov_b32 s72, -2
	v_mov_b32_e32 v3, v2
	v_mov_b64_e32 v[4:5], 0
	v_mov_b64_e32 v[6:7], 0
	v_mov_b64_e32 v[8:9], 0
	v_mov_b64_e32 v[10:11], 0
	v_mov_b64_e32 v[12:13], 0
	v_mov_b64_e32 v[14:15], 0
	v_mov_b64_e32 v[16:17], 0
	v_mov_b64_e32 v[18:19], 0
	v_mov_b64_e32 v[20:21], 0
	v_mov_b64_e32 v[22:23], 0
	v_mov_b64_e32 v[24:25], 0
	v_mov_b64_e32 v[26:27], 0
	v_mov_b64_e32 v[28:29], 0
	v_mov_b64_e32 v[30:31], 0
	v_mov_b64_e32 v[32:33], 0
	v_mov_b64_e32 v[34:35], 0
	v_mov_b64_e32 v[36:37], 0
	v_mov_b64_e32 v[38:39], 0
	v_mov_b64_e32 v[40:41], 0
	v_mov_b64_e32 v[42:43], 0
	v_mov_b64_e32 v[44:45], 0
	v_mov_b64_e32 v[46:47], 0
	v_mov_b64_e32 v[48:49], 0
	v_mov_b64_e32 v[50:51], 0
	v_mov_b64_e32 v[52:53], 0
	v_mov_b64_e32 v[54:55], 0
	v_mov_b64_e32 v[56:57], 0
	v_mov_b64_e32 v[58:59], 0
	v_mov_b64_e32 v[60:61], 0
	v_mov_b64_e32 v[62:63], 0
	v_mov_b64_e32 v[64:65], 0
	v_mov_b64_e32 v[66:67], 0
	v_mov_b64_e32 v[68:69], 0
	v_mov_b64_e32 v[70:71], 0
	v_mov_b64_e32 v[72:73], 0
	v_mov_b64_e32 v[74:75], 0
	v_mov_b64_e32 v[76:77], 0
	v_mov_b64_e32 v[78:79], 0
	v_mov_b64_e32 v[80:81], 0
	v_mov_b64_e32 v[82:83], 0
	v_mov_b64_e32 v[84:85], 0
	v_mov_b64_e32 v[86:87], 0
	v_mov_b64_e32 v[88:89], 0
	v_mov_b64_e32 v[90:91], 0
	v_mov_b64_e32 v[92:93], 0
	v_mov_b64_e32 v[94:95], 0
	v_mov_b64_e32 v[96:97], 0
	v_mov_b64_e32 v[98:99], 0
	v_mov_b64_e32 v[100:101], 0
	v_mov_b64_e32 v[102:103], 0
	v_mov_b64_e32 v[104:105], 0
	v_mov_b64_e32 v[106:107], 0
	v_mov_b64_e32 v[108:109], 0
	v_mov_b64_e32 v[110:111], 0
	v_mov_b64_e32 v[112:113], 0
	v_mov_b64_e32 v[114:115], 0
	v_mov_b64_e32 v[116:117], 0
	v_mov_b64_e32 v[118:119], 0
	v_mov_b64_e32 v[120:121], 0
	v_mov_b64_e32 v[122:123], 0
	v_mov_b64_e32 v[124:125], 0
	v_mov_b64_e32 v[126:127], 0
	v_mov_b64_e32 v[128:129], 0
	s_add_u32 s80, s42, 0xfffc0000
	s_addc_u32 s81, s43, -1
	s_cmp_eq_u32 s101, 0
	s_cbranch_scc0 .Lkt_1
.LBB0_868:
	ds_read_b128 v[146:149], v156
	ds_read_b128 v[150:153], v156 offset:1024
	ds_read_b128 v[160:163], v156 offset:2048
	ds_read_b128 v[164:167], v156 offset:3072
	ds_read_b128 v[168:171], v157
	ds_read_b128 v[172:175], v157 offset:1024
	ds_read_b128 v[176:179], v157 offset:2048
	ds_read_b128 v[180:183], v157 offset:3072
	s_add_u32 s18, s42, 0xfffc0080
	s_addc_u32 s19, s43, -1
	s_cmp_eq_u32 s72, 12
	s_cselect_b32 s47, s23, s19
	s_cselect_b32 s46, s67, s18
	s_cselect_b32 s45, s21, s71
	s_cselect_b32 s44, s69, s70
	s_add_i32 m0, s41, 0xc000
	ds_read_b128 v[184:187], v158
	ds_read_b128 v[188:191], v158 offset:1024
	ds_read_b128 v[192:195], v158 offset:2048
	ds_read_b128 v[196:199], v158 offset:3072
	ds_read_b128 v[200:203], v158 offset:4096
	ds_read_b128 v[204:207], v158 offset:5120
	ds_read_b128 v[208:211], v158 offset:6144
	ds_read_b128 v[212:215], v158 offset:7168
	global_load_lds_dwordx4 v138, s[42:43]
	s_add_i32 m0, s41, 0xe000
	s_nop 0
	global_load_lds_dwordx4 v140, s[42:43]
	s_mov_b32 m0, s60
	s_nop 0
	global_load_lds_dwordx4 v136, s[80:81]
	s_mov_b32 m0, s61
	s_nop 0
	global_load_lds_dwordx4 v132, s[80:81]
	s_waitcnt lgkmcnt(0)
	s_barrier
	s_waitcnt lgkmcnt(0)
	v_mfma_f32_16x16x32_bf16 v[126:129], v[146:149], v[184:187], v[126:129]
	v_mfma_f32_16x16x32_bf16 v[122:125], v[160:163], v[184:187], v[122:125]
	v_mfma_f32_16x16x32_bf16 v[114:117], v[146:149], v[192:195], v[114:117]
	v_mfma_f32_16x16x32_bf16 v[106:109], v[160:163], v[192:195], v[106:109]
	v_mfma_f32_16x16x32_bf16 v[98:101], v[146:149], v[200:203], v[98:101]
	v_mfma_f32_16x16x32_bf16 v[90:93], v[160:163], v[200:203], v[90:93]
	v_mfma_f32_16x16x32_bf16 v[82:85], v[146:149], v[208:211], v[82:85]
	v_mfma_f32_16x16x32_bf16 v[74:77], v[160:163], v[208:211], v[74:77]
	v_mfma_f32_16x16x32_bf16 v[126:129], v[150:153], v[188:191], v[126:129]
	v_mfma_f32_16x16x32_bf16 v[122:125], v[164:167], v[188:191], v[122:125]
	v_mfma_f32_16x16x32_bf16 v[114:117], v[150:153], v[196:199], v[114:117]
	v_mfma_f32_16x16x32_bf16 v[106:109], v[164:167], v[196:199], v[106:109]
	v_mfma_f32_16x16x32_bf16 v[98:101], v[150:153], v[204:207], v[98:101]
	v_mfma_f32_16x16x32_bf16 v[90:93], v[164:167], v[204:207], v[90:93]
	v_mfma_f32_16x16x32_bf16 v[82:85], v[150:153], v[212:215], v[82:85]
	v_mfma_f32_16x16x32_bf16 v[74:77], v[164:167], v[212:215], v[74:77]
	v_mfma_f32_16x16x32_bf16 v[118:121], v[168:171], v[184:187], v[118:121]
	v_mfma_f32_16x16x32_bf16 v[110:113], v[176:179], v[184:187], v[110:113]
	v_mfma_f32_16x16x32_bf16 v[102:105], v[168:171], v[192:195], v[102:105]
	v_mfma_f32_16x16x32_bf16 v[94:97], v[176:179], v[192:195], v[94:97]
	v_mfma_f32_16x16x32_bf16 v[86:89], v[168:171], v[200:203], v[86:89]
	v_mfma_f32_16x16x32_bf16 v[78:81], v[176:179], v[200:203], v[78:81]
	v_mfma_f32_16x16x32_bf16 v[70:73], v[168:171], v[208:211], v[70:73]
	v_mfma_f32_16x16x32_bf16 v[66:69], v[176:179], v[208:211], v[66:69]
	v_mfma_f32_16x16x32_bf16 v[118:121], v[172:175], v[188:191], v[118:121]
	v_mfma_f32_16x16x32_bf16 v[110:113], v[180:183], v[188:191], v[110:113]
	v_mfma_f32_16x16x32_bf16 v[102:105], v[172:175], v[196:199], v[102:105]
	v_mfma_f32_16x16x32_bf16 v[94:97], v[180:183], v[196:199], v[94:97]
	v_mfma_f32_16x16x32_bf16 v[86:89], v[172:175], v[204:207], v[86:89]
	v_mfma_f32_16x16x32_bf16 v[78:81], v[180:183], v[204:207], v[78:81]
	v_mfma_f32_16x16x32_bf16 v[70:73], v[172:175], v[212:215], v[70:73]
	v_mfma_f32_16x16x32_bf16 v[66:69], v[180:183], v[212:215], v[66:69]
	s_waitcnt vmcnt(8)
	s_barrier
; #define PG8_STAGE(bufoff, gbase, voff) do { _Pragma("unroll") for (int _i = 0; _i < 2; ++_i) \
;         __builtin_amdgcn_global_load_lds((const unsigned*)((const char*)(gbase) + (voff)[_i]), (PG8_LAS unsigned*)(lds + (bufoff) + ldsw + _i * 8192), 16, 0, 0); } while (0)
; #define PG8_LDA(dst, b, h) do { _Pragma("unroll") for (int m = 0; m < 4; ++m) _Pragma("unroll") for (int k = 0; k < 2; ++k) dst[m][k] = *(const PG8_LAS bf16x8*)(lds + PG8_SA(b, h) + aoff + m * 2048 + k * 1024); } while (0)
; #define PG8_LDB(dst, b, h) do { _Pragma("unroll") for (int n = 0; n < 2; ++n) _Pragma("unroll") for (int k = 0; k < 2; ++k) dst[n][k] = *(const PG8_LAS bf16x8*)(lds + PG8_SB(b, h) + boff + n * 2048 + k * 1024); } while (0)
; #define PG8_MMA(ai, bj, At, Bt) do { __builtin_amdgcn_s_setprio(1); _Pragma("unroll") for (int m = 0; m < 4; ++m) _Pragma("unroll") for (int n = 0; n < 2; ++n) _Pragma("unroll") for (int k = 0; k < 2; ++k) \
;         acc[ai][bj][m][n] = __builtin_amdgcn_mfma_f32_16x16x32_bf16(Bt[n][k], At[m][k], acc[ai][bj][m][n], 0, 0, 0); __builtin_amdgcn_s_setprio(0); } while (0)
; #define PG8_WAIT_V(n) asm volatile("s_waitcnt vmcnt(" #n ")" ::: "memory")
; #define PG8_WAIT_L(n) asm volatile("s_waitcnt lgkmcnt(" #n ")" ::: "memory")
; #define PG8_BAR __builtin_amdgcn_s_barrier()
; #define PG8_SCHED __builtin_amdgcn_sched_barrier(0)
; template <class Epi, class Sched, bool ALIGN_EPI = false, bool SP2 = false>
; __device__ __forceinline__ void gemm_phase(PG8_LAS unsigned char* lds, const Gemm g, const Sched& S, const Epi& E) {
;     ...
;             PG8_LDA(At, 0, 1); PG8_STAGE(PG8_SB(0, 0), b2, voffB); PG8_STAGE(PG8_SB(0, 1), b2 + hB, voffB); PG8_STAGE(PG8_SA(0, 0), a2, voffA);
;             PG8_WAIT_V(8); PG8_WAIT_L(0); PG8_BAR; PG8_MMA(1, 0, At, B0); PG8_MMA(1, 1, At, B1); PG8_BAR; PG8_SCHED;
;             PG8_LDB(B0, 1, 0); PG8_LDB(B1, 1, 1); PG8_SCHED; PG8_LDA(At, 1, 0); PG8_STAGE(PG8_SA(0, 1), a2 + hA, voffA);
;             PG8_WAIT_V(8); PG8_WAIT_L(0); PG8_BAR; PG8_MMA(0, 0, At, B0); PG8_MMA(0, 1, At, B1); PG8_BAR; PG8_SCHED;
	s_add_i32 s18, s64, s52
	s_add_u32 s78, s44, s8
	s_addc_u32 s79, s45, s9
	s_mov_b32 m0, s18
	ds_read_b128 v[184:187], v158 offset:16384
	ds_read_b128 v[188:191], v158 offset:17408
	ds_read_b128 v[192:195], v158 offset:18432
	ds_read_b128 v[196:199], v158 offset:19456
	ds_read_b128 v[200:203], v158 offset:20480
	ds_read_b128 v[204:207], v158 offset:21504
	ds_read_b128 v[208:211], v158 offset:22528
	ds_read_b128 v[212:215], v158 offset:23552
	global_load_lds_dwordx4 v134, s[44:45]
	s_add_i32 m0, s18, 0x2000
	s_add_u32 s74, s44, 0x40000
	s_addc_u32 s75, s45, 0
	s_add_i32 s18, s65, s52
	global_load_lds_dwordx4 v130, s[44:45]
	s_mov_b32 m0, s18
	s_nop 0
	global_load_lds_dwordx4 v134, s[74:75]
	s_add_i32 m0, s18, 0x2000
	s_nop 0
	global_load_lds_dwordx4 v130, s[74:75]
	s_add_u32 s80, s46, s8
	s_addc_u32 s81, s47, s9
	s_waitcnt lgkmcnt(0)
	s_barrier
	s_waitcnt lgkmcnt(0)
	v_mfma_f32_16x16x32_bf16 v[62:65], v[146:149], v[184:187], v[62:65]
	v_mfma_f32_16x16x32_bf16 v[58:61], v[160:163], v[184:187], v[58:61]
	v_mfma_f32_16x16x32_bf16 v[50:53], v[146:149], v[192:195], v[50:53]
	v_mfma_f32_16x16x32_bf16 v[42:45], v[160:163], v[192:195], v[42:45]
	v_mfma_f32_16x16x32_bf16 v[34:37], v[146:149], v[200:203], v[34:37]
	v_mfma_f32_16x16x32_bf16 v[26:29], v[160:163], v[200:203], v[26:29]
	v_mfma_f32_16x16x32_bf16 v[18:21], v[146:149], v[208:211], v[18:21]
	v_mfma_f32_16x16x32_bf16 v[10:13], v[160:163], v[208:211], v[10:13]
	v_mfma_f32_16x16x32_bf16 v[62:65], v[150:153], v[188:191], v[62:65]
	v_mfma_f32_16x16x32_bf16 v[58:61], v[164:167], v[188:191], v[58:61]
	v_mfma_f32_16x16x32_bf16 v[50:53], v[150:153], v[196:199], v[50:53]
	v_mfma_f32_16x16x32_bf16 v[42:45], v[164:167], v[196:199], v[42:45]
	v_mfma_f32_16x16x32_bf16 v[34:37], v[150:153], v[204:207], v[34:37]
	v_mfma_f32_16x16x32_bf16 v[26:29], v[164:167], v[204:207], v[26:29]
	v_mfma_f32_16x16x32_bf16 v[18:21], v[150:153], v[212:215], v[18:21]
	v_mfma_f32_16x16x32_bf16 v[10:13], v[164:167], v[212:215], v[10:13]
	v_mfma_f32_16x16x32_bf16 v[54:57], v[168:171], v[184:187], v[54:57]
	v_mfma_f32_16x16x32_bf16 v[46:49], v[176:179], v[184:187], v[46:49]
	v_mfma_f32_16x16x32_bf16 v[38:41], v[168:171], v[192:195], v[38:41]
	v_mfma_f32_16x16x32_bf16 v[30:33], v[176:179], v[192:195], v[30:33]
	v_mfma_f32_16x16x32_bf16 v[22:25], v[168:171], v[200:203], v[22:25]
	v_mfma_f32_16x16x32_bf16 v[14:17], v[176:179], v[200:203], v[14:17]
	v_mfma_f32_16x16x32_bf16 v[6:9], v[168:171], v[208:211], v[6:9]
	v_mfma_f32_16x16x32_bf16 v[2:5], v[176:179], v[208:211], v[2:5]
	v_mfma_f32_16x16x32_bf16 v[54:57], v[172:175], v[188:191], v[54:57]
	v_mfma_f32_16x16x32_bf16 v[46:49], v[180:183], v[188:191], v[46:49]
	v_mfma_f32_16x16x32_bf16 v[38:41], v[172:175], v[196:199], v[38:41]
	v_mfma_f32_16x16x32_bf16 v[30:33], v[180:183], v[196:199], v[30:33]
	v_mfma_f32_16x16x32_bf16 v[22:25], v[172:175], v[204:207], v[22:25]
	v_mfma_f32_16x16x32_bf16 v[14:17], v[180:183], v[204:207], v[14:17]
	v_mfma_f32_16x16x32_bf16 v[6:9], v[172:175], v[212:215], v[6:9]
	v_mfma_f32_16x16x32_bf16 v[2:5], v[180:183], v[212:215], v[2:5]
	s_waitcnt vmcnt(4)
	s_barrier
	s_add_i32 s18, 0, 0x18000
	v_add_u32_e32 v159, s18, v154
	s_add_i32 s19, 0, 0x1c000
	ds_read_b128 v[146:149], v159
	ds_read_b128 v[150:153], v159 offset:1024
	ds_read_b128 v[160:163], v159 offset:2048
	ds_read_b128 v[164:167], v159 offset:3072
	v_add_u32_e32 v159, s19, v154
	ds_read_b128 v[168:171], v159
	ds_read_b128 v[172:175], v159 offset:1024
	ds_read_b128 v[176:179], v159 offset:2048
	ds_read_b128 v[180:183], v159 offset:3072
	ds_read_b128 v[184:187], v158 offset:32768
	ds_read_b128 v[188:191], v158 offset:33792
	ds_read_b128 v[192:195], v158 offset:34816
	ds_read_b128 v[196:199], v158 offset:35840
	ds_read_b128 v[200:203], v158 offset:36864
	ds_read_b128 v[204:207], v158 offset:37888
	ds_read_b128 v[208:211], v158 offset:38912
	ds_read_b128 v[212:215], v158 offset:39936
	s_mov_b32 m0, s41
	s_nop 0
	global_load_lds_dwordx4 v136, s[46:47]
	s_mov_b32 m0, s53
	s_nop 0
	global_load_lds_dwordx4 v132, s[46:47]
	s_add_u32 s46, s46, 0x40000
	s_addc_u32 s47, s47, 0
	s_mov_b32 m0, s58
	s_nop 0
	global_load_lds_dwordx4 v136, s[46:47]
	s_mov_b32 m0, s59
	s_nop 0
	global_load_lds_dwordx4 v132, s[46:47]
	s_waitcnt lgkmcnt(0)
	s_barrier
; #define PG8_STAGE(bufoff, gbase, voff) do { _Pragma("unroll") for (int _i = 0; _i < 2; ++_i) \
;         __builtin_amdgcn_global_load_lds((const unsigned*)((const char*)(gbase) + (voff)[_i]), (PG8_LAS unsigned*)(lds + (bufoff) + ldsw + _i * 8192), 16, 0, 0); } while (0)
; #define PG8_LDA(dst, b, h) do { _Pragma("unroll") for (int m = 0; m < 4; ++m) _Pragma("unroll") for (int k = 0; k < 2; ++k) dst[m][k] = *(const PG8_LAS bf16x8*)(lds + PG8_SA(b, h) + aoff + m * 2048 + k * 1024); } while (0)
; #define PG8_MMA(ai, bj, At, Bt) do { __builtin_amdgcn_s_setprio(1); _Pragma("unroll") for (int m = 0; m < 4; ++m) _Pragma("unroll") for (int n = 0; n < 2; ++n) _Pragma("unroll") for (int k = 0; k < 2; ++k) \
;         acc[ai][bj][m][n] = __builtin_amdgcn_mfma_f32_16x16x32_bf16(Bt[n][k], At[m][k], acc[ai][bj][m][n], 0, 0, 0); __builtin_amdgcn_s_setprio(0); } while (0)
; #define PG8_WAIT_V(n) asm volatile("s_waitcnt vmcnt(" #n ")" ::: "memory")
; #define PG8_WAIT_L(n) asm volatile("s_waitcnt lgkmcnt(" #n ")" ::: "memory")
; #define PG8_BAR __builtin_amdgcn_s_barrier()
; #define PG8_SCHED __builtin_amdgcn_sched_barrier(0)
; template <class Epi, class Sched, bool ALIGN_EPI = false, bool SP2 = false>
; __device__ __forceinline__ void gemm_phase(PG8_LAS unsigned char* lds, const Gemm g, const Sched& S, const Epi& E) {
;     ...
;             PG8_WAIT_V(8); PG8_WAIT_L(0); PG8_BAR; PG8_MMA(0, 0, At, B0); PG8_MMA(0, 1, At, B1); PG8_BAR; PG8_SCHED;
;             PG8_LDA(At, 1, 1); PG8_STAGE(PG8_SB(1, 0), b3, voffB); PG8_STAGE(PG8_SB(1, 1), b3 + hB, voffB); PG8_STAGE(PG8_SA(1, 0), a3, voffA);
;             PG8_WAIT_V(8); PG8_WAIT_L(0); PG8_BAR; PG8_MMA(1, 0, At, B0); PG8_MMA(1, 1, At, B1); PG8_BAR; PG8_SCHED;
	s_waitcnt lgkmcnt(0)
	v_mfma_f32_16x16x32_bf16 v[126:129], v[146:149], v[184:187], v[126:129]
	v_mfma_f32_16x16x32_bf16 v[122:125], v[160:163], v[184:187], v[122:125]
	v_mfma_f32_16x16x32_bf16 v[114:117], v[146:149], v[192:195], v[114:117]
	v_mfma_f32_16x16x32_bf16 v[106:109], v[160:163], v[192:195], v[106:109]
	v_mfma_f32_16x16x32_bf16 v[98:101], v[146:149], v[200:203], v[98:101]
	v_mfma_f32_16x16x32_bf16 v[90:93], v[160:163], v[200:203], v[90:93]
	v_mfma_f32_16x16x32_bf16 v[82:85], v[146:149], v[208:211], v[82:85]
	v_mfma_f32_16x16x32_bf16 v[74:77], v[160:163], v[208:211], v[74:77]
	v_mfma_f32_16x16x32_bf16 v[126:129], v[150:153], v[188:191], v[126:129]
	v_mfma_f32_16x16x32_bf16 v[122:125], v[164:167], v[188:191], v[122:125]
	v_mfma_f32_16x16x32_bf16 v[114:117], v[150:153], v[196:199], v[114:117]
	v_mfma_f32_16x16x32_bf16 v[106:109], v[164:167], v[196:199], v[106:109]
	v_mfma_f32_16x16x32_bf16 v[98:101], v[150:153], v[204:207], v[98:101]
	v_mfma_f32_16x16x32_bf16 v[90:93], v[164:167], v[204:207], v[90:93]
	v_mfma_f32_16x16x32_bf16 v[82:85], v[150:153], v[212:215], v[82:85]
	v_mfma_f32_16x16x32_bf16 v[74:77], v[164:167], v[212:215], v[74:77]
	v_mfma_f32_16x16x32_bf16 v[118:121], v[168:171], v[184:187], v[118:121]
	v_mfma_f32_16x16x32_bf16 v[110:113], v[176:179], v[184:187], v[110:113]
	v_mfma_f32_16x16x32_bf16 v[102:105], v[168:171], v[192:195], v[102:105]
	v_mfma_f32_16x16x32_bf16 v[94:97], v[176:179], v[192:195], v[94:97]
	v_mfma_f32_16x16x32_bf16 v[86:89], v[168:171], v[200:203], v[86:89]
	v_mfma_f32_16x16x32_bf16 v[78:81], v[176:179], v[200:203], v[78:81]
	v_mfma_f32_16x16x32_bf16 v[70:73], v[168:171], v[208:211], v[70:73]
	v_mfma_f32_16x16x32_bf16 v[66:69], v[176:179], v[208:211], v[66:69]
	v_mfma_f32_16x16x32_bf16 v[118:121], v[172:175], v[188:191], v[118:121]
	v_mfma_f32_16x16x32_bf16 v[110:113], v[180:183], v[188:191], v[110:113]
	v_mfma_f32_16x16x32_bf16 v[102:105], v[172:175], v[196:199], v[102:105]
	v_mfma_f32_16x16x32_bf16 v[94:97], v[180:183], v[196:199], v[94:97]
	v_mfma_f32_16x16x32_bf16 v[86:89], v[172:175], v[204:207], v[86:89]
	v_mfma_f32_16x16x32_bf16 v[78:81], v[180:183], v[204:207], v[78:81]
	v_mfma_f32_16x16x32_bf16 v[70:73], v[172:175], v[212:215], v[70:73]
	v_mfma_f32_16x16x32_bf16 v[66:69], v[180:183], v[212:215], v[66:69]
	s_barrier
	s_add_i32 s18, s18, s52
	s_mov_b32 m0, s18
	ds_read_b128 v[184:187], v158 offset:49152
	ds_read_b128 v[188:191], v158 offset:50176
	ds_read_b128 v[192:195], v158 offset:51200
	ds_read_b128 v[196:199], v158 offset:52224
	ds_read_b128 v[200:203], v158 offset:53248
	ds_read_b128 v[204:207], v158 offset:54272
	ds_read_b128 v[208:211], v158 offset:55296
	ds_read_b128 v[212:215], v158 offset:56320
	global_load_lds_dwordx4 v134, s[78:79]
	s_add_i32 m0, s18, 0x2000
	s_add_u32 s44, s44, 0x40080
	s_addc_u32 s45, s45, 0
	s_add_i32 s18, s19, s52
	global_load_lds_dwordx4 v130, s[78:79]
	s_mov_b32 m0, s18
	s_nop 0
	global_load_lds_dwordx4 v134, s[44:45]
	s_add_i32 m0, s18, 0x2000
	s_nop 0
	global_load_lds_dwordx4 v130, s[44:45]
	s_waitcnt lgkmcnt(0)
	s_barrier
	s_waitcnt lgkmcnt(0)
	v_mfma_f32_16x16x32_bf16 v[62:65], v[146:149], v[184:187], v[62:65]
	v_mfma_f32_16x16x32_bf16 v[58:61], v[160:163], v[184:187], v[58:61]
	v_mfma_f32_16x16x32_bf16 v[50:53], v[146:149], v[192:195], v[50:53]
	v_mfma_f32_16x16x32_bf16 v[42:45], v[160:163], v[192:195], v[42:45]
	v_mfma_f32_16x16x32_bf16 v[34:37], v[146:149], v[200:203], v[34:37]
	v_mfma_f32_16x16x32_bf16 v[26:29], v[160:163], v[200:203], v[26:29]
	v_mfma_f32_16x16x32_bf16 v[18:21], v[146:149], v[208:211], v[18:21]
	v_mfma_f32_16x16x32_bf16 v[10:13], v[160:163], v[208:211], v[10:13]
	v_mfma_f32_16x16x32_bf16 v[62:65], v[150:153], v[188:191], v[62:65]
	v_mfma_f32_16x16x32_bf16 v[58:61], v[164:167], v[188:191], v[58:61]
	v_mfma_f32_16x16x32_bf16 v[50:53], v[150:153], v[196:199], v[50:53]
	v_mfma_f32_16x16x32_bf16 v[42:45], v[164:167], v[196:199], v[42:45]
	v_mfma_f32_16x16x32_bf16 v[34:37], v[150:153], v[204:207], v[34:37]
	v_mfma_f32_16x16x32_bf16 v[26:29], v[164:167], v[204:207], v[26:29]
	v_mfma_f32_16x16x32_bf16 v[18:21], v[150:153], v[212:215], v[18:21]
	v_mfma_f32_16x16x32_bf16 v[10:13], v[164:167], v[212:215], v[10:13]
	v_mfma_f32_16x16x32_bf16 v[54:57], v[168:171], v[184:187], v[54:57]
	v_mfma_f32_16x16x32_bf16 v[46:49], v[176:179], v[184:187], v[46:49]
	v_mfma_f32_16x16x32_bf16 v[38:41], v[168:171], v[192:195], v[38:41]
	v_mfma_f32_16x16x32_bf16 v[30:33], v[176:179], v[192:195], v[30:33]
	v_mfma_f32_16x16x32_bf16 v[22:25], v[168:171], v[200:203], v[22:25]
	v_mfma_f32_16x16x32_bf16 v[14:17], v[176:179], v[200:203], v[14:17]
	v_mfma_f32_16x16x32_bf16 v[6:9], v[168:171], v[208:211], v[6:9]
	v_mfma_f32_16x16x32_bf16 v[2:5], v[176:179], v[208:211], v[2:5]
	v_mfma_f32_16x16x32_bf16 v[54:57], v[172:175], v[188:191], v[54:57]
	v_mfma_f32_16x16x32_bf16 v[46:49], v[180:183], v[188:191], v[46:49]
	v_mfma_f32_16x16x32_bf16 v[38:41], v[172:175], v[196:199], v[38:41]
	v_mfma_f32_16x16x32_bf16 v[30:33], v[180:183], v[196:199], v[30:33]
	v_mfma_f32_16x16x32_bf16 v[22:25], v[172:175], v[204:207], v[22:25]
	v_mfma_f32_16x16x32_bf16 v[14:17], v[180:183], v[204:207], v[14:17]
	v_mfma_f32_16x16x32_bf16 v[6:9], v[172:175], v[212:215], v[6:9]
	v_mfma_f32_16x16x32_bf16 v[2:5], v[180:183], v[212:215], v[2:5]
	s_waitcnt vmcnt(6)
	s_barrier
	s_add_i32 s72, s72, 2
	s_add_u32 s42, s42, 0x100
	s_addc_u32 s43, s43, 0
	s_add_u32 s70, s70, 0x100
	s_addc_u32 s71, s71, 0
	s_cmp_gt_u32 s72, 13
	s_cbranch_scc0 .LBB0_868
	s_branch .Lkafter_1

; #define PG8_BAR __builtin_amdgcn_s_barrier()
; template <class Epi, class Sched, bool ALIGN_EPI = false, bool SP2 = false>
; __device__ __forceinline__ void gemm_phase(PG8_LAS unsigned char* lds, const Gemm g, const Sched& S, const Epi& E) {
;     ...
;         if constexpr (ALIGN_EPI) { if (wr == 0) PG8_BAR; }
.Lkafter_1:
	s_and_b64 vcc, exec, s[14:15]
	s_cbranch_vccz .LBB0_871
	s_barrier

; #define PG8_STAGE(bufoff, gbase, voff) do { _Pragma("unroll") for (int _i = 0; _i < 2; ++_i) \
;         __builtin_amdgcn_global_load_lds((const unsigned*)((const char*)(gbase) + (voff)[_i]), (PG8_LAS unsigned*)(lds + (bufoff) + ldsw + _i * 8192), 16, 0, 0); } while (0)
; #define PG8_WAIT_V(n) asm volatile("s_waitcnt vmcnt(" #n ")" ::: "memory")
; #define PG8_BAR __builtin_amdgcn_s_barrier()
; template <class Epi, class Sched, bool ALIGN_EPI = false, bool SP2 = false>
; __device__ __forceinline__ void gemm_phase(PG8_LAS unsigned char* lds, const Gemm g, const Sched& S, const Epi& E) {
;     ...
;     const int tid = tid_o, wid = __builtin_amdgcn_readfirstlane(tid >> 6), lane = tid & 63, wr = wid >> 2, wc = wid & 3, fr = lane & 15, fq = lane >> 4;
;     const int K = g.K, nt = K / BK;
;     unsigned voffA[2], voffB[2];
; #pragma unroll
;     for (int i = 0; i < 2; ++i) { int R, C; stage_rc(tid * 16 + i * 8192, R, C); const int Rb = Epi::PERM ? ((R & ~31) + perm32(R & 31)) : R;
;         voffA[i] = (unsigned)(R * g.lda + C) * 2u; voffB[i] = (unsigned)(Rb * g.ldb + C) * 2u; }
;     const size_t kstep = (size_t)(BK * 2);
;     const size_t hA = (size_t)HALF * g.lda * 2, hB = (size_t)HALF * g.ldb * 2;
;     const size_t tA = 2 * hA, tB = 2 * hB, pnA = (size_t)g.a_pn_off * 2;
;     const unsigned ldsw = (unsigned)wid * 1024u;
;     const int aoff = lds_byte(wr * 64 + fr, fq * 8), boff = lds_byte(wc * 32 + fr, fq * 8);
;     ...
;         PG8_STAGE(PG8_SB(1, 0), cB + kstep, voffB); PG8_STAGE(PG8_SA(1, 0), cA + kstep, voffA); PG8_STAGE(PG8_SB(1, 1), cB + hB + kstep, voffB);
;         PG8_WAIT_V(6); PG8_BAR;
.LBB0_878:
	s_add_u32 s8, s6, 0xd800000
	s_addc_u32 s9, s7, 0
	s_add_u32 s14, s6, 0x9800000
	s_addc_u32 s15, s7, 0
	s_lshl_b32 s6, s16, 5
	s_mov_b64 s[16:17], 0x80
	s_and_b32 s19, s6, 0x60
	s_add_i32 m0, s43, 0x18000
	v_lshl_add_u64 v[8:9], v[8:9], 0, s[16:17]
	s_lshl_b32 s18, s22, 13
	s_lshl_b32 s23, s19, 7
	s_waitcnt vmcnt(2)
	s_barrier
	global_load_lds_dwordx4 v[8:9], off
	v_lshl_add_u64 v[6:7], v[6:7], 0, s[16:17]
	s_add_i32 m0, s43, 0x1a000
	s_add_i32 s63, s43, 0x8000
	s_add_i32 s64, s43, 0xa000
	global_load_lds_dwordx4 v[6:7], off
	v_lshl_add_u64 v[2:3], v[2:3], 0, s[16:17]
	s_mov_b32 m0, s63
	s_add_u32 s6, s46, 0x80080
	global_load_lds_dwordx4 v[2:3], off
	v_lshl_add_u64 v[2:3], v[4:5], 0, s[16:17]
	s_mov_b32 m0, s64
	s_addc_u32 s7, s47, 0
	global_load_lds_dwordx4 v[2:3], off
	s_add_i32 m0, s43, 0x1c000
	v_lshl_add_u64 v[2:3], s[6:7], 0, v[150:151]
	global_load_lds_dwordx4 v[2:3], off
	v_lshl_add_u64 v[2:3], s[6:7], 0, v[146:147]
	s_add_i32 m0, s43, 0x1e000
	s_cmpk_lt_u32 s21, 0x100
	global_load_lds_dwordx4 v[2:3], off
	v_lshrrev_b32_e32 v3, 1, v11
	v_and_b32_e32 v3, 24, v3
	v_and_b32_e32 v2, 15, v11
	v_lshlrev_b32_e32 v4, 1, v3
	v_lshl_or_b32 v1, s22, 6, v2
	v_lshl_or_b32 v2, v2, 6, v4
	v_lshlrev_b32_e32 v4, 2, v11
	v_and_b32_e32 v4, 32, v4
	v_bitop3_b32 v5, v2, s18, v4 bitop3:0xde
	v_bitop3_b32 v170, v2, s23, v4 bitop3:0xde
	v_lshlrev_b32_e32 v2, 15, v15
	v_and_b32_e32 v2, 0xffff0000, v2
	v_or_b32_e32 v171, s19, v3
	v_lshl_add_u32 v2, v14, 12, v2
	v_and_b32_e32 v3, 1, v15
	v_lshl_or_b32 v2, v3, 6, v2
	v_lshl_add_u32 v154, v16, 1, v2
	v_lshlrev_b32_e32 v2, 15, v10
	v_and_b32_e32 v2, 0xffff0000, v2
	s_waitcnt vmcnt(6)
	v_lshl_add_u32 v2, v12, 12, v2
	v_and_b32_e32 v3, 1, v10
	s_sext_i32_i8 s69, s20
	s_cselect_b64 s[20:21], -1, 0
	v_lshl_or_b32 v2, v3, 6, v2
	s_add_i32 s66, 0, 0x10000
	s_add_i32 s67, 0, 0x14000
	s_waitcnt lgkmcnt(0)
	s_ashr_i32 s65, s50, 31
	v_mov_b32_e32 v155, v151
	v_lshl_add_u32 v156, v13, 1, v2
	v_mov_b32_e32 v157, v151
	v_mov_b64_e32 v[158:159], 0x200
	v_mov_b64_e32 v[160:161], 0x1ff
	v_add_u32_e32 v172, s66, v170
	v_add_u32_e32 v173, s67, v170
	v_add_u32_e32 v174, 0, v5
	s_barrier
	v_readfirstlane_b32 s101, v0
	s_nop 3
	s_lshr_b32 s101, s101, 8
	s_branch .LBB0_881

; #define PG8_STAGE(bufoff, gbase, voff) do { _Pragma("unroll") for (int _i = 0; _i < 2; ++_i) \
;         __builtin_amdgcn_global_load_lds((const unsigned*)((const char*)(gbase) + (voff)[_i]), (PG8_LAS unsigned*)(lds + (bufoff) + ldsw + _i * 8192), 16, 0, 0); } while (0)
; #define PG8_LDA(dst, b, h) do { _Pragma("unroll") for (int m = 0; m < 4; ++m) _Pragma("unroll") for (int k = 0; k < 2; ++k) dst[m][k] = *(const PG8_LAS bf16x8*)(lds + PG8_SA(b, h) + aoff + m * 2048 + k * 1024); } while (0)
; #define PG8_LDB(dst, b, h) do { _Pragma("unroll") for (int n = 0; n < 2; ++n) _Pragma("unroll") for (int k = 0; k < 2; ++k) dst[n][k] = *(const PG8_LAS bf16x8*)(lds + PG8_SB(b, h) + boff + n * 2048 + k * 1024); } while (0)
; #define PG8_WAIT_V(n) asm volatile("s_waitcnt vmcnt(" #n ")" ::: "memory")
; #define PG8_WAIT_L(n) asm volatile("s_waitcnt lgkmcnt(" #n ")" ::: "memory")
; template <class Epi, class Sched, bool ALIGN_EPI = false, bool SP2 = false>
; __device__ __forceinline__ void gemm_phase(PG8_LAS unsigned char* lds, const Gemm g, const Sched& S, const Epi& E) {
;     ...
;     for (;;) {
;         const bool has_next = S.next(ui + 1, nxt);
;         const char* nA = has_next ? (const char*)g.A + (size_t)nxt.pm * tA + (size_t)nxt.pn * pnA : cA; const char* nB = has_next ? (const char*)g.Bt + (size_t)nxt.pn * tB : cB;
; #pragma nounroll
;         for (int t = 0; t < nt; t += 2) {
;             const bool last = (t == nt - 2);
;             const char* a1 = cA + (size_t)(t + 1) * kstep;
;             const char* a2 = last ? nA : cA + (size_t)(t + 2) * kstep; const char* b2 = last ? nB : cB + (size_t)(t + 2) * kstep;
;             const char* a3 = a2 + kstep; const char* b3 = b2 + kstep;
;             if (last && has_next) S.a_ready(nxt);
;             if constexpr (SP2) {
;             PG8_LDB(B0, 0, 0); PG8_LDB(B1, 0, 1); PG8_SCHED; PG8_LDA(At, 0, 0); PG8_STAGE(PG8_SA(1, 1), a1 + hA, voffA);
;             PG8_WAIT_V(8); PG8_WAIT_L(0); PG8_BAR; PG8_MMA(0, 0, At, B0); PG8_MMA(0, 1, At, B1); PG8_BAR; PG8_SCHED;
;     ...
; #pragma unroll
;         for (int a = 0; a < 2; ++a)
; #pragma unroll
;             for (int b = 0; b < 2; ++b)
; #pragma unroll
;                 for (int m = 0; m < 4; ++m)
; #pragma unroll
;                     for (int n = 0; n < 2; ++n) acc[a][b][m][n] = (f32x4){0.f, 0.f, 0.f, 0.f};
;         cur = nxt; cA = nA; cB = nB; ++ui;
.LBB0_887:
	s_ashr_i32 s25, s24, 31
	s_lshl_b64 s[38:39], s[24:25], 20
	s_add_u32 s38, s33, s38
	s_addc_u32 s39, s51, s39
	s_and_b64 s[40:41], s[6:7], exec
	s_cselect_b32 s25, s39, s45
	s_cselect_b32 s70, s38, s44
	s_ashr_i32 s23, s22, 31
	s_lshl_b64 s[40:41], s[22:23], 20
	s_add_u32 s40, s52, s40
	s_addc_u32 s41, s53, s41
	s_and_b64 s[48:49], s[6:7], exec
	s_cselect_b32 s23, s41, s47
	s_cselect_b32 s71, s40, s46
	s_add_u32 s44, s44, 0x80080
	s_addc_u32 s45, s45, 0
	s_add_u32 s72, s46, 0x100
	v_mov_b32_e32 v2, 0
	s_addc_u32 s73, s47, 0
	s_mov_b32 s74, -2
	v_mov_b32_e32 v3, v2
	v_mov_b64_e32 v[4:5], 0
	v_mov_b64_e32 v[6:7], 0
	v_mov_b64_e32 v[8:9], 0
	v_mov_b64_e32 v[10:11], 0
	v_mov_b64_e32 v[12:13], 0
	v_mov_b64_e32 v[14:15], 0
	v_mov_b64_e32 v[16:17], 0
	v_mov_b64_e32 v[18:19], 0
	v_mov_b64_e32 v[20:21], 0
	v_mov_b64_e32 v[22:23], 0
	v_mov_b64_e32 v[24:25], 0
	v_mov_b64_e32 v[26:27], 0
	v_mov_b64_e32 v[28:29], 0
	v_mov_b64_e32 v[30:31], 0
	v_mov_b64_e32 v[32:33], 0
	v_mov_b64_e32 v[34:35], 0
	v_mov_b64_e32 v[36:37], 0
	v_mov_b64_e32 v[38:39], 0
	v_mov_b64_e32 v[40:41], 0
	v_mov_b64_e32 v[42:43], 0
	v_mov_b64_e32 v[44:45], 0
	v_mov_b64_e32 v[46:47], 0
	v_mov_b64_e32 v[48:49], 0
	v_mov_b64_e32 v[50:51], 0
	v_mov_b64_e32 v[52:53], 0
	v_mov_b64_e32 v[54:55], 0
	v_mov_b64_e32 v[56:57], 0
	v_mov_b64_e32 v[58:59], 0
	v_mov_b64_e32 v[60:61], 0
	v_mov_b64_e32 v[62:63], 0
	v_mov_b64_e32 v[64:65], 0
	v_mov_b64_e32 v[66:67], 0
	v_mov_b64_e32 v[68:69], 0
	v_mov_b64_e32 v[70:71], 0
	v_mov_b64_e32 v[72:73], 0
	v_mov_b64_e32 v[74:75], 0
	v_mov_b64_e32 v[76:77], 0
	v_mov_b64_e32 v[78:79], 0
	v_mov_b64_e32 v[80:81], 0
	v_mov_b64_e32 v[82:83], 0
	v_mov_b64_e32 v[84:85], 0
	v_mov_b64_e32 v[86:87], 0
	v_mov_b64_e32 v[88:89], 0
	v_mov_b64_e32 v[90:91], 0
	v_mov_b64_e32 v[92:93], 0
	v_mov_b64_e32 v[94:95], 0
	v_mov_b64_e32 v[96:97], 0
	v_mov_b64_e32 v[98:99], 0
	v_mov_b64_e32 v[100:101], 0
	v_mov_b64_e32 v[102:103], 0
	v_mov_b64_e32 v[104:105], 0
	v_mov_b64_e32 v[106:107], 0
	v_mov_b64_e32 v[108:109], 0
	v_mov_b64_e32 v[110:111], 0
	v_mov_b64_e32 v[112:113], 0
	v_mov_b64_e32 v[114:115], 0
	v_mov_b64_e32 v[116:117], 0
	v_mov_b64_e32 v[118:119], 0
	v_mov_b64_e32 v[120:121], 0
	v_mov_b64_e32 v[122:123], 0
	v_mov_b64_e32 v[124:125], 0
	v_mov_b64_e32 v[126:127], 0
	v_mov_b64_e32 v[128:129], 0
	s_add_u32 s80, s44, 0xfff80000
	s_addc_u32 s81, s45, -1
	s_cmp_eq_u32 s101, 0
	s_cbranch_scc0 .Lkt_2
.LBB0_888:
	ds_read_b128 v[130:133], v172
	ds_read_b128 v[134:137], v172 offset:1024
	ds_read_b128 v[138:141], v172 offset:2048
	ds_read_b128 v[142:145], v172 offset:3072
	ds_read_b128 v[162:165], v173
	ds_read_b128 v[166:169], v173 offset:1024
	ds_read_b128 v[176:179], v173 offset:2048
	ds_read_b128 v[180:183], v173 offset:3072
	s_add_u32 s18, s44, 0xfff80080
	s_addc_u32 s19, s45, -1
	s_cmp_eq_u32 s74, 28
	s_cselect_b32 s49, s25, s19
	s_cselect_b32 s48, s70, s18
	s_cselect_b32 s47, s23, s73
	s_cselect_b32 s46, s71, s72
	s_add_i32 m0, s43, 0xc000
	ds_read_b128 v[184:187], v174
	ds_read_b128 v[188:191], v174 offset:1024
	ds_read_b128 v[192:195], v174 offset:2048
	ds_read_b128 v[196:199], v174 offset:3072
	ds_read_b128 v[200:203], v174 offset:4096
	ds_read_b128 v[204:207], v174 offset:5120
	ds_read_b128 v[208:211], v174 offset:6144
	ds_read_b128 v[212:215], v174 offset:7168
	global_load_lds_dwordx4 v154, s[44:45]
	s_add_i32 m0, s43, 0xe000
	s_nop 0
	global_load_lds_dwordx4 v156, s[44:45]
	s_mov_b32 m0, s63
	s_nop 0
	global_load_lds_dwordx4 v152, s[80:81]
	s_mov_b32 m0, s64
	s_nop 0
	global_load_lds_dwordx4 v148, s[80:81]
	s_waitcnt lgkmcnt(0)
	s_barrier
	s_waitcnt lgkmcnt(0)
	v_mfma_f32_16x16x32_bf16 v[126:129], v[130:133], v[184:187], v[126:129]
	v_mfma_f32_16x16x32_bf16 v[122:125], v[138:141], v[184:187], v[122:125]
	v_mfma_f32_16x16x32_bf16 v[110:113], v[130:133], v[192:195], v[110:113]
	v_mfma_f32_16x16x32_bf16 v[106:109], v[138:141], v[192:195], v[106:109]
	v_mfma_f32_16x16x32_bf16 v[94:97], v[130:133], v[200:203], v[94:97]
	v_mfma_f32_16x16x32_bf16 v[90:93], v[138:141], v[200:203], v[90:93]
	v_mfma_f32_16x16x32_bf16 v[78:81], v[130:133], v[208:211], v[78:81]
	v_mfma_f32_16x16x32_bf16 v[74:77], v[138:141], v[208:211], v[74:77]
	v_mfma_f32_16x16x32_bf16 v[126:129], v[134:137], v[188:191], v[126:129]
	v_mfma_f32_16x16x32_bf16 v[122:125], v[142:145], v[188:191], v[122:125]
	v_mfma_f32_16x16x32_bf16 v[110:113], v[134:137], v[196:199], v[110:113]
	v_mfma_f32_16x16x32_bf16 v[106:109], v[142:145], v[196:199], v[106:109]
	v_mfma_f32_16x16x32_bf16 v[94:97], v[134:137], v[204:207], v[94:97]
	v_mfma_f32_16x16x32_bf16 v[90:93], v[142:145], v[204:207], v[90:93]
	v_mfma_f32_16x16x32_bf16 v[78:81], v[134:137], v[212:215], v[78:81]
	v_mfma_f32_16x16x32_bf16 v[74:77], v[142:145], v[212:215], v[74:77]
	v_mfma_f32_16x16x32_bf16 v[118:121], v[162:165], v[184:187], v[118:121]
	v_mfma_f32_16x16x32_bf16 v[114:117], v[176:179], v[184:187], v[114:117]
	v_mfma_f32_16x16x32_bf16 v[102:105], v[162:165], v[192:195], v[102:105]
	v_mfma_f32_16x16x32_bf16 v[98:101], v[176:179], v[192:195], v[98:101]
	v_mfma_f32_16x16x32_bf16 v[86:89], v[162:165], v[200:203], v[86:89]
	v_mfma_f32_16x16x32_bf16 v[82:85], v[176:179], v[200:203], v[82:85]
	v_mfma_f32_16x16x32_bf16 v[70:73], v[162:165], v[208:211], v[70:73]
	v_mfma_f32_16x16x32_bf16 v[66:69], v[176:179], v[208:211], v[66:69]
	v_mfma_f32_16x16x32_bf16 v[118:121], v[166:169], v[188:191], v[118:121]
	v_mfma_f32_16x16x32_bf16 v[114:117], v[180:183], v[188:191], v[114:117]
	v_mfma_f32_16x16x32_bf16 v[102:105], v[166:169], v[196:199], v[102:105]
	v_mfma_f32_16x16x32_bf16 v[98:101], v[180:183], v[196:199], v[98:101]
	v_mfma_f32_16x16x32_bf16 v[86:89], v[166:169], v[204:207], v[86:89]
	v_mfma_f32_16x16x32_bf16 v[82:85], v[180:183], v[204:207], v[82:85]
	v_mfma_f32_16x16x32_bf16 v[70:73], v[166:169], v[212:215], v[70:73]
	v_mfma_f32_16x16x32_bf16 v[66:69], v[180:183], v[212:215], v[66:69]
	s_waitcnt vmcnt(8)
	s_barrier
; #define PG8_STAGE(bufoff, gbase, voff) do { _Pragma("unroll") for (int _i = 0; _i < 2; ++_i) \
;         __builtin_amdgcn_global_load_lds((const unsigned*)((const char*)(gbase) + (voff)[_i]), (PG8_LAS unsigned*)(lds + (bufoff) + ldsw + _i * 8192), 16, 0, 0); } while (0)
; #define PG8_LDA(dst, b, h) do { _Pragma("unroll") for (int m = 0; m < 4; ++m) _Pragma("unroll") for (int k = 0; k < 2; ++k) dst[m][k] = *(const PG8_LAS bf16x8*)(lds + PG8_SA(b, h) + aoff + m * 2048 + k * 1024); } while (0)
; #define PG8_LDB(dst, b, h) do { _Pragma("unroll") for (int n = 0; n < 2; ++n) _Pragma("unroll") for (int k = 0; k < 2; ++k) dst[n][k] = *(const PG8_LAS bf16x8*)(lds + PG8_SB(b, h) + boff + n * 2048 + k * 1024); } while (0)
; #define PG8_MMA(ai, bj, At, Bt) do { __builtin_amdgcn_s_setprio(1); _Pragma("unroll") for (int m = 0; m < 4; ++m) _Pragma("unroll") for (int n = 0; n < 2; ++n) _Pragma("unroll") for (int k = 0; k < 2; ++k) \
;         acc[ai][bj][m][n] = __builtin_amdgcn_mfma_f32_16x16x32_bf16(Bt[n][k], At[m][k], acc[ai][bj][m][n], 0, 0, 0); __builtin_amdgcn_s_setprio(0); } while (0)
; #define PG8_WAIT_V(n) asm volatile("s_waitcnt vmcnt(" #n ")" ::: "memory")
; #define PG8_WAIT_L(n) asm volatile("s_waitcnt lgkmcnt(" #n ")" ::: "memory")
; #define PG8_BAR __builtin_amdgcn_s_barrier()
; #define PG8_SCHED __builtin_amdgcn_sched_barrier(0)
; template <class Epi, class Sched, bool ALIGN_EPI = false, bool SP2 = false>
; __device__ __forceinline__ void gemm_phase(PG8_LAS unsigned char* lds, const Gemm g, const Sched& S, const Epi& E) {
;     ...
;             PG8_LDA(At, 0, 1); PG8_STAGE(PG8_SB(0, 0), b2, voffB); PG8_STAGE(PG8_SB(0, 1), b2 + hB, voffB); PG8_STAGE(PG8_SA(0, 0), a2, voffA);
;             PG8_WAIT_V(8); PG8_WAIT_L(0); PG8_BAR; PG8_MMA(1, 0, At, B0); PG8_MMA(1, 1, At, B1); PG8_BAR; PG8_SCHED;
;             PG8_LDB(B0, 1, 0); PG8_LDB(B1, 1, 1); PG8_SCHED; PG8_LDA(At, 1, 0); PG8_STAGE(PG8_SA(0, 1), a2 + hA, voffA);
	s_add_i32 s18, s66, s58
	s_add_u32 s78, s46, s16
	s_addc_u32 s79, s47, s17
	s_mov_b32 m0, s18
	ds_read_b128 v[184:187], v174 offset:16384
	ds_read_b128 v[188:191], v174 offset:17408
	ds_read_b128 v[192:195], v174 offset:18432
	ds_read_b128 v[196:199], v174 offset:19456
	ds_read_b128 v[200:203], v174 offset:20480
	ds_read_b128 v[204:207], v174 offset:21504
	ds_read_b128 v[208:211], v174 offset:22528
	ds_read_b128 v[212:215], v174 offset:23552
	global_load_lds_dwordx4 v150, s[46:47]
	s_add_i32 m0, s18, 0x2000
	s_add_u32 s76, s46, 0x80000
	s_addc_u32 s77, s47, 0
	s_add_i32 s18, s67, s58
	global_load_lds_dwordx4 v146, s[46:47]
	s_mov_b32 m0, s18
	s_nop 0
	global_load_lds_dwordx4 v150, s[76:77]
	s_add_i32 m0, s18, 0x2000
	s_nop 0
	global_load_lds_dwordx4 v146, s[76:77]
	s_add_u32 s80, s48, s16
	s_addc_u32 s81, s49, s17
	s_waitcnt lgkmcnt(0)
	s_barrier
	s_waitcnt lgkmcnt(0)
	v_mfma_f32_16x16x32_bf16 v[62:65], v[130:133], v[184:187], v[62:65]
	v_mfma_f32_16x16x32_bf16 v[58:61], v[138:141], v[184:187], v[58:61]
	v_mfma_f32_16x16x32_bf16 v[46:49], v[130:133], v[192:195], v[46:49]
	v_mfma_f32_16x16x32_bf16 v[42:45], v[138:141], v[192:195], v[42:45]
	v_mfma_f32_16x16x32_bf16 v[30:33], v[130:133], v[200:203], v[30:33]
	v_mfma_f32_16x16x32_bf16 v[26:29], v[138:141], v[200:203], v[26:29]
	v_mfma_f32_16x16x32_bf16 v[14:17], v[130:133], v[208:211], v[14:17]
	v_mfma_f32_16x16x32_bf16 v[10:13], v[138:141], v[208:211], v[10:13]
	v_mfma_f32_16x16x32_bf16 v[62:65], v[134:137], v[188:191], v[62:65]
	v_mfma_f32_16x16x32_bf16 v[58:61], v[142:145], v[188:191], v[58:61]
	v_mfma_f32_16x16x32_bf16 v[46:49], v[134:137], v[196:199], v[46:49]
	v_mfma_f32_16x16x32_bf16 v[42:45], v[142:145], v[196:199], v[42:45]
	v_mfma_f32_16x16x32_bf16 v[30:33], v[134:137], v[204:207], v[30:33]
	v_mfma_f32_16x16x32_bf16 v[26:29], v[142:145], v[204:207], v[26:29]
	v_mfma_f32_16x16x32_bf16 v[14:17], v[134:137], v[212:215], v[14:17]
	v_mfma_f32_16x16x32_bf16 v[10:13], v[142:145], v[212:215], v[10:13]
	v_mfma_f32_16x16x32_bf16 v[54:57], v[162:165], v[184:187], v[54:57]
	v_mfma_f32_16x16x32_bf16 v[50:53], v[176:179], v[184:187], v[50:53]
	v_mfma_f32_16x16x32_bf16 v[38:41], v[162:165], v[192:195], v[38:41]
	v_mfma_f32_16x16x32_bf16 v[34:37], v[176:179], v[192:195], v[34:37]
	v_mfma_f32_16x16x32_bf16 v[22:25], v[162:165], v[200:203], v[22:25]
	v_mfma_f32_16x16x32_bf16 v[18:21], v[176:179], v[200:203], v[18:21]
	v_mfma_f32_16x16x32_bf16 v[6:9], v[162:165], v[208:211], v[6:9]
	v_mfma_f32_16x16x32_bf16 v[2:5], v[176:179], v[208:211], v[2:5]
	v_mfma_f32_16x16x32_bf16 v[54:57], v[166:169], v[188:191], v[54:57]
	v_mfma_f32_16x16x32_bf16 v[50:53], v[180:183], v[188:191], v[50:53]
	v_mfma_f32_16x16x32_bf16 v[38:41], v[166:169], v[196:199], v[38:41]
	v_mfma_f32_16x16x32_bf16 v[34:37], v[180:183], v[196:199], v[34:37]
	v_mfma_f32_16x16x32_bf16 v[22:25], v[166:169], v[204:207], v[22:25]
	v_mfma_f32_16x16x32_bf16 v[18:21], v[180:183], v[204:207], v[18:21]
	v_mfma_f32_16x16x32_bf16 v[6:9], v[166:169], v[212:215], v[6:9]
	v_mfma_f32_16x16x32_bf16 v[2:5], v[180:183], v[212:215], v[2:5]
	s_waitcnt vmcnt(4)
	s_barrier
	s_add_i32 s18, 0, 0x18000
	s_add_i32 s19, 0, 0x1c000
	v_add_u32_e32 v142, s18, v170
	v_add_u32_e32 v175, s19, v170
	ds_read_b128 v[130:133], v142
	ds_read_b128 v[134:137], v142 offset:1024
	ds_read_b128 v[138:141], v142 offset:2048
	ds_read_b128 v[142:145], v142 offset:3072
	ds_read_b128 v[162:165], v175
	ds_read_b128 v[166:169], v175 offset:1024
	ds_read_b128 v[176:179], v175 offset:2048
	ds_read_b128 v[180:183], v175 offset:3072
	ds_read_b128 v[184:187], v174 offset:32768
	ds_read_b128 v[188:191], v174 offset:33792
	ds_read_b128 v[192:195], v174 offset:34816
	ds_read_b128 v[196:199], v174 offset:35840
	ds_read_b128 v[200:203], v174 offset:36864
	ds_read_b128 v[204:207], v174 offset:37888
	ds_read_b128 v[208:211], v174 offset:38912
	ds_read_b128 v[212:215], v174 offset:39936
	s_mov_b32 m0, s43
	s_nop 0
	global_load_lds_dwordx4 v152, s[48:49]
	s_mov_b32 m0, s59
	s_nop 0
	global_load_lds_dwordx4 v148, s[48:49]
	s_add_u32 s48, s48, 0x80000
	s_addc_u32 s49, s49, 0
	s_mov_b32 m0, s60
	s_nop 0
	global_load_lds_dwordx4 v152, s[48:49]
	s_mov_b32 m0, s61
	s_nop 0
	global_load_lds_dwordx4 v148, s[48:49]
	s_waitcnt lgkmcnt(0)
	s_barrier
; #define PG8_STAGE(bufoff, gbase, voff) do { _Pragma("unroll") for (int _i = 0; _i < 2; ++_i) \
;         __builtin_amdgcn_global_load_lds((const unsigned*)((const char*)(gbase) + (voff)[_i]), (PG8_LAS unsigned*)(lds + (bufoff) + ldsw + _i * 8192), 16, 0, 0); } while (0)
; #define PG8_LDA(dst, b, h) do { _Pragma("unroll") for (int m = 0; m < 4; ++m) _Pragma("unroll") for (int k = 0; k < 2; ++k) dst[m][k] = *(const PG8_LAS bf16x8*)(lds + PG8_SA(b, h) + aoff + m * 2048 + k * 1024); } while (0)
; #define PG8_MMA(ai, bj, At, Bt) do { __builtin_amdgcn_s_setprio(1); _Pragma("unroll") for (int m = 0; m < 4; ++m) _Pragma("unroll") for (int n = 0; n < 2; ++n) _Pragma("unroll") for (int k = 0; k < 2; ++k) \
;         acc[ai][bj][m][n] = __builtin_amdgcn_mfma_f32_16x16x32_bf16(Bt[n][k], At[m][k], acc[ai][bj][m][n], 0, 0, 0); __builtin_amdgcn_s_setprio(0); } while (0)
; #define PG8_WAIT_V(n) asm volatile("s_waitcnt vmcnt(" #n ")" ::: "memory")
; #define PG8_WAIT_L(n) asm volatile("s_waitcnt lgkmcnt(" #n ")" ::: "memory")
; #define PG8_BAR __builtin_amdgcn_s_barrier()
; #define PG8_SCHED __builtin_amdgcn_sched_barrier(0)
; template <class Epi, class Sched, bool ALIGN_EPI = false, bool SP2 = false>
; __device__ __forceinline__ void gemm_phase(PG8_LAS unsigned char* lds, const Gemm g, const Sched& S, const Epi& E) {
;     ...
;             PG8_WAIT_V(8); PG8_WAIT_L(0); PG8_BAR; PG8_MMA(0, 0, At, B0); PG8_MMA(0, 1, At, B1); PG8_BAR; PG8_SCHED;
;             PG8_LDA(At, 1, 1); PG8_STAGE(PG8_SB(1, 0), b3, voffB); PG8_STAGE(PG8_SB(1, 1), b3 + hB, voffB); PG8_STAGE(PG8_SA(1, 0), a3, voffA);
;             PG8_WAIT_V(8); PG8_WAIT_L(0); PG8_BAR; PG8_MMA(1, 0, At, B0); PG8_MMA(1, 1, At, B1); PG8_BAR; PG8_SCHED;
	s_waitcnt lgkmcnt(0)
	v_mfma_f32_16x16x32_bf16 v[126:129], v[130:133], v[184:187], v[126:129]
	v_mfma_f32_16x16x32_bf16 v[122:125], v[138:141], v[184:187], v[122:125]
	v_mfma_f32_16x16x32_bf16 v[110:113], v[130:133], v[192:195], v[110:113]
	v_mfma_f32_16x16x32_bf16 v[106:109], v[138:141], v[192:195], v[106:109]
	v_mfma_f32_16x16x32_bf16 v[94:97], v[130:133], v[200:203], v[94:97]
	v_mfma_f32_16x16x32_bf16 v[90:93], v[138:141], v[200:203], v[90:93]
	v_mfma_f32_16x16x32_bf16 v[78:81], v[130:133], v[208:211], v[78:81]
	v_mfma_f32_16x16x32_bf16 v[74:77], v[138:141], v[208:211], v[74:77]
	v_mfma_f32_16x16x32_bf16 v[126:129], v[134:137], v[188:191], v[126:129]
	v_mfma_f32_16x16x32_bf16 v[122:125], v[142:145], v[188:191], v[122:125]
	v_mfma_f32_16x16x32_bf16 v[110:113], v[134:137], v[196:199], v[110:113]
	v_mfma_f32_16x16x32_bf16 v[106:109], v[142:145], v[196:199], v[106:109]
	v_mfma_f32_16x16x32_bf16 v[94:97], v[134:137], v[204:207], v[94:97]
	v_mfma_f32_16x16x32_bf16 v[90:93], v[142:145], v[204:207], v[90:93]
	v_mfma_f32_16x16x32_bf16 v[78:81], v[134:137], v[212:215], v[78:81]
	v_mfma_f32_16x16x32_bf16 v[74:77], v[142:145], v[212:215], v[74:77]
	v_mfma_f32_16x16x32_bf16 v[118:121], v[162:165], v[184:187], v[118:121]
	v_mfma_f32_16x16x32_bf16 v[114:117], v[176:179], v[184:187], v[114:117]
	v_mfma_f32_16x16x32_bf16 v[102:105], v[162:165], v[192:195], v[102:105]
	v_mfma_f32_16x16x32_bf16 v[98:101], v[176:179], v[192:195], v[98:101]
	v_mfma_f32_16x16x32_bf16 v[86:89], v[162:165], v[200:203], v[86:89]
	v_mfma_f32_16x16x32_bf16 v[82:85], v[176:179], v[200:203], v[82:85]
	v_mfma_f32_16x16x32_bf16 v[70:73], v[162:165], v[208:211], v[70:73]
	v_mfma_f32_16x16x32_bf16 v[66:69], v[176:179], v[208:211], v[66:69]
	v_mfma_f32_16x16x32_bf16 v[118:121], v[166:169], v[188:191], v[118:121]
	v_mfma_f32_16x16x32_bf16 v[114:117], v[180:183], v[188:191], v[114:117]
	v_mfma_f32_16x16x32_bf16 v[102:105], v[166:169], v[196:199], v[102:105]
	v_mfma_f32_16x16x32_bf16 v[98:101], v[180:183], v[196:199], v[98:101]
	v_mfma_f32_16x16x32_bf16 v[86:89], v[166:169], v[204:207], v[86:89]
	v_mfma_f32_16x16x32_bf16 v[82:85], v[180:183], v[204:207], v[82:85]
	v_mfma_f32_16x16x32_bf16 v[70:73], v[166:169], v[212:215], v[70:73]
	v_mfma_f32_16x16x32_bf16 v[66:69], v[180:183], v[212:215], v[66:69]
	s_barrier
	s_add_i32 s18, s18, s58
	s_mov_b32 m0, s18
	ds_read_b128 v[184:187], v174 offset:49152
	ds_read_b128 v[188:191], v174 offset:50176
	ds_read_b128 v[192:195], v174 offset:51200
	ds_read_b128 v[196:199], v174 offset:52224
	ds_read_b128 v[200:203], v174 offset:53248
	ds_read_b128 v[204:207], v174 offset:54272
	ds_read_b128 v[208:211], v174 offset:55296
	ds_read_b128 v[212:215], v174 offset:56320
	global_load_lds_dwordx4 v150, s[78:79]
	s_add_i32 m0, s18, 0x2000
	s_add_u32 s46, s46, 0x80080
	s_addc_u32 s47, s47, 0
	s_add_i32 s18, s19, s58
	global_load_lds_dwordx4 v146, s[78:79]
	s_mov_b32 m0, s18
	s_nop 0
	global_load_lds_dwordx4 v150, s[46:47]
	s_add_i32 m0, s18, 0x2000
	s_nop 0
	global_load_lds_dwordx4 v146, s[46:47]
	s_waitcnt lgkmcnt(0)
	s_barrier
	s_waitcnt lgkmcnt(0)
	v_mfma_f32_16x16x32_bf16 v[62:65], v[130:133], v[184:187], v[62:65]
	v_mfma_f32_16x16x32_bf16 v[58:61], v[138:141], v[184:187], v[58:61]
	v_mfma_f32_16x16x32_bf16 v[46:49], v[130:133], v[192:195], v[46:49]
	v_mfma_f32_16x16x32_bf16 v[42:45], v[138:141], v[192:195], v[42:45]
	v_mfma_f32_16x16x32_bf16 v[30:33], v[130:133], v[200:203], v[30:33]
	v_mfma_f32_16x16x32_bf16 v[26:29], v[138:141], v[200:203], v[26:29]
	v_mfma_f32_16x16x32_bf16 v[14:17], v[130:133], v[208:211], v[14:17]
	v_mfma_f32_16x16x32_bf16 v[10:13], v[138:141], v[208:211], v[10:13]
	v_mfma_f32_16x16x32_bf16 v[62:65], v[134:137], v[188:191], v[62:65]
	v_mfma_f32_16x16x32_bf16 v[58:61], v[142:145], v[188:191], v[58:61]
	v_mfma_f32_16x16x32_bf16 v[46:49], v[134:137], v[196:199], v[46:49]
	v_mfma_f32_16x16x32_bf16 v[42:45], v[142:145], v[196:199], v[42:45]
	v_mfma_f32_16x16x32_bf16 v[30:33], v[134:137], v[204:207], v[30:33]
	v_mfma_f32_16x16x32_bf16 v[26:29], v[142:145], v[204:207], v[26:29]
	v_mfma_f32_16x16x32_bf16 v[14:17], v[134:137], v[212:215], v[14:17]
	v_mfma_f32_16x16x32_bf16 v[10:13], v[142:145], v[212:215], v[10:13]
	v_mfma_f32_16x16x32_bf16 v[54:57], v[162:165], v[184:187], v[54:57]
	v_mfma_f32_16x16x32_bf16 v[50:53], v[176:179], v[184:187], v[50:53]
	v_mfma_f32_16x16x32_bf16 v[38:41], v[162:165], v[192:195], v[38:41]
	v_mfma_f32_16x16x32_bf16 v[34:37], v[176:179], v[192:195], v[34:37]
	v_mfma_f32_16x16x32_bf16 v[22:25], v[162:165], v[200:203], v[22:25]
	v_mfma_f32_16x16x32_bf16 v[18:21], v[176:179], v[200:203], v[18:21]
	v_mfma_f32_16x16x32_bf16 v[6:9], v[162:165], v[208:211], v[6:9]
	v_mfma_f32_16x16x32_bf16 v[2:5], v[176:179], v[208:211], v[2:5]
	v_mfma_f32_16x16x32_bf16 v[54:57], v[166:169], v[188:191], v[54:57]
	v_mfma_f32_16x16x32_bf16 v[50:53], v[180:183], v[188:191], v[50:53]
	v_mfma_f32_16x16x32_bf16 v[38:41], v[166:169], v[196:199], v[38:41]
	v_mfma_f32_16x16x32_bf16 v[34:37], v[180:183], v[196:199], v[34:37]
	v_mfma_f32_16x16x32_bf16 v[22:25], v[166:169], v[204:207], v[22:25]
	v_mfma_f32_16x16x32_bf16 v[18:21], v[180:183], v[204:207], v[18:21]
	v_mfma_f32_16x16x32_bf16 v[6:9], v[166:169], v[212:215], v[6:9]
	v_mfma_f32_16x16x32_bf16 v[2:5], v[180:183], v[212:215], v[2:5]
	s_waitcnt vmcnt(6)
	s_barrier
	s_add_i32 s74, s74, 2
	s_add_u32 s44, s44, 0x100
	s_addc_u32 s45, s45, 0
	s_add_u32 s72, s72, 0x100
	s_addc_u32 s73, s73, 0
	s_cmp_gt_u32 s74, 29
	s_cbranch_scc0 .LBB0_888
	s_branch .Lkafter_2

; #define PG8_BAR __builtin_amdgcn_s_barrier()
; template <class Epi, class Sched, bool ALIGN_EPI = false, bool SP2 = false>
; __device__ __forceinline__ void gemm_phase(PG8_LAS unsigned char* lds, const Gemm g, const Sched& S, const Epi& E) {
;     ...
;         if constexpr (ALIGN_EPI) { if (wr == 0) PG8_BAR; }
.Lkafter_2:
	s_and_b64 vcc, exec, s[20:21]
	s_cbranch_vccz .LBB0_891
	s_barrier

; #define PG8_STAGE(bufoff, gbase, voff) do { _Pragma("unroll") for (int _i = 0; _i < 2; ++_i) \
;         __builtin_amdgcn_global_load_lds((const unsigned*)((const char*)(gbase) + (voff)[_i]), (PG8_LAS unsigned*)(lds + (bufoff) + ldsw + _i * 8192), 16, 0, 0); } while (0)
; #define PG8_WAIT_V(n) asm volatile("s_waitcnt vmcnt(" #n ")" ::: "memory")
; #define PG8_BAR __builtin_amdgcn_s_barrier()
; template <class Epi, class Sched, bool ALIGN_EPI = false, bool SP2 = false>
; __device__ __forceinline__ void gemm_phase(PG8_LAS unsigned char* lds, const Gemm g, const Sched& S, const Epi& E) {
;     ...
;     const int tid = tid_o, wid = __builtin_amdgcn_readfirstlane(tid >> 6), lane = tid & 63, wr = wid >> 2, wc = wid & 3, fr = lane & 15, fq = lane >> 4;
;     const int K = g.K, nt = K / BK;
;     unsigned voffA[2], voffB[2];
; #pragma unroll
;     for (int i = 0; i < 2; ++i) { int R, C; stage_rc(tid * 16 + i * 8192, R, C); const int Rb = Epi::PERM ? ((R & ~31) + perm32(R & 31)) : R;
;         voffA[i] = (unsigned)(R * g.lda + C) * 2u; voffB[i] = (unsigned)(Rb * g.ldb + C) * 2u; }
;     const size_t kstep = (size_t)(BK * 2);
;     const size_t hA = (size_t)HALF * g.lda * 2, hB = (size_t)HALF * g.ldb * 2;
;     const size_t tA = 2 * hA, tB = 2 * hB, pnA = (size_t)g.a_pn_off * 2;
;     const unsigned ldsw = (unsigned)wid * 1024u;
;     const int aoff = lds_byte(wr * 64 + fr, fq * 8), boff = lds_byte(wc * 32 + fr, fq * 8);
;     ...
;         PG8_STAGE(PG8_SB(1, 0), cB + kstep, voffB); PG8_STAGE(PG8_SA(1, 0), cA + kstep, voffA); PG8_STAGE(PG8_SB(1, 1), cB + hB + kstep, voffB);
;         PG8_WAIT_V(6); PG8_BAR;
.LBB0_953:
	s_add_u32 s16, s6, 0x15800000
	s_addc_u32 s17, s7, 0
	s_add_u32 s20, s6, 0x1e00000
	s_mov_b64 s[22:23], 0x80
	s_addc_u32 s21, s7, 0
	s_and_b32 s67, s9, 3
	s_add_i32 m0, s62, 0x18000
	v_lshl_add_u64 v[8:9], v[8:9], 0, s[22:23]
	s_lshl_b32 s9, s24, 13
	s_lshl_b32 s18, s67, 12
	s_waitcnt vmcnt(2)
	s_barrier
	global_load_lds_dwordx4 v[8:9], off
	v_lshl_add_u64 v[6:7], v[6:7], 0, s[22:23]
	s_add_i32 m0, s62, 0x1a000
	s_add_i32 s69, s62, 0x8000
	s_add_i32 s70, s62, 0xa000
	global_load_lds_dwordx4 v[6:7], off
	v_lshl_add_u64 v[2:3], v[2:3], 0, s[22:23]
	s_mov_b32 m0, s69
	s_add_u32 s6, s50, 0x80080
	global_load_lds_dwordx4 v[2:3], off
	v_lshl_add_u64 v[2:3], v[4:5], 0, s[22:23]
	s_mov_b32 m0, s70
	s_addc_u32 s7, s51, 0
	global_load_lds_dwordx4 v[2:3], off
	s_add_i32 m0, s62, 0x1c000
	v_lshl_add_u64 v[2:3], s[6:7], 0, v[180:181]
	global_load_lds_dwordx4 v[2:3], off
	v_lshl_add_u64 v[2:3], s[6:7], 0, v[184:185]
	s_add_i32 m0, s62, 0x1e000
	s_cmpk_lt_u32 s8, 0x100
	global_load_lds_dwordx4 v[2:3], off
	v_bfe_u32 v3, v10, 4, 2
	v_and_b32_e32 v2, 15, v10
	v_lshlrev_b32_e32 v5, 4, v3
	v_lshl_or_b32 v1, s24, 6, v2
	v_lshl_or_b32 v2, v2, 6, v5
	v_lshlrev_b32_e32 v5, 2, v10
	v_and_b32_e32 v5, 32, v5
	v_bitop3_b32 v6, v2, s9, v5 bitop3:0xde
	v_bitop3_b32 v206, v2, s18, v5 bitop3:0xde
	v_lshlrev_b32_e32 v2, 15, v11
	v_and_b32_e32 v2, 0xffff0000, v2
	v_lshlrev_b32_e32 v4, 3, v3
	v_cmp_eq_u32_e64 s[6:7], 0, v3
	v_lshl_add_u32 v2, v12, 12, v2
	v_and_b32_e32 v3, 1, v11
	v_lshl_or_b32 v2, v3, 6, v2
	v_lshl_add_u32 v186, v13, 1, v2
	v_lshlrev_b32_e32 v2, 15, v14
	v_and_b32_e32 v2, 0xffff0000, v2
	s_waitcnt vmcnt(6)
	v_lshl_add_u32 v2, v15, 12, v2
	v_and_b32_e32 v3, 1, v14
	s_cselect_b64 s[24:25], -1, 0
	v_lshl_or_b32 v2, v3, 6, v2
	s_add_i32 s72, 0, 0x10000
	s_add_i32 s73, 0, 0x14000
	v_lshl_or_b32 v207, s67, 5, v4
	s_waitcnt lgkmcnt(0)
	s_ashr_i32 s71, s66, 31
	v_mov_b32_e32 v187, v181
	v_lshl_add_u32 v188, v16, 1, v2
	v_mov_b32_e32 v189, v181
	v_mov_b64_e32 v[190:191], 0x200
	v_mov_b64_e32 v[192:193], 0x1ff
	v_add_u32_e32 v208, s72, v206
	v_add_u32_e32 v209, s73, v206
	v_add_u32_e32 v210, 0, v6
	v_mbcnt_hi_u32_b32 v211, -1, v222
	s_mov_b32 s74, 0
	s_barrier
	v_readfirstlane_b32 s101, v0
	s_nop 3
	s_lshr_b32 s101, s101, 8
	s_branch .LBB0_956

; #define PG8_STAGE(bufoff, gbase, voff) do { _Pragma("unroll") for (int _i = 0; _i < 2; ++_i) \
;         __builtin_amdgcn_global_load_lds((const unsigned*)((const char*)(gbase) + (voff)[_i]), (PG8_LAS unsigned*)(lds + (bufoff) + ldsw + _i * 8192), 16, 0, 0); } while (0)
; #define PG8_LDA(dst, b, h) do { _Pragma("unroll") for (int m = 0; m < 4; ++m) _Pragma("unroll") for (int k = 0; k < 2; ++k) dst[m][k] = *(const PG8_LAS bf16x8*)(lds + PG8_SA(b, h) + aoff + m * 2048 + k * 1024); } while (0)
; #define PG8_LDB(dst, b, h) do { _Pragma("unroll") for (int n = 0; n < 2; ++n) _Pragma("unroll") for (int k = 0; k < 2; ++k) dst[n][k] = *(const PG8_LAS bf16x8*)(lds + PG8_SB(b, h) + boff + n * 2048 + k * 1024); } while (0)
; #define PG8_MMA(ai, bj, At, Bt) do { __builtin_amdgcn_s_setprio(1); _Pragma("unroll") for (int m = 0; m < 4; ++m) _Pragma("unroll") for (int n = 0; n < 2; ++n) _Pragma("unroll") for (int k = 0; k < 2; ++k) \
;         acc[ai][bj][m][n] = __builtin_amdgcn_mfma_f32_16x16x32_bf16(Bt[n][k], At[m][k], acc[ai][bj][m][n], 0, 0, 0); __builtin_amdgcn_s_setprio(0); } while (0)
; #define PG8_WAIT_V(n) asm volatile("s_waitcnt vmcnt(" #n ")" ::: "memory")
; #define PG8_WAIT_L(n) asm volatile("s_waitcnt lgkmcnt(" #n ")" ::: "memory")
; template <class Epi, class Sched, bool ALIGN_EPI = false, bool SP2 = false>
; __device__ __forceinline__ void gemm_phase(PG8_LAS unsigned char* lds, const Gemm g, const Sched& S, const Epi& E) {
;     ...
;             const bool last = (t == nt - 2);
;             const char* a1 = cA + (size_t)(t + 1) * kstep;
;             const char* a2 = last ? nA : cA + (size_t)(t + 2) * kstep; const char* b2 = last ? nB : cB + (size_t)(t + 2) * kstep;
;             const char* a3 = a2 + kstep; const char* b3 = b2 + kstep;
;             if (last && has_next) S.a_ready(nxt);
;             if constexpr (SP2) {
;             PG8_LDB(B0, 0, 0); PG8_LDB(B1, 0, 1); PG8_SCHED; PG8_LDA(At, 0, 0); PG8_STAGE(PG8_SA(1, 1), a1 + hA, voffA);
;             PG8_WAIT_V(8); PG8_WAIT_L(0); PG8_BAR; PG8_MMA(0, 0, At, B0); PG8_MMA(0, 1, At, B1); PG8_BAR; PG8_SCHED;
;     ...
;         for (int a = 0; a < 2; ++a)
; #pragma unroll
;             for (int b = 0; b < 2; ++b)
; #pragma unroll
;                 for (int m = 0; m < 4; ++m)
; #pragma unroll
;                     for (int n = 0; n < 2; ++n) acc[a][b][m][n] = (f32x4){0.f, 0.f, 0.f, 0.f};
.LBB0_962:
	s_ashr_i32 s41, s40, 31
	s_lshl_b64 s[42:43], s[40:41], 20
	s_add_u32 s42, s33, s42
	s_addc_u32 s43, s58, s43
	s_and_b64 s[44:45], s[8:9], exec
	s_cselect_b32 s41, s43, s49
	s_cselect_b32 s47, s42, s48
	s_ashr_i32 s39, s38, 31
	s_lshl_b64 s[44:45], s[38:39], 20
	s_add_u32 s44, s59, s44
	s_addc_u32 s45, s60, s45
	s_and_b64 s[52:53], s[8:9], exec
	s_cselect_b32 s39, s45, s51
	s_cselect_b32 s75, s44, s50
	s_add_u32 s48, s48, 0x80080
	s_addc_u32 s49, s49, 0
	s_add_u32 s76, s50, 0x100
	v_mov_b32_e32 v2, 0
	s_addc_u32 s77, s51, 0
	s_mov_b32 s78, -2
	s_waitcnt lgkmcnt(0)
	v_mov_b32_e32 v3, v2
	v_mov_b64_e32 v[4:5], 0
	v_mov_b64_e32 v[6:7], 0
	v_mov_b64_e32 v[8:9], 0
	v_mov_b64_e32 v[10:11], 0
	v_mov_b64_e32 v[12:13], 0
	v_mov_b64_e32 v[14:15], 0
	v_mov_b64_e32 v[16:17], 0
	v_mov_b64_e32 v[18:19], 0
	v_mov_b64_e32 v[20:21], 0
	v_mov_b64_e32 v[22:23], 0
	v_mov_b64_e32 v[24:25], 0
	v_mov_b64_e32 v[26:27], 0
	v_mov_b64_e32 v[28:29], 0
	v_mov_b64_e32 v[30:31], 0
	v_mov_b64_e32 v[32:33], 0
	v_mov_b64_e32 v[34:35], 0
	v_mov_b64_e32 v[36:37], 0
	v_mov_b64_e32 v[38:39], 0
	v_mov_b64_e32 v[40:41], 0
	v_mov_b64_e32 v[42:43], 0
	v_mov_b64_e32 v[44:45], 0
	v_mov_b64_e32 v[46:47], 0
	v_mov_b64_e32 v[48:49], 0
	v_mov_b64_e32 v[50:51], 0
	v_mov_b64_e32 v[52:53], 0
	v_mov_b64_e32 v[54:55], 0
	v_mov_b64_e32 v[56:57], 0
	v_mov_b64_e32 v[58:59], 0
	v_mov_b64_e32 v[60:61], 0
	v_mov_b64_e32 v[62:63], 0
	v_mov_b64_e32 v[64:65], 0
	v_mov_b64_e32 v[66:67], 0
	v_mov_b64_e32 v[68:69], 0
	v_mov_b64_e32 v[70:71], 0
	v_mov_b64_e32 v[72:73], 0
	v_mov_b64_e32 v[74:75], 0
	v_mov_b64_e32 v[76:77], 0
	v_mov_b64_e32 v[78:79], 0
	v_mov_b64_e32 v[80:81], 0
	v_mov_b64_e32 v[82:83], 0
	v_mov_b64_e32 v[84:85], 0
	v_mov_b64_e32 v[86:87], 0
	v_mov_b64_e32 v[88:89], 0
	v_mov_b64_e32 v[90:91], 0
	v_mov_b64_e32 v[92:93], 0
	v_mov_b64_e32 v[94:95], 0
	v_mov_b64_e32 v[96:97], 0
	v_mov_b64_e32 v[98:99], 0
	v_mov_b64_e32 v[100:101], 0
	v_mov_b64_e32 v[102:103], 0
	v_mov_b64_e32 v[104:105], 0
	v_mov_b64_e32 v[106:107], 0
	v_mov_b64_e32 v[108:109], 0
	v_mov_b64_e32 v[110:111], 0
	v_mov_b64_e32 v[112:113], 0
	v_mov_b64_e32 v[114:115], 0
	v_mov_b64_e32 v[116:117], 0
	v_mov_b64_e32 v[118:119], 0
	v_mov_b64_e32 v[120:121], 0
	v_mov_b64_e32 v[122:123], 0
	v_mov_b64_e32 v[124:125], 0
	v_mov_b64_e32 v[126:127], 0
	v_mov_b64_e32 v[128:129], 0
	s_add_u32 s88, s48, 0xfff80000
	s_addc_u32 s89, s49, -1
	s_cmp_eq_u32 s101, 0
	s_cbranch_scc0 .Lkt_3
.LBB0_963:
	ds_read_b128 v[130:133], v208
	ds_read_b128 v[134:137], v208 offset:1024
	ds_read_b128 v[138:141], v208 offset:2048
	ds_read_b128 v[142:145], v208 offset:3072
	ds_read_b128 v[146:149], v209
	ds_read_b128 v[150:153], v209 offset:1024
	ds_read_b128 v[154:157], v209 offset:2048
	ds_read_b128 v[158:161], v209 offset:3072
	s_add_u32 s18, s48, 0xfff80080
	s_addc_u32 s19, s49, -1
	s_cmp_eq_u32 s78, 28
	s_cselect_b32 s53, s41, s19
	s_cselect_b32 s52, s47, s18
	s_cselect_b32 s51, s39, s77
	s_cselect_b32 s50, s75, s76
	s_add_i32 m0, s62, 0xc000
	ds_read_b128 v[162:165], v210
	ds_read_b128 v[166:169], v210 offset:1024
	ds_read_b128 v[170:173], v210 offset:2048
	ds_read_b128 v[174:177], v210 offset:3072
	ds_read_b128 v[194:197], v210 offset:4096
	ds_read_b128 v[198:201], v210 offset:5120
	ds_read_b128 v[202:205], v210 offset:6144
	ds_read_b128 v[212:215], v210 offset:7168
	global_load_lds_dwordx4 v186, s[48:49]
	s_add_i32 m0, s62, 0xe000
	s_nop 0
	global_load_lds_dwordx4 v188, s[48:49]
	s_mov_b32 m0, s69
	s_nop 0
	global_load_lds_dwordx4 v178, s[88:89]
	s_mov_b32 m0, s70
	s_nop 0
	global_load_lds_dwordx4 v182, s[88:89]
	s_waitcnt lgkmcnt(0)
	s_barrier
	s_waitcnt lgkmcnt(0)
	v_mfma_f32_16x16x32_bf16 v[126:129], v[130:133], v[162:165], v[126:129]
	v_mfma_f32_16x16x32_bf16 v[122:125], v[138:141], v[162:165], v[122:125]
	v_mfma_f32_16x16x32_bf16 v[110:113], v[130:133], v[170:173], v[110:113]
	v_mfma_f32_16x16x32_bf16 v[106:109], v[138:141], v[170:173], v[106:109]
	v_mfma_f32_16x16x32_bf16 v[94:97], v[130:133], v[194:197], v[94:97]
	v_mfma_f32_16x16x32_bf16 v[90:93], v[138:141], v[194:197], v[90:93]
	v_mfma_f32_16x16x32_bf16 v[78:81], v[130:133], v[202:205], v[78:81]
	v_mfma_f32_16x16x32_bf16 v[74:77], v[138:141], v[202:205], v[74:77]
	v_mfma_f32_16x16x32_bf16 v[126:129], v[134:137], v[166:169], v[126:129]
	v_mfma_f32_16x16x32_bf16 v[122:125], v[142:145], v[166:169], v[122:125]
	v_mfma_f32_16x16x32_bf16 v[110:113], v[134:137], v[174:177], v[110:113]
	v_mfma_f32_16x16x32_bf16 v[106:109], v[142:145], v[174:177], v[106:109]
	v_mfma_f32_16x16x32_bf16 v[94:97], v[134:137], v[198:201], v[94:97]
	v_mfma_f32_16x16x32_bf16 v[90:93], v[142:145], v[198:201], v[90:93]
	v_mfma_f32_16x16x32_bf16 v[78:81], v[134:137], v[212:215], v[78:81]
	v_mfma_f32_16x16x32_bf16 v[74:77], v[142:145], v[212:215], v[74:77]
	v_mfma_f32_16x16x32_bf16 v[118:121], v[146:149], v[162:165], v[118:121]
	v_mfma_f32_16x16x32_bf16 v[114:117], v[154:157], v[162:165], v[114:117]
	v_mfma_f32_16x16x32_bf16 v[102:105], v[146:149], v[170:173], v[102:105]
	v_mfma_f32_16x16x32_bf16 v[98:101], v[154:157], v[170:173], v[98:101]
	v_mfma_f32_16x16x32_bf16 v[86:89], v[146:149], v[194:197], v[86:89]
	v_mfma_f32_16x16x32_bf16 v[82:85], v[154:157], v[194:197], v[82:85]
	v_mfma_f32_16x16x32_bf16 v[70:73], v[146:149], v[202:205], v[70:73]
	v_mfma_f32_16x16x32_bf16 v[66:69], v[154:157], v[202:205], v[66:69]
	v_mfma_f32_16x16x32_bf16 v[118:121], v[150:153], v[166:169], v[118:121]
	v_mfma_f32_16x16x32_bf16 v[114:117], v[158:161], v[166:169], v[114:117]
	v_mfma_f32_16x16x32_bf16 v[102:105], v[150:153], v[174:177], v[102:105]
	v_mfma_f32_16x16x32_bf16 v[98:101], v[158:161], v[174:177], v[98:101]
	v_mfma_f32_16x16x32_bf16 v[86:89], v[150:153], v[198:201], v[86:89]
	v_mfma_f32_16x16x32_bf16 v[82:85], v[158:161], v[198:201], v[82:85]
	v_mfma_f32_16x16x32_bf16 v[70:73], v[150:153], v[212:215], v[70:73]
	v_mfma_f32_16x16x32_bf16 v[66:69], v[158:161], v[212:215], v[66:69]
	s_waitcnt vmcnt(8)
	s_barrier
; #define PG8_STAGE(bufoff, gbase, voff) do { _Pragma("unroll") for (int _i = 0; _i < 2; ++_i) \
;         __builtin_amdgcn_global_load_lds((const unsigned*)((const char*)(gbase) + (voff)[_i]), (PG8_LAS unsigned*)(lds + (bufoff) + ldsw + _i * 8192), 16, 0, 0); } while (0)
; #define PG8_LDA(dst, b, h) do { _Pragma("unroll") for (int m = 0; m < 4; ++m) _Pragma("unroll") for (int k = 0; k < 2; ++k) dst[m][k] = *(const PG8_LAS bf16x8*)(lds + PG8_SA(b, h) + aoff + m * 2048 + k * 1024); } while (0)
; #define PG8_LDB(dst, b, h) do { _Pragma("unroll") for (int n = 0; n < 2; ++n) _Pragma("unroll") for (int k = 0; k < 2; ++k) dst[n][k] = *(const PG8_LAS bf16x8*)(lds + PG8_SB(b, h) + boff + n * 2048 + k * 1024); } while (0)
; #define PG8_MMA(ai, bj, At, Bt) do { __builtin_amdgcn_s_setprio(1); _Pragma("unroll") for (int m = 0; m < 4; ++m) _Pragma("unroll") for (int n = 0; n < 2; ++n) _Pragma("unroll") for (int k = 0; k < 2; ++k) \
;         acc[ai][bj][m][n] = __builtin_amdgcn_mfma_f32_16x16x32_bf16(Bt[n][k], At[m][k], acc[ai][bj][m][n], 0, 0, 0); __builtin_amdgcn_s_setprio(0); } while (0)
; #define PG8_WAIT_V(n) asm volatile("s_waitcnt vmcnt(" #n ")" ::: "memory")
; #define PG8_WAIT_L(n) asm volatile("s_waitcnt lgkmcnt(" #n ")" ::: "memory")
; #define PG8_BAR __builtin_amdgcn_s_barrier()
; #define PG8_SCHED __builtin_amdgcn_sched_barrier(0)
; template <class Epi, class Sched, bool ALIGN_EPI = false, bool SP2 = false>
; __device__ __forceinline__ void gemm_phase(PG8_LAS unsigned char* lds, const Gemm g, const Sched& S, const Epi& E) {
;     ...
;             PG8_LDA(At, 0, 1); PG8_STAGE(PG8_SB(0, 0), b2, voffB); PG8_STAGE(PG8_SB(0, 1), b2 + hB, voffB); PG8_STAGE(PG8_SA(0, 0), a2, voffA);
;             PG8_WAIT_V(8); PG8_WAIT_L(0); PG8_BAR; PG8_MMA(1, 0, At, B0); PG8_MMA(1, 1, At, B1); PG8_BAR; PG8_SCHED;
;             PG8_LDB(B0, 1, 0); PG8_LDB(B1, 1, 1); PG8_SCHED; PG8_LDA(At, 1, 0); PG8_STAGE(PG8_SA(0, 1), a2 + hA, voffA);
	s_add_i32 s18, s72, s61
	s_add_u32 s82, s50, s22
	s_addc_u32 s83, s51, s23
	s_mov_b32 m0, s18
	ds_read_b128 v[162:165], v210 offset:16384
	ds_read_b128 v[166:169], v210 offset:17408
	ds_read_b128 v[170:173], v210 offset:18432
	ds_read_b128 v[174:177], v210 offset:19456
	ds_read_b128 v[194:197], v210 offset:20480
	ds_read_b128 v[198:201], v210 offset:21504
	ds_read_b128 v[202:205], v210 offset:22528
	ds_read_b128 v[212:215], v210 offset:23552
	global_load_lds_dwordx4 v180, s[50:51]
	s_add_i32 m0, s18, 0x2000
	s_add_u32 s80, s50, 0x80000
	s_addc_u32 s81, s51, 0
	s_add_i32 s18, s73, s61
	global_load_lds_dwordx4 v184, s[50:51]
	s_mov_b32 m0, s18
	s_nop 0
	global_load_lds_dwordx4 v180, s[80:81]
	s_add_i32 m0, s18, 0x2000
	s_nop 0
	global_load_lds_dwordx4 v184, s[80:81]
	s_add_u32 s88, s52, s22
	s_addc_u32 s89, s53, s23
	s_waitcnt lgkmcnt(0)
	s_barrier
	s_waitcnt lgkmcnt(0)
	v_mfma_f32_16x16x32_bf16 v[62:65], v[130:133], v[162:165], v[62:65]
	v_mfma_f32_16x16x32_bf16 v[58:61], v[138:141], v[162:165], v[58:61]
	v_mfma_f32_16x16x32_bf16 v[46:49], v[130:133], v[170:173], v[46:49]
	v_mfma_f32_16x16x32_bf16 v[42:45], v[138:141], v[170:173], v[42:45]
	v_mfma_f32_16x16x32_bf16 v[30:33], v[130:133], v[194:197], v[30:33]
	v_mfma_f32_16x16x32_bf16 v[26:29], v[138:141], v[194:197], v[26:29]
	v_mfma_f32_16x16x32_bf16 v[14:17], v[130:133], v[202:205], v[14:17]
	v_mfma_f32_16x16x32_bf16 v[10:13], v[138:141], v[202:205], v[10:13]
	v_mfma_f32_16x16x32_bf16 v[62:65], v[134:137], v[166:169], v[62:65]
	v_mfma_f32_16x16x32_bf16 v[58:61], v[142:145], v[166:169], v[58:61]
	v_mfma_f32_16x16x32_bf16 v[46:49], v[134:137], v[174:177], v[46:49]
	v_mfma_f32_16x16x32_bf16 v[42:45], v[142:145], v[174:177], v[42:45]
	v_mfma_f32_16x16x32_bf16 v[30:33], v[134:137], v[198:201], v[30:33]
	v_mfma_f32_16x16x32_bf16 v[26:29], v[142:145], v[198:201], v[26:29]
	v_mfma_f32_16x16x32_bf16 v[14:17], v[134:137], v[212:215], v[14:17]
	v_mfma_f32_16x16x32_bf16 v[10:13], v[142:145], v[212:215], v[10:13]
	v_mfma_f32_16x16x32_bf16 v[54:57], v[146:149], v[162:165], v[54:57]
	v_mfma_f32_16x16x32_bf16 v[50:53], v[154:157], v[162:165], v[50:53]
	v_mfma_f32_16x16x32_bf16 v[38:41], v[146:149], v[170:173], v[38:41]
	v_mfma_f32_16x16x32_bf16 v[34:37], v[154:157], v[170:173], v[34:37]
	v_mfma_f32_16x16x32_bf16 v[22:25], v[146:149], v[194:197], v[22:25]
	v_mfma_f32_16x16x32_bf16 v[18:21], v[154:157], v[194:197], v[18:21]
	v_mfma_f32_16x16x32_bf16 v[6:9], v[146:149], v[202:205], v[6:9]
	v_mfma_f32_16x16x32_bf16 v[2:5], v[154:157], v[202:205], v[2:5]
	v_mfma_f32_16x16x32_bf16 v[54:57], v[150:153], v[166:169], v[54:57]
	v_mfma_f32_16x16x32_bf16 v[50:53], v[158:161], v[166:169], v[50:53]
	v_mfma_f32_16x16x32_bf16 v[38:41], v[150:153], v[174:177], v[38:41]
	v_mfma_f32_16x16x32_bf16 v[34:37], v[158:161], v[174:177], v[34:37]
	v_mfma_f32_16x16x32_bf16 v[22:25], v[150:153], v[198:201], v[22:25]
	v_mfma_f32_16x16x32_bf16 v[18:21], v[158:161], v[198:201], v[18:21]
	v_mfma_f32_16x16x32_bf16 v[6:9], v[150:153], v[212:215], v[6:9]
	v_mfma_f32_16x16x32_bf16 v[2:5], v[158:161], v[212:215], v[2:5]
	s_waitcnt vmcnt(4)
	s_barrier
	s_add_i32 s18, 0, 0x18000
	s_add_i32 s19, 0, 0x1c000
	v_add_u32_e32 v142, s18, v206
	v_add_u32_e32 v158, s19, v206
	ds_read_b128 v[130:133], v142
	ds_read_b128 v[134:137], v142 offset:1024
	ds_read_b128 v[138:141], v142 offset:2048
	ds_read_b128 v[142:145], v142 offset:3072
	ds_read_b128 v[146:149], v158
	ds_read_b128 v[150:153], v158 offset:1024
	ds_read_b128 v[154:157], v158 offset:2048
	ds_read_b128 v[158:161], v158 offset:3072
	ds_read_b128 v[162:165], v210 offset:32768
	ds_read_b128 v[166:169], v210 offset:33792
	ds_read_b128 v[170:173], v210 offset:34816
	ds_read_b128 v[174:177], v210 offset:35840
	ds_read_b128 v[194:197], v210 offset:36864
	ds_read_b128 v[198:201], v210 offset:37888
	ds_read_b128 v[202:205], v210 offset:38912
	ds_read_b128 v[212:215], v210 offset:39936
	s_mov_b32 m0, s62
	s_nop 0
	global_load_lds_dwordx4 v178, s[52:53]
	s_mov_b32 m0, s63
	s_nop 0
	global_load_lds_dwordx4 v182, s[52:53]
	s_add_u32 s52, s52, 0x80000
	s_addc_u32 s53, s53, 0
	s_mov_b32 m0, s64
	s_nop 0
	global_load_lds_dwordx4 v178, s[52:53]
	s_mov_b32 m0, s65
	s_nop 0
	global_load_lds_dwordx4 v182, s[52:53]
	s_waitcnt lgkmcnt(0)
	s_barrier
; #define PG8_STAGE(bufoff, gbase, voff) do { _Pragma("unroll") for (int _i = 0; _i < 2; ++_i) \
;         __builtin_amdgcn_global_load_lds((const unsigned*)((const char*)(gbase) + (voff)[_i]), (PG8_LAS unsigned*)(lds + (bufoff) + ldsw + _i * 8192), 16, 0, 0); } while (0)
; #define PG8_LDA(dst, b, h) do { _Pragma("unroll") for (int m = 0; m < 4; ++m) _Pragma("unroll") for (int k = 0; k < 2; ++k) dst[m][k] = *(const PG8_LAS bf16x8*)(lds + PG8_SA(b, h) + aoff + m * 2048 + k * 1024); } while (0)
; #define PG8_MMA(ai, bj, At, Bt) do { __builtin_amdgcn_s_setprio(1); _Pragma("unroll") for (int m = 0; m < 4; ++m) _Pragma("unroll") for (int n = 0; n < 2; ++n) _Pragma("unroll") for (int k = 0; k < 2; ++k) \
;         acc[ai][bj][m][n] = __builtin_amdgcn_mfma_f32_16x16x32_bf16(Bt[n][k], At[m][k], acc[ai][bj][m][n], 0, 0, 0); __builtin_amdgcn_s_setprio(0); } while (0)
; #define PG8_WAIT_V(n) asm volatile("s_waitcnt vmcnt(" #n ")" ::: "memory")
; #define PG8_WAIT_L(n) asm volatile("s_waitcnt lgkmcnt(" #n ")" ::: "memory")
; #define PG8_BAR __builtin_amdgcn_s_barrier()
; #define PG8_SCHED __builtin_amdgcn_sched_barrier(0)
; template <class Epi, class Sched, bool ALIGN_EPI = false, bool SP2 = false>
; __device__ __forceinline__ void gemm_phase(PG8_LAS unsigned char* lds, const Gemm g, const Sched& S, const Epi& E) {
;     ...
;             PG8_WAIT_V(8); PG8_WAIT_L(0); PG8_BAR; PG8_MMA(0, 0, At, B0); PG8_MMA(0, 1, At, B1); PG8_BAR; PG8_SCHED;
;             PG8_LDA(At, 1, 1); PG8_STAGE(PG8_SB(1, 0), b3, voffB); PG8_STAGE(PG8_SB(1, 1), b3 + hB, voffB); PG8_STAGE(PG8_SA(1, 0), a3, voffA);
;             PG8_WAIT_V(8); PG8_WAIT_L(0); PG8_BAR; PG8_MMA(1, 0, At, B0); PG8_MMA(1, 1, At, B1); PG8_BAR; PG8_SCHED;
	s_waitcnt lgkmcnt(0)
	v_mfma_f32_16x16x32_bf16 v[126:129], v[130:133], v[162:165], v[126:129]
	v_mfma_f32_16x16x32_bf16 v[122:125], v[138:141], v[162:165], v[122:125]
	v_mfma_f32_16x16x32_bf16 v[110:113], v[130:133], v[170:173], v[110:113]
	v_mfma_f32_16x16x32_bf16 v[106:109], v[138:141], v[170:173], v[106:109]
	v_mfma_f32_16x16x32_bf16 v[94:97], v[130:133], v[194:197], v[94:97]
	v_mfma_f32_16x16x32_bf16 v[90:93], v[138:141], v[194:197], v[90:93]
	v_mfma_f32_16x16x32_bf16 v[78:81], v[130:133], v[202:205], v[78:81]
	v_mfma_f32_16x16x32_bf16 v[74:77], v[138:141], v[202:205], v[74:77]
	v_mfma_f32_16x16x32_bf16 v[126:129], v[134:137], v[166:169], v[126:129]
	v_mfma_f32_16x16x32_bf16 v[122:125], v[142:145], v[166:169], v[122:125]
	v_mfma_f32_16x16x32_bf16 v[110:113], v[134:137], v[174:177], v[110:113]
	v_mfma_f32_16x16x32_bf16 v[106:109], v[142:145], v[174:177], v[106:109]
	v_mfma_f32_16x16x32_bf16 v[94:97], v[134:137], v[198:201], v[94:97]
	v_mfma_f32_16x16x32_bf16 v[90:93], v[142:145], v[198:201], v[90:93]
	v_mfma_f32_16x16x32_bf16 v[78:81], v[134:137], v[212:215], v[78:81]
	v_mfma_f32_16x16x32_bf16 v[74:77], v[142:145], v[212:215], v[74:77]
	v_mfma_f32_16x16x32_bf16 v[118:121], v[146:149], v[162:165], v[118:121]
	v_mfma_f32_16x16x32_bf16 v[114:117], v[154:157], v[162:165], v[114:117]
	v_mfma_f32_16x16x32_bf16 v[102:105], v[146:149], v[170:173], v[102:105]
	v_mfma_f32_16x16x32_bf16 v[98:101], v[154:157], v[170:173], v[98:101]
	v_mfma_f32_16x16x32_bf16 v[86:89], v[146:149], v[194:197], v[86:89]
	v_mfma_f32_16x16x32_bf16 v[82:85], v[154:157], v[194:197], v[82:85]
	v_mfma_f32_16x16x32_bf16 v[70:73], v[146:149], v[202:205], v[70:73]
	v_mfma_f32_16x16x32_bf16 v[66:69], v[154:157], v[202:205], v[66:69]
	v_mfma_f32_16x16x32_bf16 v[118:121], v[150:153], v[166:169], v[118:121]
	v_mfma_f32_16x16x32_bf16 v[114:117], v[158:161], v[166:169], v[114:117]
	v_mfma_f32_16x16x32_bf16 v[102:105], v[150:153], v[174:177], v[102:105]
	v_mfma_f32_16x16x32_bf16 v[98:101], v[158:161], v[174:177], v[98:101]
	v_mfma_f32_16x16x32_bf16 v[86:89], v[150:153], v[198:201], v[86:89]
	v_mfma_f32_16x16x32_bf16 v[82:85], v[158:161], v[198:201], v[82:85]
	v_mfma_f32_16x16x32_bf16 v[70:73], v[150:153], v[212:215], v[70:73]
	v_mfma_f32_16x16x32_bf16 v[66:69], v[158:161], v[212:215], v[66:69]
	s_barrier
	s_add_i32 s18, s18, s61
	s_mov_b32 m0, s18
	ds_read_b128 v[162:165], v210 offset:49152
	ds_read_b128 v[166:169], v210 offset:50176
	ds_read_b128 v[170:173], v210 offset:51200
	ds_read_b128 v[174:177], v210 offset:52224
	ds_read_b128 v[194:197], v210 offset:53248
	ds_read_b128 v[198:201], v210 offset:54272
	ds_read_b128 v[202:205], v210 offset:55296
	ds_read_b128 v[212:215], v210 offset:56320
	global_load_lds_dwordx4 v180, s[82:83]
	s_add_i32 m0, s18, 0x2000
	s_add_u32 s50, s50, 0x80080
	s_addc_u32 s51, s51, 0
	s_add_i32 s18, s19, s61
	global_load_lds_dwordx4 v184, s[82:83]
	s_mov_b32 m0, s18
	s_nop 0
	global_load_lds_dwordx4 v180, s[50:51]
	s_add_i32 m0, s18, 0x2000
	s_nop 0
	global_load_lds_dwordx4 v184, s[50:51]
	s_waitcnt lgkmcnt(0)
	s_barrier
	s_waitcnt lgkmcnt(0)
	v_mfma_f32_16x16x32_bf16 v[62:65], v[130:133], v[162:165], v[62:65]
	v_mfma_f32_16x16x32_bf16 v[58:61], v[138:141], v[162:165], v[58:61]
	v_mfma_f32_16x16x32_bf16 v[46:49], v[130:133], v[170:173], v[46:49]
	v_mfma_f32_16x16x32_bf16 v[42:45], v[138:141], v[170:173], v[42:45]
	v_mfma_f32_16x16x32_bf16 v[30:33], v[130:133], v[194:197], v[30:33]
	v_mfma_f32_16x16x32_bf16 v[26:29], v[138:141], v[194:197], v[26:29]
	v_mfma_f32_16x16x32_bf16 v[14:17], v[130:133], v[202:205], v[14:17]
	v_mfma_f32_16x16x32_bf16 v[10:13], v[138:141], v[202:205], v[10:13]
	v_mfma_f32_16x16x32_bf16 v[62:65], v[134:137], v[166:169], v[62:65]
	v_mfma_f32_16x16x32_bf16 v[58:61], v[142:145], v[166:169], v[58:61]
	v_mfma_f32_16x16x32_bf16 v[46:49], v[134:137], v[174:177], v[46:49]
	v_mfma_f32_16x16x32_bf16 v[42:45], v[142:145], v[174:177], v[42:45]
	v_mfma_f32_16x16x32_bf16 v[30:33], v[134:137], v[198:201], v[30:33]
	v_mfma_f32_16x16x32_bf16 v[26:29], v[142:145], v[198:201], v[26:29]
	v_mfma_f32_16x16x32_bf16 v[14:17], v[134:137], v[212:215], v[14:17]
	v_mfma_f32_16x16x32_bf16 v[10:13], v[142:145], v[212:215], v[10:13]
	v_mfma_f32_16x16x32_bf16 v[54:57], v[146:149], v[162:165], v[54:57]
	v_mfma_f32_16x16x32_bf16 v[50:53], v[154:157], v[162:165], v[50:53]
	v_mfma_f32_16x16x32_bf16 v[38:41], v[146:149], v[170:173], v[38:41]
	v_mfma_f32_16x16x32_bf16 v[34:37], v[154:157], v[170:173], v[34:37]
	v_mfma_f32_16x16x32_bf16 v[22:25], v[146:149], v[194:197], v[22:25]
	v_mfma_f32_16x16x32_bf16 v[18:21], v[154:157], v[194:197], v[18:21]
	v_mfma_f32_16x16x32_bf16 v[6:9], v[146:149], v[202:205], v[6:9]
	v_mfma_f32_16x16x32_bf16 v[2:5], v[154:157], v[202:205], v[2:5]
	v_mfma_f32_16x16x32_bf16 v[54:57], v[150:153], v[166:169], v[54:57]
	v_mfma_f32_16x16x32_bf16 v[50:53], v[158:161], v[166:169], v[50:53]
	v_mfma_f32_16x16x32_bf16 v[38:41], v[150:153], v[174:177], v[38:41]
	v_mfma_f32_16x16x32_bf16 v[34:37], v[158:161], v[174:177], v[34:37]
	v_mfma_f32_16x16x32_bf16 v[22:25], v[150:153], v[198:201], v[22:25]
	v_mfma_f32_16x16x32_bf16 v[18:21], v[158:161], v[198:201], v[18:21]
	v_mfma_f32_16x16x32_bf16 v[6:9], v[150:153], v[212:215], v[6:9]
	v_mfma_f32_16x16x32_bf16 v[2:5], v[158:161], v[212:215], v[2:5]
	s_waitcnt vmcnt(6)
	s_barrier
	s_add_i32 s78, s78, 2
	s_add_u32 s48, s48, 0x100
	s_addc_u32 s49, s49, 0
	s_add_u32 s76, s76, 0x100
	s_addc_u32 s77, s77, 0
	s_cmp_gt_u32 s78, 29
	s_cbranch_scc0 .LBB0_963
	s_branch .Lkafter_3

; #define PG8_BAR __builtin_amdgcn_s_barrier()
; template <class Epi, class Sched, bool ALIGN_EPI = false, bool SP2 = false>
; __device__ __forceinline__ void gemm_phase(PG8_LAS unsigned char* lds, const Gemm g, const Sched& S, const Epi& E) {
;     ...
;         if constexpr (ALIGN_EPI) { if (wr == 0) PG8_BAR; }
.Lkafter_3:
	s_and_b64 vcc, exec, s[24:25]
	s_cbranch_vccz .LBB0_966
	s_barrier

; #define PG8_STAGE(bufoff, gbase, voff) do { _Pragma("unroll") for (int _i = 0; _i < 2; ++_i) \
;         __builtin_amdgcn_global_load_lds((const unsigned*)((const char*)(gbase) + (voff)[_i]), (PG8_LAS unsigned*)(lds + (bufoff) + ldsw + _i * 8192), 16, 0, 0); } while (0)
; #define PG8_WAIT_V(n) asm volatile("s_waitcnt vmcnt(" #n ")" ::: "memory")
; #define PG8_BAR __builtin_amdgcn_s_barrier()
; template <class Epi, class Sched, bool ALIGN_EPI = false, bool SP2 = false>
; __device__ __forceinline__ void gemm_phase(PG8_LAS unsigned char* lds, const Gemm g, const Sched& S, const Epi& E) {
;     ...
;     const int tid = tid_o, wid = __builtin_amdgcn_readfirstlane(tid >> 6), lane = tid & 63, wr = wid >> 2, wc = wid & 3, fr = lane & 15, fq = lane >> 4;
;     const int K = g.K, nt = K / BK;
;     unsigned voffA[2], voffB[2];
; #pragma unroll
;     for (int i = 0; i < 2; ++i) { int R, C; stage_rc(tid * 16 + i * 8192, R, C); const int Rb = Epi::PERM ? ((R & ~31) + perm32(R & 31)) : R;
;         voffA[i] = (unsigned)(R * g.lda + C) * 2u; voffB[i] = (unsigned)(Rb * g.ldb + C) * 2u; }
;     const size_t kstep = (size_t)(BK * 2);
;     const size_t hA = (size_t)HALF * g.lda * 2, hB = (size_t)HALF * g.ldb * 2;
;     const size_t tA = 2 * hA, tB = 2 * hB, pnA = (size_t)g.a_pn_off * 2;
;     const unsigned ldsw = (unsigned)wid * 1024u;
;     const int aoff = lds_byte(wr * 64 + fr, fq * 8), boff = lds_byte(wc * 32 + fr, fq * 8);
;     ...
;         PG8_STAGE(PG8_SB(1, 0), cB + kstep, voffB); PG8_STAGE(PG8_SA(1, 0), cA + kstep, voffA); PG8_STAGE(PG8_SB(1, 1), cB + hB + kstep, voffB);
;         PG8_WAIT_V(6); PG8_BAR;
.LBB0_1042:
	s_add_u32 s16, s6, 0x5800000
	s_addc_u32 s17, s7, 0
	s_lshl_b32 s18, s20, 5
	s_mov_b64 s[20:21], 0x80
	s_and_b32 s18, s18, 0x60
	s_add_i32 m0, s51, 0x18000
	v_lshl_add_u64 v[8:9], v[8:9], 0, s[20:21]
	s_lshl_b32 s1, s24, 13
	s_lshl_b32 s19, s18, 7
	s_waitcnt vmcnt(2)
	s_barrier
	global_load_lds_dwordx4 v[8:9], off
	v_lshl_add_u64 v[6:7], v[6:7], 0, s[20:21]
	s_add_i32 m0, s51, 0x1a000
	s_add_i32 s60, s51, 0x8000
	s_add_i32 s61, s51, 0xa000
	global_load_lds_dwordx4 v[6:7], off
	v_lshl_add_u64 v[2:3], v[2:3], 0, s[20:21]
	s_mov_b32 m0, s60
	s_add_u32 s36, s42, 0x80080
	global_load_lds_dwordx4 v[2:3], off
	v_lshl_add_u64 v[2:3], v[4:5], 0, s[20:21]
	s_mov_b32 m0, s61
	s_addc_u32 s37, s43, 0
	global_load_lds_dwordx4 v[2:3], off
	s_add_i32 m0, s51, 0x1c000
	v_lshl_add_u64 v[2:3], s[36:37], 0, v[134:135]
	global_load_lds_dwordx4 v[2:3], off
	v_lshl_add_u64 v[2:3], s[36:37], 0, v[130:131]
	s_add_i32 m0, s51, 0x1e000
	s_cmpk_lt_u32 s23, 0x100
	global_load_lds_dwordx4 v[2:3], off
	v_lshrrev_b32_e32 v3, 1, v12
	v_and_b32_e32 v4, 24, v3
	v_and_b32_e32 v2, 15, v12
	v_lshlrev_b32_e32 v3, 1, v4
	v_lshl_or_b32 v1, s24, 6, v2
	v_lshl_or_b32 v2, v2, 6, v3
	v_lshlrev_b32_e32 v3, 2, v12
	v_and_b32_e32 v3, 32, v3
	v_bitop3_b32 v5, v2, s1, v3 bitop3:0xde
	v_bitop3_b32 v165, v2, s19, v3 bitop3:0xde
	v_lshlrev_b32_e32 v2, 2, v4
	v_mov_b32_e32 v3, v135
	v_lshl_add_u64 v[2:3], s[6:7], 0, v[2:3]
	s_mov_b64 s[6:7], 0x1e00000
	v_lshl_add_u64 v[138:139], v[2:3], 0, s[6:7]
	v_lshlrev_b32_e32 v2, 15, v15
	v_and_b32_e32 v2, 0xffff0000, v2
	v_lshl_add_u32 v2, v14, 12, v2
	v_and_b32_e32 v3, 1, v15
	v_lshl_or_b32 v2, v3, 6, v2
	v_lshl_add_u32 v140, v16, 1, v2
	v_lshlrev_b32_e32 v2, 15, v10
	v_and_b32_e32 v2, 0xffff0000, v2
	s_waitcnt vmcnt(6)
	v_lshl_add_u32 v2, v11, 12, v2
	v_and_b32_e32 v3, 1, v10
	s_sext_i32_i16 s67, s22
	s_cselect_b64 s[22:23], -1, 0
	v_lshl_or_b32 v2, v3, 6, v2
	s_add_i32 s63, 0, 0x10000
	s_add_i32 s64, 0, 0x14000
	s_waitcnt lgkmcnt(0)
	s_ashr_i32 s62, s58, 31
	v_or_b32_e32 v167, s18, v4
	v_mov_b32_e32 v141, v135
	v_lshl_add_u32 v142, v13, 1, v2
	v_mov_b32_e32 v143, v135
	v_mov_b64_e32 v[144:145], 0xb00
	v_mov_b64_e32 v[146:147], 0xaff
	v_add_u32_e32 v169, s63, v165
	v_add_u32_e32 v171, s64, v165
	v_add_u32_e32 v173, 0, v5
	v_mbcnt_hi_u32_b32 v175, -1, v222
	v_mov_b32_e32 v177, 0x358637bd
	s_mov_b32 s65, 0xf800000
	v_mov_b32_e32 v179, 0x260
	s_movk_i32 s66, 0x2c00
	s_barrier
	s_mov_b32 s98, -1
	v_readfirstlane_b32 s101, v0
	s_nop 3
	s_lshr_b32 s101, s101, 8
	s_branch .LBB0_1045

; #define PG8_STAGE(bufoff, gbase, voff) do { _Pragma("unroll") for (int _i = 0; _i < 2; ++_i) \
;         __builtin_amdgcn_global_load_lds((const unsigned*)((const char*)(gbase) + (voff)[_i]), (PG8_LAS unsigned*)(lds + (bufoff) + ldsw + _i * 8192), 16, 0, 0); } while (0)
; #define PG8_LDA(dst, b, h) do { _Pragma("unroll") for (int m = 0; m < 4; ++m) _Pragma("unroll") for (int k = 0; k < 2; ++k) dst[m][k] = *(const PG8_LAS bf16x8*)(lds + PG8_SA(b, h) + aoff + m * 2048 + k * 1024); } while (0)
; #define PG8_LDB(dst, b, h) do { _Pragma("unroll") for (int n = 0; n < 2; ++n) _Pragma("unroll") for (int k = 0; k < 2; ++k) dst[n][k] = *(const PG8_LAS bf16x8*)(lds + PG8_SB(b, h) + boff + n * 2048 + k * 1024); } while (0)
; #define PG8_MMA(ai, bj, At, Bt) do { __builtin_amdgcn_s_setprio(1); _Pragma("unroll") for (int m = 0; m < 4; ++m) _Pragma("unroll") for (int n = 0; n < 2; ++n) _Pragma("unroll") for (int k = 0; k < 2; ++k) \
;         acc[ai][bj][m][n] = __builtin_amdgcn_mfma_f32_16x16x32_bf16(Bt[n][k], At[m][k], acc[ai][bj][m][n], 0, 0, 0); __builtin_amdgcn_s_setprio(0); } while (0)
; #define PG8_WAIT_V(n) asm volatile("s_waitcnt vmcnt(" #n ")" ::: "memory")
; #define PG8_WAIT_L(n) asm volatile("s_waitcnt lgkmcnt(" #n ")" ::: "memory")
; template <class Epi, class Sched, bool ALIGN_EPI = false, bool SP2 = false>
; __device__ __forceinline__ void gemm_phase(PG8_LAS unsigned char* lds, const Gemm g, const Sched& S, const Epi& E) {
;     ...
;             const bool last = (t == nt - 2);
;             const char* a1 = cA + (size_t)(t + 1) * kstep;
;             const char* a2 = last ? nA : cA + (size_t)(t + 2) * kstep; const char* b2 = last ? nB : cB + (size_t)(t + 2) * kstep;
;             const char* a3 = a2 + kstep; const char* b3 = b2 + kstep;
;             if (last && has_next) S.a_ready(nxt);
;             if constexpr (SP2) {
;             PG8_LDB(B0, 0, 0); PG8_LDB(B1, 0, 1); PG8_SCHED; PG8_LDA(At, 0, 0); PG8_STAGE(PG8_SA(1, 1), a1 + hA, voffA);
;             PG8_WAIT_V(8); PG8_WAIT_L(0); PG8_BAR; PG8_MMA(0, 0, At, B0); PG8_MMA(0, 1, At, B1); PG8_BAR; PG8_SCHED;
;     ...
;         for (int a = 0; a < 2; ++a)
; #pragma unroll
;             for (int b = 0; b < 2; ++b)
; #pragma unroll
;                 for (int m = 0; m < 4; ++m)
; #pragma unroll
;                     for (int n = 0; n < 2; ++n) acc[a][b][m][n] = (f32x4){0.f, 0.f, 0.f, 0.f};
.LBB0_1047:
	s_ashr_i32 s37, s36, 31
	s_lshl_b64 s[38:39], s[36:37], 20
	s_add_u32 s38, s33, s38
	s_addc_u32 s39, s46, s39
	s_and_b64 s[40:41], s[6:7], exec
	s_cselect_b32 s1, s39, s9
	s_cselect_b32 s37, s38, s8
	s_ashr_i32 s25, s24, 31
	s_lshl_b64 s[40:41], s[24:25], 20
	s_add_u32 s40, s47, s40
	s_addc_u32 s41, s48, s41
	s_and_b64 s[44:45], s[6:7], exec
	s_cselect_b32 s25, s41, s43
	s_cselect_b32 s69, s40, s42
	s_add_u32 s8, s8, 0x80080
	s_addc_u32 s9, s9, 0
	s_add_u32 s70, s42, 0x100
	v_mov_b32_e32 v2, 0
	s_addc_u32 s71, s43, 0
	s_mov_b32 s72, -2
	v_mov_b32_e32 v3, v2
	v_mov_b64_e32 v[4:5], 0
	v_mov_b64_e32 v[6:7], 0
	v_mov_b64_e32 v[8:9], 0
	v_mov_b64_e32 v[10:11], 0
	v_mov_b64_e32 v[12:13], 0
	v_mov_b64_e32 v[14:15], 0
	v_mov_b64_e32 v[16:17], 0
	v_mov_b64_e32 v[18:19], 0
	v_mov_b64_e32 v[20:21], 0
	v_mov_b64_e32 v[22:23], 0
	v_mov_b64_e32 v[24:25], 0
	v_mov_b64_e32 v[26:27], 0
	v_mov_b64_e32 v[28:29], 0
	v_mov_b64_e32 v[30:31], 0
	v_mov_b64_e32 v[32:33], 0
	v_mov_b64_e32 v[34:35], 0
	v_mov_b64_e32 v[36:37], 0
	v_mov_b64_e32 v[38:39], 0
	v_mov_b64_e32 v[40:41], 0
	v_mov_b64_e32 v[42:43], 0
	v_mov_b64_e32 v[44:45], 0
	v_mov_b64_e32 v[46:47], 0
	v_mov_b64_e32 v[48:49], 0
	v_mov_b64_e32 v[50:51], 0
	v_mov_b64_e32 v[52:53], 0
	v_mov_b64_e32 v[54:55], 0
	v_mov_b64_e32 v[56:57], 0
	v_mov_b64_e32 v[58:59], 0
	v_mov_b64_e32 v[60:61], 0
	v_mov_b64_e32 v[62:63], 0
	v_mov_b64_e32 v[64:65], 0
	v_mov_b64_e32 v[66:67], 0
	v_mov_b64_e32 v[68:69], 0
	v_mov_b64_e32 v[70:71], 0
	v_mov_b64_e32 v[72:73], 0
	v_mov_b64_e32 v[74:75], 0
	v_mov_b64_e32 v[76:77], 0
	v_mov_b64_e32 v[78:79], 0
	v_mov_b64_e32 v[80:81], 0
	v_mov_b64_e32 v[82:83], 0
	v_mov_b64_e32 v[84:85], 0
	v_mov_b64_e32 v[86:87], 0
	v_mov_b64_e32 v[88:89], 0
	v_mov_b64_e32 v[90:91], 0
	v_mov_b64_e32 v[92:93], 0
	v_mov_b64_e32 v[94:95], 0
	v_mov_b64_e32 v[96:97], 0
	v_mov_b64_e32 v[98:99], 0
	v_mov_b64_e32 v[100:101], 0
	v_mov_b64_e32 v[102:103], 0
	v_mov_b64_e32 v[104:105], 0
	v_mov_b64_e32 v[106:107], 0
	v_mov_b64_e32 v[108:109], 0
	v_mov_b64_e32 v[110:111], 0
	v_mov_b64_e32 v[112:113], 0
	v_mov_b64_e32 v[114:115], 0
	v_mov_b64_e32 v[116:117], 0
	v_mov_b64_e32 v[118:119], 0
	v_mov_b64_e32 v[120:121], 0
	v_mov_b64_e32 v[122:123], 0
	v_mov_b64_e32 v[124:125], 0
	v_mov_b64_e32 v[126:127], 0
	v_mov_b64_e32 v[128:129], 0
	s_add_u32 s78, s8, 0xfff80000
	s_addc_u32 s79, s9, -1
	s_cmp_eq_u32 s101, 0
	s_cbranch_scc0 .Lkt_4
.LBB0_1048:
	ds_read_b128 v[148:151], v169
	ds_read_b128 v[152:155], v169 offset:1024
	ds_read_b128 v[156:159], v169 offset:2048
	ds_read_b128 v[160:163], v169 offset:3072
	ds_read_b128 v[180:183], v171
	ds_read_b128 v[184:187], v171 offset:1024
	ds_read_b128 v[188:191], v171 offset:2048
	ds_read_b128 v[192:195], v171 offset:3072
	s_add_u32 s18, s8, 0xfff80080
	s_addc_u32 s19, s9, -1
	s_cmp_eq_u32 s72, 28
	s_cselect_b32 s45, s1, s19
	s_cselect_b32 s44, s37, s18
	s_cselect_b32 s43, s25, s71
	s_cselect_b32 s42, s69, s70
	s_add_i32 m0, s51, 0xc000
	ds_read_b128 v[196:199], v173
	ds_read_b128 v[200:203], v173 offset:1024
	ds_read_b128 v[204:207], v173 offset:2048
	ds_read_b128 v[208:211], v173 offset:3072
	ds_read_b128 v[212:215], v173 offset:4096
	ds_read_b128 v[216:219], v173 offset:5120
	ds_read_b128 v[224:227], v173 offset:6144
	ds_read_b128 v[228:231], v173 offset:7168
	global_load_lds_dwordx4 v140, s[8:9]
	s_add_i32 m0, s51, 0xe000
	s_nop 0
	global_load_lds_dwordx4 v142, s[8:9]
	s_mov_b32 m0, s60
	s_nop 0
	global_load_lds_dwordx4 v136, s[78:79]
	s_mov_b32 m0, s61
	s_nop 0
	global_load_lds_dwordx4 v132, s[78:79]
	s_waitcnt lgkmcnt(0)
	s_barrier
	s_waitcnt lgkmcnt(0)
	v_mfma_f32_16x16x32_bf16 v[126:129], v[148:151], v[196:199], v[126:129]
	v_mfma_f32_16x16x32_bf16 v[122:125], v[156:159], v[196:199], v[122:125]
	v_mfma_f32_16x16x32_bf16 v[110:113], v[148:151], v[204:207], v[110:113]
	v_mfma_f32_16x16x32_bf16 v[106:109], v[156:159], v[204:207], v[106:109]
	v_mfma_f32_16x16x32_bf16 v[94:97], v[148:151], v[212:215], v[94:97]
	v_mfma_f32_16x16x32_bf16 v[90:93], v[156:159], v[212:215], v[90:93]
	v_mfma_f32_16x16x32_bf16 v[78:81], v[148:151], v[224:227], v[78:81]
	v_mfma_f32_16x16x32_bf16 v[74:77], v[156:159], v[224:227], v[74:77]
	v_mfma_f32_16x16x32_bf16 v[126:129], v[152:155], v[200:203], v[126:129]
	v_mfma_f32_16x16x32_bf16 v[122:125], v[160:163], v[200:203], v[122:125]
	v_mfma_f32_16x16x32_bf16 v[110:113], v[152:155], v[208:211], v[110:113]
	v_mfma_f32_16x16x32_bf16 v[106:109], v[160:163], v[208:211], v[106:109]
	v_mfma_f32_16x16x32_bf16 v[94:97], v[152:155], v[216:219], v[94:97]
	v_mfma_f32_16x16x32_bf16 v[90:93], v[160:163], v[216:219], v[90:93]
	v_mfma_f32_16x16x32_bf16 v[78:81], v[152:155], v[228:231], v[78:81]
	v_mfma_f32_16x16x32_bf16 v[74:77], v[160:163], v[228:231], v[74:77]
	v_mfma_f32_16x16x32_bf16 v[118:121], v[180:183], v[196:199], v[118:121]
	v_mfma_f32_16x16x32_bf16 v[114:117], v[188:191], v[196:199], v[114:117]
	v_mfma_f32_16x16x32_bf16 v[102:105], v[180:183], v[204:207], v[102:105]
	v_mfma_f32_16x16x32_bf16 v[98:101], v[188:191], v[204:207], v[98:101]
	v_mfma_f32_16x16x32_bf16 v[86:89], v[180:183], v[212:215], v[86:89]
	v_mfma_f32_16x16x32_bf16 v[82:85], v[188:191], v[212:215], v[82:85]
	v_mfma_f32_16x16x32_bf16 v[70:73], v[180:183], v[224:227], v[70:73]
	v_mfma_f32_16x16x32_bf16 v[66:69], v[188:191], v[224:227], v[66:69]
	v_mfma_f32_16x16x32_bf16 v[118:121], v[184:187], v[200:203], v[118:121]
	v_mfma_f32_16x16x32_bf16 v[114:117], v[192:195], v[200:203], v[114:117]
	v_mfma_f32_16x16x32_bf16 v[102:105], v[184:187], v[208:211], v[102:105]
	v_mfma_f32_16x16x32_bf16 v[98:101], v[192:195], v[208:211], v[98:101]
	v_mfma_f32_16x16x32_bf16 v[86:89], v[184:187], v[216:219], v[86:89]
	v_mfma_f32_16x16x32_bf16 v[82:85], v[192:195], v[216:219], v[82:85]
	v_mfma_f32_16x16x32_bf16 v[70:73], v[184:187], v[228:231], v[70:73]
	v_mfma_f32_16x16x32_bf16 v[66:69], v[192:195], v[228:231], v[66:69]
	s_waitcnt vmcnt(8)
	s_barrier
; #define PG8_STAGE(bufoff, gbase, voff) do { _Pragma("unroll") for (int _i = 0; _i < 2; ++_i) \
;         __builtin_amdgcn_global_load_lds((const unsigned*)((const char*)(gbase) + (voff)[_i]), (PG8_LAS unsigned*)(lds + (bufoff) + ldsw + _i * 8192), 16, 0, 0); } while (0)
; #define PG8_LDA(dst, b, h) do { _Pragma("unroll") for (int m = 0; m < 4; ++m) _Pragma("unroll") for (int k = 0; k < 2; ++k) dst[m][k] = *(const PG8_LAS bf16x8*)(lds + PG8_SA(b, h) + aoff + m * 2048 + k * 1024); } while (0)
; #define PG8_LDB(dst, b, h) do { _Pragma("unroll") for (int n = 0; n < 2; ++n) _Pragma("unroll") for (int k = 0; k < 2; ++k) dst[n][k] = *(const PG8_LAS bf16x8*)(lds + PG8_SB(b, h) + boff + n * 2048 + k * 1024); } while (0)
; #define PG8_MMA(ai, bj, At, Bt) do { __builtin_amdgcn_s_setprio(1); _Pragma("unroll") for (int m = 0; m < 4; ++m) _Pragma("unroll") for (int n = 0; n < 2; ++n) _Pragma("unroll") for (int k = 0; k < 2; ++k) \
;         acc[ai][bj][m][n] = __builtin_amdgcn_mfma_f32_16x16x32_bf16(Bt[n][k], At[m][k], acc[ai][bj][m][n], 0, 0, 0); __builtin_amdgcn_s_setprio(0); } while (0)
; #define PG8_WAIT_V(n) asm volatile("s_waitcnt vmcnt(" #n ")" ::: "memory")
; #define PG8_WAIT_L(n) asm volatile("s_waitcnt lgkmcnt(" #n ")" ::: "memory")
; #define PG8_BAR __builtin_amdgcn_s_barrier()
; #define PG8_SCHED __builtin_amdgcn_sched_barrier(0)
; template <class Epi, class Sched, bool ALIGN_EPI = false, bool SP2 = false>
; __device__ __forceinline__ void gemm_phase(PG8_LAS unsigned char* lds, const Gemm g, const Sched& S, const Epi& E) {
;     ...
;             PG8_LDA(At, 0, 1); PG8_STAGE(PG8_SB(0, 0), b2, voffB); PG8_STAGE(PG8_SB(0, 1), b2 + hB, voffB); PG8_STAGE(PG8_SA(0, 0), a2, voffA);
;             PG8_WAIT_V(8); PG8_WAIT_L(0); PG8_BAR; PG8_MMA(1, 0, At, B0); PG8_MMA(1, 1, At, B1); PG8_BAR; PG8_SCHED;
;             PG8_LDB(B0, 1, 0); PG8_LDB(B1, 1, 1); PG8_SCHED; PG8_LDA(At, 1, 0); PG8_STAGE(PG8_SA(0, 1), a2 + hA, voffA);
	s_add_i32 s18, s63, s49
	s_add_u32 s76, s42, s20
	s_addc_u32 s77, s43, s21
	s_mov_b32 m0, s18
	ds_read_b128 v[196:199], v173 offset:16384
	ds_read_b128 v[200:203], v173 offset:17408
	ds_read_b128 v[204:207], v173 offset:18432
	ds_read_b128 v[208:211], v173 offset:19456
	ds_read_b128 v[212:215], v173 offset:20480
	ds_read_b128 v[216:219], v173 offset:21504
	ds_read_b128 v[224:227], v173 offset:22528
	ds_read_b128 v[228:231], v173 offset:23552
	global_load_lds_dwordx4 v134, s[42:43]
	s_add_i32 m0, s18, 0x2000
	s_add_u32 s74, s42, 0x80000
	s_addc_u32 s75, s43, 0
	s_add_i32 s18, s64, s49
	global_load_lds_dwordx4 v130, s[42:43]
	s_mov_b32 m0, s18
	s_nop 0
	global_load_lds_dwordx4 v134, s[74:75]
	s_add_i32 m0, s18, 0x2000
	s_nop 0
	global_load_lds_dwordx4 v130, s[74:75]
	s_add_u32 s78, s44, s20
	s_addc_u32 s79, s45, s21
	s_waitcnt lgkmcnt(0)
	s_barrier
	s_waitcnt lgkmcnt(0)
	v_mfma_f32_16x16x32_bf16 v[62:65], v[148:151], v[196:199], v[62:65]
	v_mfma_f32_16x16x32_bf16 v[58:61], v[156:159], v[196:199], v[58:61]
	v_mfma_f32_16x16x32_bf16 v[46:49], v[148:151], v[204:207], v[46:49]
	v_mfma_f32_16x16x32_bf16 v[42:45], v[156:159], v[204:207], v[42:45]
	v_mfma_f32_16x16x32_bf16 v[30:33], v[148:151], v[212:215], v[30:33]
	v_mfma_f32_16x16x32_bf16 v[26:29], v[156:159], v[212:215], v[26:29]
	v_mfma_f32_16x16x32_bf16 v[14:17], v[148:151], v[224:227], v[14:17]
	v_mfma_f32_16x16x32_bf16 v[10:13], v[156:159], v[224:227], v[10:13]
	v_mfma_f32_16x16x32_bf16 v[62:65], v[152:155], v[200:203], v[62:65]
	v_mfma_f32_16x16x32_bf16 v[58:61], v[160:163], v[200:203], v[58:61]
	v_mfma_f32_16x16x32_bf16 v[46:49], v[152:155], v[208:211], v[46:49]
	v_mfma_f32_16x16x32_bf16 v[42:45], v[160:163], v[208:211], v[42:45]
	v_mfma_f32_16x16x32_bf16 v[30:33], v[152:155], v[216:219], v[30:33]
	v_mfma_f32_16x16x32_bf16 v[26:29], v[160:163], v[216:219], v[26:29]
	v_mfma_f32_16x16x32_bf16 v[14:17], v[152:155], v[228:231], v[14:17]
	v_mfma_f32_16x16x32_bf16 v[10:13], v[160:163], v[228:231], v[10:13]
	v_mfma_f32_16x16x32_bf16 v[54:57], v[180:183], v[196:199], v[54:57]
	v_mfma_f32_16x16x32_bf16 v[50:53], v[188:191], v[196:199], v[50:53]
	v_mfma_f32_16x16x32_bf16 v[38:41], v[180:183], v[204:207], v[38:41]
	v_mfma_f32_16x16x32_bf16 v[34:37], v[188:191], v[204:207], v[34:37]
	v_mfma_f32_16x16x32_bf16 v[22:25], v[180:183], v[212:215], v[22:25]
	v_mfma_f32_16x16x32_bf16 v[18:21], v[188:191], v[212:215], v[18:21]
	v_mfma_f32_16x16x32_bf16 v[6:9], v[180:183], v[224:227], v[6:9]
	v_mfma_f32_16x16x32_bf16 v[2:5], v[188:191], v[224:227], v[2:5]
	v_mfma_f32_16x16x32_bf16 v[54:57], v[184:187], v[200:203], v[54:57]
	v_mfma_f32_16x16x32_bf16 v[50:53], v[192:195], v[200:203], v[50:53]
	v_mfma_f32_16x16x32_bf16 v[38:41], v[184:187], v[208:211], v[38:41]
	v_mfma_f32_16x16x32_bf16 v[34:37], v[192:195], v[208:211], v[34:37]
	v_mfma_f32_16x16x32_bf16 v[22:25], v[184:187], v[216:219], v[22:25]
	v_mfma_f32_16x16x32_bf16 v[18:21], v[192:195], v[216:219], v[18:21]
	v_mfma_f32_16x16x32_bf16 v[6:9], v[184:187], v[228:231], v[6:9]
	v_mfma_f32_16x16x32_bf16 v[2:5], v[192:195], v[228:231], v[2:5]
	s_waitcnt vmcnt(4)
	s_barrier
	s_add_i32 s18, 0, 0x18000
	s_add_i32 s19, 0, 0x1c000
	v_add_u32_e32 v160, s18, v165
	v_add_u32_e32 v164, s19, v165
	ds_read_b128 v[148:151], v160
	ds_read_b128 v[152:155], v160 offset:1024
	ds_read_b128 v[156:159], v160 offset:2048
	ds_read_b128 v[160:163], v160 offset:3072
	ds_read_b128 v[180:183], v164
	ds_read_b128 v[184:187], v164 offset:1024
	ds_read_b128 v[188:191], v164 offset:2048
	ds_read_b128 v[192:195], v164 offset:3072
	ds_read_b128 v[196:199], v173 offset:32768
	ds_read_b128 v[200:203], v173 offset:33792
	ds_read_b128 v[204:207], v173 offset:34816
	ds_read_b128 v[208:211], v173 offset:35840
	ds_read_b128 v[212:215], v173 offset:36864
	ds_read_b128 v[216:219], v173 offset:37888
	ds_read_b128 v[224:227], v173 offset:38912
	ds_read_b128 v[228:231], v173 offset:39936
	s_mov_b32 m0, s51
	s_nop 0
	global_load_lds_dwordx4 v136, s[44:45]
	s_mov_b32 m0, s52
	s_nop 0
	global_load_lds_dwordx4 v132, s[44:45]
	s_add_u32 s44, s44, 0x80000
	s_addc_u32 s45, s45, 0
	s_mov_b32 m0, s53
	s_nop 0
	global_load_lds_dwordx4 v136, s[44:45]
	s_mov_b32 m0, s57
	s_nop 0
	global_load_lds_dwordx4 v132, s[44:45]
	s_waitcnt lgkmcnt(0)
	s_barrier
; #define PG8_STAGE(bufoff, gbase, voff) do { _Pragma("unroll") for (int _i = 0; _i < 2; ++_i) \
;         __builtin_amdgcn_global_load_lds((const unsigned*)((const char*)(gbase) + (voff)[_i]), (PG8_LAS unsigned*)(lds + (bufoff) + ldsw + _i * 8192), 16, 0, 0); } while (0)
; #define PG8_LDA(dst, b, h) do { _Pragma("unroll") for (int m = 0; m < 4; ++m) _Pragma("unroll") for (int k = 0; k < 2; ++k) dst[m][k] = *(const PG8_LAS bf16x8*)(lds + PG8_SA(b, h) + aoff + m * 2048 + k * 1024); } while (0)
; #define PG8_MMA(ai, bj, At, Bt) do { __builtin_amdgcn_s_setprio(1); _Pragma("unroll") for (int m = 0; m < 4; ++m) _Pragma("unroll") for (int n = 0; n < 2; ++n) _Pragma("unroll") for (int k = 0; k < 2; ++k) \
;         acc[ai][bj][m][n] = __builtin_amdgcn_mfma_f32_16x16x32_bf16(Bt[n][k], At[m][k], acc[ai][bj][m][n], 0, 0, 0); __builtin_amdgcn_s_setprio(0); } while (0)
; #define PG8_WAIT_V(n) asm volatile("s_waitcnt vmcnt(" #n ")" ::: "memory")
; #define PG8_WAIT_L(n) asm volatile("s_waitcnt lgkmcnt(" #n ")" ::: "memory")
; #define PG8_BAR __builtin_amdgcn_s_barrier()
; #define PG8_SCHED __builtin_amdgcn_sched_barrier(0)
; template <class Epi, class Sched, bool ALIGN_EPI = false, bool SP2 = false>
; __device__ __forceinline__ void gemm_phase(PG8_LAS unsigned char* lds, const Gemm g, const Sched& S, const Epi& E) {
;     ...
;             PG8_WAIT_V(8); PG8_WAIT_L(0); PG8_BAR; PG8_MMA(0, 0, At, B0); PG8_MMA(0, 1, At, B1); PG8_BAR; PG8_SCHED;
;             PG8_LDA(At, 1, 1); PG8_STAGE(PG8_SB(1, 0), b3, voffB); PG8_STAGE(PG8_SB(1, 1), b3 + hB, voffB); PG8_STAGE(PG8_SA(1, 0), a3, voffA);
;             PG8_WAIT_V(8); PG8_WAIT_L(0); PG8_BAR; PG8_MMA(1, 0, At, B0); PG8_MMA(1, 1, At, B1); PG8_BAR; PG8_SCHED;
	s_waitcnt lgkmcnt(0)
	v_mfma_f32_16x16x32_bf16 v[126:129], v[148:151], v[196:199], v[126:129]
	v_mfma_f32_16x16x32_bf16 v[122:125], v[156:159], v[196:199], v[122:125]
	v_mfma_f32_16x16x32_bf16 v[110:113], v[148:151], v[204:207], v[110:113]
	v_mfma_f32_16x16x32_bf16 v[106:109], v[156:159], v[204:207], v[106:109]
	v_mfma_f32_16x16x32_bf16 v[94:97], v[148:151], v[212:215], v[94:97]
	v_mfma_f32_16x16x32_bf16 v[90:93], v[156:159], v[212:215], v[90:93]
	v_mfma_f32_16x16x32_bf16 v[78:81], v[148:151], v[224:227], v[78:81]
	v_mfma_f32_16x16x32_bf16 v[74:77], v[156:159], v[224:227], v[74:77]
	v_mfma_f32_16x16x32_bf16 v[126:129], v[152:155], v[200:203], v[126:129]
	v_mfma_f32_16x16x32_bf16 v[122:125], v[160:163], v[200:203], v[122:125]
	v_mfma_f32_16x16x32_bf16 v[110:113], v[152:155], v[208:211], v[110:113]
	v_mfma_f32_16x16x32_bf16 v[106:109], v[160:163], v[208:211], v[106:109]
	v_mfma_f32_16x16x32_bf16 v[94:97], v[152:155], v[216:219], v[94:97]
	v_mfma_f32_16x16x32_bf16 v[90:93], v[160:163], v[216:219], v[90:93]
	v_mfma_f32_16x16x32_bf16 v[78:81], v[152:155], v[228:231], v[78:81]
	v_mfma_f32_16x16x32_bf16 v[74:77], v[160:163], v[228:231], v[74:77]
	v_mfma_f32_16x16x32_bf16 v[118:121], v[180:183], v[196:199], v[118:121]
	v_mfma_f32_16x16x32_bf16 v[114:117], v[188:191], v[196:199], v[114:117]
	v_mfma_f32_16x16x32_bf16 v[102:105], v[180:183], v[204:207], v[102:105]
	v_mfma_f32_16x16x32_bf16 v[98:101], v[188:191], v[204:207], v[98:101]
	v_mfma_f32_16x16x32_bf16 v[86:89], v[180:183], v[212:215], v[86:89]
	v_mfma_f32_16x16x32_bf16 v[82:85], v[188:191], v[212:215], v[82:85]
	v_mfma_f32_16x16x32_bf16 v[70:73], v[180:183], v[224:227], v[70:73]
	v_mfma_f32_16x16x32_bf16 v[66:69], v[188:191], v[224:227], v[66:69]
	v_mfma_f32_16x16x32_bf16 v[118:121], v[184:187], v[200:203], v[118:121]
	v_mfma_f32_16x16x32_bf16 v[114:117], v[192:195], v[200:203], v[114:117]
	v_mfma_f32_16x16x32_bf16 v[102:105], v[184:187], v[208:211], v[102:105]
	v_mfma_f32_16x16x32_bf16 v[98:101], v[192:195], v[208:211], v[98:101]
	v_mfma_f32_16x16x32_bf16 v[86:89], v[184:187], v[216:219], v[86:89]
	v_mfma_f32_16x16x32_bf16 v[82:85], v[192:195], v[216:219], v[82:85]
	v_mfma_f32_16x16x32_bf16 v[70:73], v[184:187], v[228:231], v[70:73]
	v_mfma_f32_16x16x32_bf16 v[66:69], v[192:195], v[228:231], v[66:69]
	s_barrier
	s_add_i32 s18, s18, s49
	s_mov_b32 m0, s18
	ds_read_b128 v[196:199], v173 offset:49152
	ds_read_b128 v[200:203], v173 offset:50176
	ds_read_b128 v[204:207], v173 offset:51200
	ds_read_b128 v[208:211], v173 offset:52224
	ds_read_b128 v[212:215], v173 offset:53248
	ds_read_b128 v[216:219], v173 offset:54272
	ds_read_b128 v[224:227], v173 offset:55296
	ds_read_b128 v[228:231], v173 offset:56320
	global_load_lds_dwordx4 v134, s[76:77]
	s_add_i32 m0, s18, 0x2000
	s_add_u32 s42, s42, 0x80080
	s_addc_u32 s43, s43, 0
	s_add_i32 s18, s19, s49
	global_load_lds_dwordx4 v130, s[76:77]
	s_mov_b32 m0, s18
	s_nop 0
	global_load_lds_dwordx4 v134, s[42:43]
	s_add_i32 m0, s18, 0x2000
	s_nop 0
	global_load_lds_dwordx4 v130, s[42:43]
	s_waitcnt lgkmcnt(0)
	s_barrier
	s_waitcnt lgkmcnt(0)
	v_mfma_f32_16x16x32_bf16 v[62:65], v[148:151], v[196:199], v[62:65]
	v_mfma_f32_16x16x32_bf16 v[58:61], v[156:159], v[196:199], v[58:61]
	v_mfma_f32_16x16x32_bf16 v[46:49], v[148:151], v[204:207], v[46:49]
	v_mfma_f32_16x16x32_bf16 v[42:45], v[156:159], v[204:207], v[42:45]
	v_mfma_f32_16x16x32_bf16 v[30:33], v[148:151], v[212:215], v[30:33]
	v_mfma_f32_16x16x32_bf16 v[26:29], v[156:159], v[212:215], v[26:29]
	v_mfma_f32_16x16x32_bf16 v[14:17], v[148:151], v[224:227], v[14:17]
	v_mfma_f32_16x16x32_bf16 v[10:13], v[156:159], v[224:227], v[10:13]
	v_mfma_f32_16x16x32_bf16 v[62:65], v[152:155], v[200:203], v[62:65]
	v_mfma_f32_16x16x32_bf16 v[58:61], v[160:163], v[200:203], v[58:61]
	v_mfma_f32_16x16x32_bf16 v[46:49], v[152:155], v[208:211], v[46:49]
	v_mfma_f32_16x16x32_bf16 v[42:45], v[160:163], v[208:211], v[42:45]
	v_mfma_f32_16x16x32_bf16 v[30:33], v[152:155], v[216:219], v[30:33]
	v_mfma_f32_16x16x32_bf16 v[26:29], v[160:163], v[216:219], v[26:29]
	v_mfma_f32_16x16x32_bf16 v[14:17], v[152:155], v[228:231], v[14:17]
	v_mfma_f32_16x16x32_bf16 v[10:13], v[160:163], v[228:231], v[10:13]
	v_mfma_f32_16x16x32_bf16 v[54:57], v[180:183], v[196:199], v[54:57]
	v_mfma_f32_16x16x32_bf16 v[50:53], v[188:191], v[196:199], v[50:53]
	v_mfma_f32_16x16x32_bf16 v[38:41], v[180:183], v[204:207], v[38:41]
	v_mfma_f32_16x16x32_bf16 v[34:37], v[188:191], v[204:207], v[34:37]
	v_mfma_f32_16x16x32_bf16 v[22:25], v[180:183], v[212:215], v[22:25]
	v_mfma_f32_16x16x32_bf16 v[18:21], v[188:191], v[212:215], v[18:21]
	v_mfma_f32_16x16x32_bf16 v[6:9], v[180:183], v[224:227], v[6:9]
	v_mfma_f32_16x16x32_bf16 v[2:5], v[188:191], v[224:227], v[2:5]
	v_mfma_f32_16x16x32_bf16 v[54:57], v[184:187], v[200:203], v[54:57]
	v_mfma_f32_16x16x32_bf16 v[50:53], v[192:195], v[200:203], v[50:53]
	v_mfma_f32_16x16x32_bf16 v[38:41], v[184:187], v[208:211], v[38:41]
	v_mfma_f32_16x16x32_bf16 v[34:37], v[192:195], v[208:211], v[34:37]
	v_mfma_f32_16x16x32_bf16 v[22:25], v[184:187], v[216:219], v[22:25]
	v_mfma_f32_16x16x32_bf16 v[18:21], v[192:195], v[216:219], v[18:21]
	v_mfma_f32_16x16x32_bf16 v[6:9], v[184:187], v[228:231], v[6:9]
	v_mfma_f32_16x16x32_bf16 v[2:5], v[192:195], v[228:231], v[2:5]
	s_waitcnt vmcnt(6)
	s_barrier
	s_add_i32 s72, s72, 2
	s_add_u32 s8, s8, 0x100
	s_addc_u32 s9, s9, 0
	s_add_u32 s70, s70, 0x100
	s_addc_u32 s71, s71, 0
	s_cmp_gt_u32 s72, 29
	s_cbranch_scc0 .LBB0_1048
	s_branch .Lkafter_4

; #define PG8_BAR __builtin_amdgcn_s_barrier()
; template <class Epi, class Sched, bool ALIGN_EPI = false, bool SP2 = false>
; __device__ __forceinline__ void gemm_phase(PG8_LAS unsigned char* lds, const Gemm g, const Sched& S, const Epi& E) {
;     ...
;         if constexpr (ALIGN_EPI) { if (wr == 0) PG8_BAR; }
.Lkafter_4:
	s_and_b64 vcc, exec, s[22:23]
	s_cbranch_vccz .LBB0_1051
	s_barrier

; #define PG8_STAGE(bufoff, gbase, voff) do { _Pragma("unroll") for (int _i = 0; _i < 2; ++_i) \
;         __builtin_amdgcn_global_load_lds((const unsigned*)((const char*)(gbase) + (voff)[_i]), (PG8_LAS unsigned*)(lds + (bufoff) + ldsw + _i * 8192), 16, 0, 0); } while (0)
; #define PG8_WAIT_V(n) asm volatile("s_waitcnt vmcnt(" #n ")" ::: "memory")
; #define PG8_BAR __builtin_amdgcn_s_barrier()
; template <class Epi, class Sched, bool ALIGN_EPI = false, bool SP2 = false>
; __device__ __forceinline__ void gemm_phase(PG8_LAS unsigned char* lds, const Gemm g, const Sched& S, const Epi& E) {
;     ...
;     const int tid = tid_o, wid = __builtin_amdgcn_readfirstlane(tid >> 6), lane = tid & 63, wr = wid >> 2, wc = wid & 3, fr = lane & 15, fq = lane >> 4;
;     const int K = g.K, nt = K / BK;
;     unsigned voffA[2], voffB[2];
; #pragma unroll
;     for (int i = 0; i < 2; ++i) { int R, C; stage_rc(tid * 16 + i * 8192, R, C); const int Rb = Epi::PERM ? ((R & ~31) + perm32(R & 31)) : R;
;         voffA[i] = (unsigned)(R * g.lda + C) * 2u; voffB[i] = (unsigned)(Rb * g.ldb + C) * 2u; }
;     const size_t kstep = (size_t)(BK * 2);
;     const size_t hA = (size_t)HALF * g.lda * 2, hB = (size_t)HALF * g.ldb * 2;
;     const size_t tA = 2 * hA, tB = 2 * hB, pnA = (size_t)g.a_pn_off * 2;
;     const unsigned ldsw = (unsigned)wid * 1024u;
;     const int aoff = lds_byte(wr * 64 + fr, fq * 8), boff = lds_byte(wc * 32 + fr, fq * 8);
;     ...
;         PG8_STAGE(PG8_SB(1, 0), cB + kstep, voffB); PG8_STAGE(PG8_SA(1, 0), cA + kstep, voffA); PG8_STAGE(PG8_SB(1, 1), cB + hB + kstep, voffB);
;         PG8_WAIT_V(6); PG8_BAR;
.LBB0_1113:
	s_add_u32 s12, s6, 0x15800000
	s_addc_u32 s13, s7, 0
	s_add_u32 s14, s6, 0x2000000
	s_mov_b64 s[16:17], 0x80
	s_addc_u32 s15, s7, 0
	s_and_b32 s51, s4, 3
	s_add_i32 m0, s46, 0x18000
	v_lshl_add_u64 v[8:9], v[8:9], 0, s[16:17]
	s_lshl_b32 s4, s5, 13
	s_lshl_b32 s18, s51, 12
	s_waitcnt vmcnt(2)
	s_barrier
	global_load_lds_dwordx4 v[8:9], off
	v_lshl_add_u64 v[4:5], v[4:5], 0, s[16:17]
	s_add_i32 m0, s46, 0x1a000
	s_add_i32 s52, s46, 0x8000
	s_add_i32 s53, s46, 0xa000
	global_load_lds_dwordx4 v[4:5], off
	v_lshl_add_u64 v[2:3], v[2:3], 0, s[16:17]
	s_mov_b32 m0, s52
	s_add_u32 s6, s36, 0x160080
	global_load_lds_dwordx4 v[2:3], off
	v_lshl_add_u64 v[2:3], v[6:7], 0, s[16:17]
	s_mov_b32 m0, s53
	s_addc_u32 s7, s37, 0
	global_load_lds_dwordx4 v[2:3], off
	s_add_i32 m0, s46, 0x1c000
	v_lshl_add_u64 v[2:3], s[6:7], 0, v[156:157]
	global_load_lds_dwordx4 v[2:3], off
	v_lshl_add_u64 v[2:3], s[6:7], 0, v[160:161]
	s_add_i32 m0, s46, 0x1e000
	s_mov_b64 s[6:7], 0x160080
	global_load_lds_dwordx4 v[2:3], off
	v_bfe_u32 v3, v10, 4, 2
	v_and_b32_e32 v2, 15, v10
	v_lshlrev_b32_e32 v5, 4, v3
	v_lshl_or_b32 v1, s5, 6, v2
	v_lshl_or_b32 v2, v2, 6, v5
	v_lshlrev_b32_e32 v5, 2, v10
	v_and_b32_e32 v5, 32, v5
	v_lshlrev_b32_e32 v4, 3, v3
	v_bitop3_b32 v6, v2, s4, v5 bitop3:0xde
	v_bitop3_b32 v188, v2, s18, v5 bitop3:0xde
	v_cmp_eq_u32_e64 s[4:5], 0, v3
	v_lshrrev_b32_e32 v3, 1, v11
	v_mul_lo_u32 v2, v12, s9
	v_mad_u64_u32 v[2:3], s[38:39], v3, s22, v[2:3]
	v_or_b32_e32 v2, v2, v13
	v_add_lshl_u32 v2, v2, v14, 1
	v_mov_b32_e32 v3, v157
	v_lshl_add_u64 v[162:163], v[2:3], 0, s[6:7]
	v_lshrrev_b32_e32 v3, 1, v15
	v_mul_lo_u32 v2, v16, s9
	s_cmpk_lt_u32 s8, 0x100
	v_mad_u64_u32 v[2:3], s[8:9], v3, s22, v[2:3]
	s_waitcnt vmcnt(6)
	v_or_b32_e32 v2, v2, v17
	s_cselect_b64 s[20:21], -1, 0
	v_add_lshl_u32 v2, v2, v18, 1
	v_mov_b32_e32 v3, v157
	s_add_i32 s55, 0, 0x10000
	s_add_i32 s56, 0, 0x14000
	v_lshl_or_b32 v189, s51, 5, v4
	s_waitcnt lgkmcnt(0)
	s_ashr_i32 s54, s50, 31
	v_lshl_add_u64 v[164:165], v[2:3], 0, s[6:7]
	v_mov_b64_e32 v[166:167], 0x200
	v_mov_b64_e32 v[168:169], 0x1ff
	v_add_u32_e32 v190, s55, v188
	v_add_u32_e32 v191, s56, v188
	v_add_u32_e32 v192, 0, v6
	v_mbcnt_hi_u32_b32 v193, -1, v222
	s_mov_b32 s57, 0
	s_barrier
	v_readfirstlane_b32 s101, v0
	s_nop 3
	s_lshr_b32 s101, s101, 8
	s_branch .LBB0_1116

; #define PG8_STAGE(bufoff, gbase, voff) do { _Pragma("unroll") for (int _i = 0; _i < 2; ++_i) \
;         __builtin_amdgcn_global_load_lds((const unsigned*)((const char*)(gbase) + (voff)[_i]), (PG8_LAS unsigned*)(lds + (bufoff) + ldsw + _i * 8192), 16, 0, 0); } while (0)
; #define PG8_LDA(dst, b, h) do { _Pragma("unroll") for (int m = 0; m < 4; ++m) _Pragma("unroll") for (int k = 0; k < 2; ++k) dst[m][k] = *(const PG8_LAS bf16x8*)(lds + PG8_SA(b, h) + aoff + m * 2048 + k * 1024); } while (0)
; #define PG8_LDB(dst, b, h) do { _Pragma("unroll") for (int n = 0; n < 2; ++n) _Pragma("unroll") for (int k = 0; k < 2; ++k) dst[n][k] = *(const PG8_LAS bf16x8*)(lds + PG8_SB(b, h) + boff + n * 2048 + k * 1024); } while (0)
; #define PG8_MMA(ai, bj, At, Bt) do { __builtin_amdgcn_s_setprio(1); _Pragma("unroll") for (int m = 0; m < 4; ++m) _Pragma("unroll") for (int n = 0; n < 2; ++n) _Pragma("unroll") for (int k = 0; k < 2; ++k) \
;         acc[ai][bj][m][n] = __builtin_amdgcn_mfma_f32_16x16x32_bf16(Bt[n][k], At[m][k], acc[ai][bj][m][n], 0, 0, 0); __builtin_amdgcn_s_setprio(0); } while (0)
; #define PG8_WAIT_V(n) asm volatile("s_waitcnt vmcnt(" #n ")" ::: "memory")
; #define PG8_WAIT_L(n) asm volatile("s_waitcnt lgkmcnt(" #n ")" ::: "memory")
; template <class Epi, class Sched, bool ALIGN_EPI = false, bool SP2 = false>
; __device__ __forceinline__ void gemm_phase(PG8_LAS unsigned char* lds, const Gemm g, const Sched& S, const Epi& E) {
;     ...
;             const bool last = (t == nt - 2);
;             const char* a1 = cA + (size_t)(t + 1) * kstep;
;             const char* a2 = last ? nA : cA + (size_t)(t + 2) * kstep; const char* b2 = last ? nB : cB + (size_t)(t + 2) * kstep;
;             const char* a3 = a2 + kstep; const char* b3 = b2 + kstep;
;             if (last && has_next) S.a_ready(nxt);
;             if constexpr (SP2) {
;             PG8_LDB(B0, 0, 0); PG8_LDB(B1, 0, 1); PG8_SCHED; PG8_LDA(At, 0, 0); PG8_STAGE(PG8_SA(1, 1), a1 + hA, voffA);
;             PG8_WAIT_V(8); PG8_WAIT_L(0); PG8_BAR; PG8_MMA(0, 0, At, B0); PG8_MMA(0, 1, At, B1); PG8_BAR; PG8_SCHED;
;     ...
;         for (int a = 0; a < 2; ++a)
; #pragma unroll
;             for (int b = 0; b < 2; ++b)
; #pragma unroll
;                 for (int m = 0; m < 4; ++m)
; #pragma unroll
;                     for (int n = 0; n < 2; ++n) acc[a][b][m][n] = (f32x4){0.f, 0.f, 0.f, 0.f};
.LBB0_1126:
	s_add_u32 s61, s36, 0x100
	v_mov_b32_e32 v2, 0
	s_addc_u32 s62, s37, 0
	s_mov_b32 s63, -2
	s_waitcnt lgkmcnt(0)
	v_mov_b32_e32 v3, v2
	v_mov_b64_e32 v[4:5], 0
	v_mov_b64_e32 v[6:7], 0
	v_mov_b64_e32 v[8:9], 0
	v_mov_b64_e32 v[10:11], 0
	v_mov_b64_e32 v[12:13], 0
	v_mov_b64_e32 v[14:15], 0
	v_mov_b64_e32 v[16:17], 0
	v_mov_b64_e32 v[18:19], 0
	v_mov_b64_e32 v[20:21], 0
	v_mov_b64_e32 v[22:23], 0
	v_mov_b64_e32 v[24:25], 0
	v_mov_b64_e32 v[26:27], 0
	v_mov_b64_e32 v[28:29], 0
	v_mov_b64_e32 v[30:31], 0
	v_mov_b64_e32 v[32:33], 0
	v_mov_b64_e32 v[34:35], 0
	v_mov_b64_e32 v[36:37], 0
	v_mov_b64_e32 v[38:39], 0
	v_mov_b64_e32 v[40:41], 0
	v_mov_b64_e32 v[42:43], 0
	v_mov_b64_e32 v[44:45], 0
	v_mov_b64_e32 v[46:47], 0
	v_mov_b64_e32 v[48:49], 0
	v_mov_b64_e32 v[50:51], 0
	v_mov_b64_e32 v[52:53], 0
	v_mov_b64_e32 v[54:55], 0
	v_mov_b64_e32 v[56:57], 0
	v_mov_b64_e32 v[58:59], 0
	v_mov_b64_e32 v[60:61], 0
	v_mov_b64_e32 v[62:63], 0
	v_mov_b64_e32 v[64:65], 0
	v_mov_b64_e32 v[66:67], 0
	v_mov_b64_e32 v[68:69], 0
	v_mov_b64_e32 v[70:71], 0
	v_mov_b64_e32 v[72:73], 0
	v_mov_b64_e32 v[74:75], 0
	v_mov_b64_e32 v[76:77], 0
	v_mov_b64_e32 v[78:79], 0
	v_mov_b64_e32 v[80:81], 0
	v_mov_b64_e32 v[82:83], 0
	v_mov_b64_e32 v[84:85], 0
	v_mov_b64_e32 v[86:87], 0
	v_mov_b64_e32 v[88:89], 0
	v_mov_b64_e32 v[90:91], 0
	v_mov_b64_e32 v[92:93], 0
	v_mov_b64_e32 v[94:95], 0
	v_mov_b64_e32 v[96:97], 0
	v_mov_b64_e32 v[98:99], 0
	v_mov_b64_e32 v[100:101], 0
	v_mov_b64_e32 v[102:103], 0
	v_mov_b64_e32 v[104:105], 0
	v_mov_b64_e32 v[106:107], 0
	v_mov_b64_e32 v[108:109], 0
	v_mov_b64_e32 v[110:111], 0
	v_mov_b64_e32 v[112:113], 0
	v_mov_b64_e32 v[114:115], 0
	v_mov_b64_e32 v[116:117], 0
	v_mov_b64_e32 v[118:119], 0
	v_mov_b64_e32 v[120:121], 0
	v_mov_b64_e32 v[122:123], 0
	v_mov_b64_e32 v[124:125], 0
	v_mov_b64_e32 v[126:127], 0
	v_mov_b64_e32 v[128:129], 0
	s_add_u32 s78, s24, 0x80
	s_addc_u32 s79, s25, 0
	s_cmp_eq_u32 s101, 0
	s_cbranch_scc0 .Lkt_5
.LBB0_1127:
	ds_read_b128 v[130:133], v190
	ds_read_b128 v[134:137], v190 offset:1024
	ds_read_b128 v[138:141], v190 offset:2048
	ds_read_b128 v[142:145], v190 offset:3072
	ds_read_b128 v[146:149], v191
	ds_read_b128 v[150:153], v191 offset:1024
	ds_read_b128 v[170:173], v191 offset:2048
	ds_read_b128 v[174:177], v191 offset:3072
	s_add_u32 s36, s24, 0x100
	s_addc_u32 s37, s25, 0
	s_cmpk_eq_i32 s63, 0x54
	s_cselect_b32 s41, s9, s37
	s_cselect_b32 s40, s8, s36
	s_cselect_b32 s39, s23, s62
	s_cselect_b32 s38, s22, s61
	s_add_i32 m0, s46, 0xc000
	ds_read_b128 v[178:181], v192
	ds_read_b128 v[182:185], v192 offset:1024
	ds_read_b128 v[194:197], v192 offset:2048
	ds_read_b128 v[198:201], v192 offset:3072
	ds_read_b128 v[202:205], v192 offset:4096
	ds_read_b128 v[206:209], v192 offset:5120
	ds_read_b128 v[210:213], v192 offset:6144
	ds_read_b128 v[214:217], v192 offset:7168
	global_load_lds_dwordx4 v162, s[24:25]
	s_add_i32 m0, s46, 0xe000
	s_nop 0
	global_load_lds_dwordx4 v164, s[24:25]
	s_mov_b32 m0, s52
	s_nop 0
	global_load_lds_dwordx4 v154, s[78:79]
	s_mov_b32 m0, s53
	s_nop 0
	global_load_lds_dwordx4 v158, s[78:79]
	s_waitcnt lgkmcnt(0)
	s_barrier
	s_waitcnt lgkmcnt(0)
	v_mfma_f32_16x16x32_bf16 v[126:129], v[130:133], v[178:181], v[126:129]
	v_mfma_f32_16x16x32_bf16 v[122:125], v[138:141], v[178:181], v[122:125]
	v_mfma_f32_16x16x32_bf16 v[110:113], v[130:133], v[194:197], v[110:113]
	v_mfma_f32_16x16x32_bf16 v[106:109], v[138:141], v[194:197], v[106:109]
	v_mfma_f32_16x16x32_bf16 v[94:97], v[130:133], v[202:205], v[94:97]
	v_mfma_f32_16x16x32_bf16 v[90:93], v[138:141], v[202:205], v[90:93]
	v_mfma_f32_16x16x32_bf16 v[78:81], v[130:133], v[210:213], v[78:81]
	v_mfma_f32_16x16x32_bf16 v[74:77], v[138:141], v[210:213], v[74:77]
	v_mfma_f32_16x16x32_bf16 v[126:129], v[134:137], v[182:185], v[126:129]
	v_mfma_f32_16x16x32_bf16 v[122:125], v[142:145], v[182:185], v[122:125]
	v_mfma_f32_16x16x32_bf16 v[110:113], v[134:137], v[198:201], v[110:113]
	v_mfma_f32_16x16x32_bf16 v[106:109], v[142:145], v[198:201], v[106:109]
	v_mfma_f32_16x16x32_bf16 v[94:97], v[134:137], v[206:209], v[94:97]
	v_mfma_f32_16x16x32_bf16 v[90:93], v[142:145], v[206:209], v[90:93]
	v_mfma_f32_16x16x32_bf16 v[78:81], v[134:137], v[214:217], v[78:81]
	v_mfma_f32_16x16x32_bf16 v[74:77], v[142:145], v[214:217], v[74:77]
	v_mfma_f32_16x16x32_bf16 v[118:121], v[146:149], v[178:181], v[118:121]
	v_mfma_f32_16x16x32_bf16 v[114:117], v[170:173], v[178:181], v[114:117]
	v_mfma_f32_16x16x32_bf16 v[102:105], v[146:149], v[194:197], v[102:105]
	v_mfma_f32_16x16x32_bf16 v[98:101], v[170:173], v[194:197], v[98:101]
	v_mfma_f32_16x16x32_bf16 v[86:89], v[146:149], v[202:205], v[86:89]
	v_mfma_f32_16x16x32_bf16 v[82:85], v[170:173], v[202:205], v[82:85]
	v_mfma_f32_16x16x32_bf16 v[70:73], v[146:149], v[210:213], v[70:73]
	v_mfma_f32_16x16x32_bf16 v[66:69], v[170:173], v[210:213], v[66:69]
	v_mfma_f32_16x16x32_bf16 v[118:121], v[150:153], v[182:185], v[118:121]
	v_mfma_f32_16x16x32_bf16 v[114:117], v[174:177], v[182:185], v[114:117]
	v_mfma_f32_16x16x32_bf16 v[102:105], v[150:153], v[198:201], v[102:105]
	v_mfma_f32_16x16x32_bf16 v[98:101], v[174:177], v[198:201], v[98:101]
	v_mfma_f32_16x16x32_bf16 v[86:89], v[150:153], v[206:209], v[86:89]
	v_mfma_f32_16x16x32_bf16 v[82:85], v[174:177], v[206:209], v[82:85]
	v_mfma_f32_16x16x32_bf16 v[70:73], v[150:153], v[214:217], v[70:73]
	v_mfma_f32_16x16x32_bf16 v[66:69], v[174:177], v[214:217], v[66:69]
	s_waitcnt vmcnt(8)
	s_barrier
; #define PG8_STAGE(bufoff, gbase, voff) do { _Pragma("unroll") for (int _i = 0; _i < 2; ++_i) \
;         __builtin_amdgcn_global_load_lds((const unsigned*)((const char*)(gbase) + (voff)[_i]), (PG8_LAS unsigned*)(lds + (bufoff) + ldsw + _i * 8192), 16, 0, 0); } while (0)
; #define PG8_LDA(dst, b, h) do { _Pragma("unroll") for (int m = 0; m < 4; ++m) _Pragma("unroll") for (int k = 0; k < 2; ++k) dst[m][k] = *(const PG8_LAS bf16x8*)(lds + PG8_SA(b, h) + aoff + m * 2048 + k * 1024); } while (0)
; #define PG8_LDB(dst, b, h) do { _Pragma("unroll") for (int n = 0; n < 2; ++n) _Pragma("unroll") for (int k = 0; k < 2; ++k) dst[n][k] = *(const PG8_LAS bf16x8*)(lds + PG8_SB(b, h) + boff + n * 2048 + k * 1024); } while (0)
; #define PG8_MMA(ai, bj, At, Bt) do { __builtin_amdgcn_s_setprio(1); _Pragma("unroll") for (int m = 0; m < 4; ++m) _Pragma("unroll") for (int n = 0; n < 2; ++n) _Pragma("unroll") for (int k = 0; k < 2; ++k) \
;         acc[ai][bj][m][n] = __builtin_amdgcn_mfma_f32_16x16x32_bf16(Bt[n][k], At[m][k], acc[ai][bj][m][n], 0, 0, 0); __builtin_amdgcn_s_setprio(0); } while (0)
; #define PG8_WAIT_V(n) asm volatile("s_waitcnt vmcnt(" #n ")" ::: "memory")
; #define PG8_WAIT_L(n) asm volatile("s_waitcnt lgkmcnt(" #n ")" ::: "memory")
; #define PG8_BAR __builtin_amdgcn_s_barrier()
; #define PG8_SCHED __builtin_amdgcn_sched_barrier(0)
; template <class Epi, class Sched, bool ALIGN_EPI = false, bool SP2 = false>
; __device__ __forceinline__ void gemm_phase(PG8_LAS unsigned char* lds, const Gemm g, const Sched& S, const Epi& E) {
;     ...
;             PG8_LDA(At, 0, 1); PG8_STAGE(PG8_SB(0, 0), b2, voffB); PG8_STAGE(PG8_SB(0, 1), b2 + hB, voffB); PG8_STAGE(PG8_SA(0, 0), a2, voffA);
;             PG8_WAIT_V(8); PG8_WAIT_L(0); PG8_BAR; PG8_MMA(1, 0, At, B0); PG8_MMA(1, 1, At, B1); PG8_BAR; PG8_SCHED;
;             PG8_LDB(B0, 1, 0); PG8_LDB(B1, 1, 1); PG8_SCHED; PG8_LDA(At, 1, 0); PG8_STAGE(PG8_SA(0, 1), a2 + hA, voffA);
	s_add_i32 s18, s55, s45
	s_add_u32 s76, s38, s16
	s_addc_u32 s77, s39, s17
	s_mov_b32 m0, s18
	ds_read_b128 v[178:181], v192 offset:16384
	ds_read_b128 v[182:185], v192 offset:17408
	ds_read_b128 v[194:197], v192 offset:18432
	ds_read_b128 v[198:201], v192 offset:19456
	ds_read_b128 v[202:205], v192 offset:20480
	ds_read_b128 v[206:209], v192 offset:21504
	ds_read_b128 v[210:213], v192 offset:22528
	ds_read_b128 v[214:217], v192 offset:23552
	global_load_lds_dwordx4 v156, s[38:39]
	s_add_i32 m0, s18, 0x2000
	s_add_u32 s24, s38, 0x160000
	s_addc_u32 s25, s39, 0
	s_add_i32 s18, s56, s45
	global_load_lds_dwordx4 v160, s[38:39]
	s_mov_b32 m0, s18
	s_nop 0
	global_load_lds_dwordx4 v156, s[24:25]
	s_add_i32 m0, s18, 0x2000
	s_nop 0
	global_load_lds_dwordx4 v160, s[24:25]
	s_add_u32 s78, s40, s16
	s_addc_u32 s79, s41, s17
	s_waitcnt lgkmcnt(0)
	s_barrier
	s_waitcnt lgkmcnt(0)
	v_mfma_f32_16x16x32_bf16 v[62:65], v[130:133], v[178:181], v[62:65]
	v_mfma_f32_16x16x32_bf16 v[58:61], v[138:141], v[178:181], v[58:61]
	v_mfma_f32_16x16x32_bf16 v[46:49], v[130:133], v[194:197], v[46:49]
	v_mfma_f32_16x16x32_bf16 v[42:45], v[138:141], v[194:197], v[42:45]
	v_mfma_f32_16x16x32_bf16 v[30:33], v[130:133], v[202:205], v[30:33]
	v_mfma_f32_16x16x32_bf16 v[26:29], v[138:141], v[202:205], v[26:29]
	v_mfma_f32_16x16x32_bf16 v[14:17], v[130:133], v[210:213], v[14:17]
	v_mfma_f32_16x16x32_bf16 v[10:13], v[138:141], v[210:213], v[10:13]
	v_mfma_f32_16x16x32_bf16 v[62:65], v[134:137], v[182:185], v[62:65]
	v_mfma_f32_16x16x32_bf16 v[58:61], v[142:145], v[182:185], v[58:61]
	v_mfma_f32_16x16x32_bf16 v[46:49], v[134:137], v[198:201], v[46:49]
	v_mfma_f32_16x16x32_bf16 v[42:45], v[142:145], v[198:201], v[42:45]
	v_mfma_f32_16x16x32_bf16 v[30:33], v[134:137], v[206:209], v[30:33]
	v_mfma_f32_16x16x32_bf16 v[26:29], v[142:145], v[206:209], v[26:29]
	v_mfma_f32_16x16x32_bf16 v[14:17], v[134:137], v[214:217], v[14:17]
	v_mfma_f32_16x16x32_bf16 v[10:13], v[142:145], v[214:217], v[10:13]
	v_mfma_f32_16x16x32_bf16 v[54:57], v[146:149], v[178:181], v[54:57]
	v_mfma_f32_16x16x32_bf16 v[50:53], v[170:173], v[178:181], v[50:53]
	v_mfma_f32_16x16x32_bf16 v[38:41], v[146:149], v[194:197], v[38:41]
	v_mfma_f32_16x16x32_bf16 v[34:37], v[170:173], v[194:197], v[34:37]
	v_mfma_f32_16x16x32_bf16 v[22:25], v[146:149], v[202:205], v[22:25]
	v_mfma_f32_16x16x32_bf16 v[18:21], v[170:173], v[202:205], v[18:21]
	v_mfma_f32_16x16x32_bf16 v[6:9], v[146:149], v[210:213], v[6:9]
	v_mfma_f32_16x16x32_bf16 v[2:5], v[170:173], v[210:213], v[2:5]
	v_mfma_f32_16x16x32_bf16 v[54:57], v[150:153], v[182:185], v[54:57]
	v_mfma_f32_16x16x32_bf16 v[50:53], v[174:177], v[182:185], v[50:53]
	v_mfma_f32_16x16x32_bf16 v[38:41], v[150:153], v[198:201], v[38:41]
	v_mfma_f32_16x16x32_bf16 v[34:37], v[174:177], v[198:201], v[34:37]
	v_mfma_f32_16x16x32_bf16 v[22:25], v[150:153], v[206:209], v[22:25]
	v_mfma_f32_16x16x32_bf16 v[18:21], v[174:177], v[206:209], v[18:21]
	v_mfma_f32_16x16x32_bf16 v[6:9], v[150:153], v[214:217], v[6:9]
	v_mfma_f32_16x16x32_bf16 v[2:5], v[174:177], v[214:217], v[2:5]
	s_waitcnt vmcnt(4)
	s_barrier
	s_add_i32 s18, 0, 0x18000
	s_add_i32 s19, 0, 0x1c000
	v_add_u32_e32 v142, s18, v188
	v_add_u32_e32 v174, s19, v188
	ds_read_b128 v[130:133], v142
	ds_read_b128 v[134:137], v142 offset:1024
	ds_read_b128 v[138:141], v142 offset:2048
	ds_read_b128 v[142:145], v142 offset:3072
	ds_read_b128 v[146:149], v174
	ds_read_b128 v[150:153], v174 offset:1024
	ds_read_b128 v[170:173], v174 offset:2048
	ds_read_b128 v[174:177], v174 offset:3072
	s_add_u32 s24, s40, 0x160000
	s_addc_u32 s25, s41, 0
	s_mov_b32 m0, s48
	ds_read_b128 v[178:181], v192 offset:32768
	ds_read_b128 v[182:185], v192 offset:33792
	ds_read_b128 v[194:197], v192 offset:34816
	ds_read_b128 v[198:201], v192 offset:35840
	ds_read_b128 v[202:205], v192 offset:36864
	ds_read_b128 v[206:209], v192 offset:37888
	ds_read_b128 v[210:213], v192 offset:38912
	ds_read_b128 v[214:217], v192 offset:39936
	global_load_lds_dwordx4 v154, s[24:25]
	s_mov_b32 m0, s49
	s_nop 0
	global_load_lds_dwordx4 v158, s[24:25]
	s_mov_b32 m0, s46
	s_nop 0
	global_load_lds_dwordx4 v154, s[40:41]
	s_mov_b32 m0, s47
	s_nop 0
	global_load_lds_dwordx4 v158, s[40:41]
	s_waitcnt lgkmcnt(0)
	s_barrier
; #define PG8_STAGE(bufoff, gbase, voff) do { _Pragma("unroll") for (int _i = 0; _i < 2; ++_i) \
;         __builtin_amdgcn_global_load_lds((const unsigned*)((const char*)(gbase) + (voff)[_i]), (PG8_LAS unsigned*)(lds + (bufoff) + ldsw + _i * 8192), 16, 0, 0); } while (0)
; #define PG8_LDA(dst, b, h) do { _Pragma("unroll") for (int m = 0; m < 4; ++m) _Pragma("unroll") for (int k = 0; k < 2; ++k) dst[m][k] = *(const PG8_LAS bf16x8*)(lds + PG8_SA(b, h) + aoff + m * 2048 + k * 1024); } while (0)
; #define PG8_MMA(ai, bj, At, Bt) do { __builtin_amdgcn_s_setprio(1); _Pragma("unroll") for (int m = 0; m < 4; ++m) _Pragma("unroll") for (int n = 0; n < 2; ++n) _Pragma("unroll") for (int k = 0; k < 2; ++k) \
;         acc[ai][bj][m][n] = __builtin_amdgcn_mfma_f32_16x16x32_bf16(Bt[n][k], At[m][k], acc[ai][bj][m][n], 0, 0, 0); __builtin_amdgcn_s_setprio(0); } while (0)
; #define PG8_WAIT_V(n) asm volatile("s_waitcnt vmcnt(" #n ")" ::: "memory")
; #define PG8_WAIT_L(n) asm volatile("s_waitcnt lgkmcnt(" #n ")" ::: "memory")
; #define PG8_BAR __builtin_amdgcn_s_barrier()
; #define PG8_SCHED __builtin_amdgcn_sched_barrier(0)
; template <class Epi, class Sched, bool ALIGN_EPI = false, bool SP2 = false>
; __device__ __forceinline__ void gemm_phase(PG8_LAS unsigned char* lds, const Gemm g, const Sched& S, const Epi& E) {
;     ...
;             PG8_WAIT_V(8); PG8_WAIT_L(0); PG8_BAR; PG8_MMA(0, 0, At, B0); PG8_MMA(0, 1, At, B1); PG8_BAR; PG8_SCHED;
;             PG8_LDA(At, 1, 1); PG8_STAGE(PG8_SB(1, 0), b3, voffB); PG8_STAGE(PG8_SB(1, 1), b3 + hB, voffB); PG8_STAGE(PG8_SA(1, 0), a3, voffA);
;             PG8_WAIT_V(8); PG8_WAIT_L(0); PG8_BAR; PG8_MMA(1, 0, At, B0); PG8_MMA(1, 1, At, B1); PG8_BAR; PG8_SCHED;
	s_waitcnt lgkmcnt(0)
	v_mfma_f32_16x16x32_bf16 v[126:129], v[130:133], v[178:181], v[126:129]
	v_mfma_f32_16x16x32_bf16 v[122:125], v[138:141], v[178:181], v[122:125]
	v_mfma_f32_16x16x32_bf16 v[110:113], v[130:133], v[194:197], v[110:113]
	v_mfma_f32_16x16x32_bf16 v[106:109], v[138:141], v[194:197], v[106:109]
	v_mfma_f32_16x16x32_bf16 v[94:97], v[130:133], v[202:205], v[94:97]
	v_mfma_f32_16x16x32_bf16 v[90:93], v[138:141], v[202:205], v[90:93]
	v_mfma_f32_16x16x32_bf16 v[78:81], v[130:133], v[210:213], v[78:81]
	v_mfma_f32_16x16x32_bf16 v[74:77], v[138:141], v[210:213], v[74:77]
	v_mfma_f32_16x16x32_bf16 v[126:129], v[134:137], v[182:185], v[126:129]
	v_mfma_f32_16x16x32_bf16 v[122:125], v[142:145], v[182:185], v[122:125]
	v_mfma_f32_16x16x32_bf16 v[110:113], v[134:137], v[198:201], v[110:113]
	v_mfma_f32_16x16x32_bf16 v[106:109], v[142:145], v[198:201], v[106:109]
	v_mfma_f32_16x16x32_bf16 v[94:97], v[134:137], v[206:209], v[94:97]
	v_mfma_f32_16x16x32_bf16 v[90:93], v[142:145], v[206:209], v[90:93]
	v_mfma_f32_16x16x32_bf16 v[78:81], v[134:137], v[214:217], v[78:81]
	v_mfma_f32_16x16x32_bf16 v[74:77], v[142:145], v[214:217], v[74:77]
	v_mfma_f32_16x16x32_bf16 v[118:121], v[146:149], v[178:181], v[118:121]
	v_mfma_f32_16x16x32_bf16 v[114:117], v[170:173], v[178:181], v[114:117]
	v_mfma_f32_16x16x32_bf16 v[102:105], v[146:149], v[194:197], v[102:105]
	v_mfma_f32_16x16x32_bf16 v[98:101], v[170:173], v[194:197], v[98:101]
	v_mfma_f32_16x16x32_bf16 v[86:89], v[146:149], v[202:205], v[86:89]
	v_mfma_f32_16x16x32_bf16 v[82:85], v[170:173], v[202:205], v[82:85]
	v_mfma_f32_16x16x32_bf16 v[70:73], v[146:149], v[210:213], v[70:73]
	v_mfma_f32_16x16x32_bf16 v[66:69], v[170:173], v[210:213], v[66:69]
	v_mfma_f32_16x16x32_bf16 v[118:121], v[150:153], v[182:185], v[118:121]
	v_mfma_f32_16x16x32_bf16 v[114:117], v[174:177], v[182:185], v[114:117]
	v_mfma_f32_16x16x32_bf16 v[102:105], v[150:153], v[198:201], v[102:105]
	v_mfma_f32_16x16x32_bf16 v[98:101], v[174:177], v[198:201], v[98:101]
	v_mfma_f32_16x16x32_bf16 v[86:89], v[150:153], v[206:209], v[86:89]
	v_mfma_f32_16x16x32_bf16 v[82:85], v[174:177], v[206:209], v[82:85]
	v_mfma_f32_16x16x32_bf16 v[70:73], v[150:153], v[214:217], v[70:73]
	v_mfma_f32_16x16x32_bf16 v[66:69], v[174:177], v[214:217], v[66:69]
	s_barrier
	s_add_i32 s18, s18, s45
	s_mov_b32 m0, s18
	ds_read_b128 v[178:181], v192 offset:49152
	ds_read_b128 v[182:185], v192 offset:50176
	ds_read_b128 v[194:197], v192 offset:51200
	ds_read_b128 v[198:201], v192 offset:52224
	ds_read_b128 v[202:205], v192 offset:53248
	ds_read_b128 v[206:209], v192 offset:54272
	ds_read_b128 v[210:213], v192 offset:55296
	ds_read_b128 v[214:217], v192 offset:56320
	global_load_lds_dwordx4 v156, s[76:77]
	s_add_i32 m0, s18, 0x2000
	s_add_u32 s24, s38, 0x160080
	s_addc_u32 s25, s39, 0
	s_add_i32 s18, s19, s45
	global_load_lds_dwordx4 v160, s[76:77]
	s_mov_b32 m0, s18
	s_nop 0
	global_load_lds_dwordx4 v156, s[24:25]
	s_add_i32 m0, s18, 0x2000
	s_nop 0
	global_load_lds_dwordx4 v160, s[24:25]
	s_waitcnt lgkmcnt(0)
	s_barrier
	s_waitcnt lgkmcnt(0)
	v_mfma_f32_16x16x32_bf16 v[62:65], v[130:133], v[178:181], v[62:65]
	v_mfma_f32_16x16x32_bf16 v[58:61], v[138:141], v[178:181], v[58:61]
	v_mfma_f32_16x16x32_bf16 v[46:49], v[130:133], v[194:197], v[46:49]
	v_mfma_f32_16x16x32_bf16 v[42:45], v[138:141], v[194:197], v[42:45]
	v_mfma_f32_16x16x32_bf16 v[30:33], v[130:133], v[202:205], v[30:33]
	v_mfma_f32_16x16x32_bf16 v[26:29], v[138:141], v[202:205], v[26:29]
	v_mfma_f32_16x16x32_bf16 v[14:17], v[130:133], v[210:213], v[14:17]
	v_mfma_f32_16x16x32_bf16 v[10:13], v[138:141], v[210:213], v[10:13]
	v_mfma_f32_16x16x32_bf16 v[62:65], v[134:137], v[182:185], v[62:65]
	v_mfma_f32_16x16x32_bf16 v[58:61], v[142:145], v[182:185], v[58:61]
	v_mfma_f32_16x16x32_bf16 v[46:49], v[134:137], v[198:201], v[46:49]
	v_mfma_f32_16x16x32_bf16 v[42:45], v[142:145], v[198:201], v[42:45]
	v_mfma_f32_16x16x32_bf16 v[30:33], v[134:137], v[206:209], v[30:33]
	v_mfma_f32_16x16x32_bf16 v[26:29], v[142:145], v[206:209], v[26:29]
	v_mfma_f32_16x16x32_bf16 v[14:17], v[134:137], v[214:217], v[14:17]
	v_mfma_f32_16x16x32_bf16 v[10:13], v[142:145], v[214:217], v[10:13]
	v_mfma_f32_16x16x32_bf16 v[54:57], v[146:149], v[178:181], v[54:57]
	v_mfma_f32_16x16x32_bf16 v[50:53], v[170:173], v[178:181], v[50:53]
	v_mfma_f32_16x16x32_bf16 v[38:41], v[146:149], v[194:197], v[38:41]
	v_mfma_f32_16x16x32_bf16 v[34:37], v[170:173], v[194:197], v[34:37]
	v_mfma_f32_16x16x32_bf16 v[22:25], v[146:149], v[202:205], v[22:25]
	v_mfma_f32_16x16x32_bf16 v[18:21], v[170:173], v[202:205], v[18:21]
	v_mfma_f32_16x16x32_bf16 v[6:9], v[146:149], v[210:213], v[6:9]
	v_mfma_f32_16x16x32_bf16 v[2:5], v[170:173], v[210:213], v[2:5]
	v_mfma_f32_16x16x32_bf16 v[54:57], v[150:153], v[182:185], v[54:57]
	v_mfma_f32_16x16x32_bf16 v[50:53], v[174:177], v[182:185], v[50:53]
	v_mfma_f32_16x16x32_bf16 v[38:41], v[150:153], v[198:201], v[38:41]
	v_mfma_f32_16x16x32_bf16 v[34:37], v[174:177], v[198:201], v[34:37]
	v_mfma_f32_16x16x32_bf16 v[22:25], v[150:153], v[206:209], v[22:25]
	v_mfma_f32_16x16x32_bf16 v[18:21], v[174:177], v[206:209], v[18:21]
	v_mfma_f32_16x16x32_bf16 v[6:9], v[150:153], v[214:217], v[6:9]
	v_mfma_f32_16x16x32_bf16 v[2:5], v[174:177], v[214:217], v[2:5]
	s_waitcnt vmcnt(6)
	s_barrier
	s_add_i32 s63, s63, 2
	s_add_u32 s61, s61, 0x100
	s_addc_u32 s62, s62, 0
	s_cmpk_gt_u32 s63, 0x55
	s_mov_b64 s[24:25], s[36:37]
	s_cbranch_scc0 .LBB0_1127
	s_branch .Lkafter_5

; __global__ void __launch_bounds__(512, 2) fwd_megakernel(Args a) {
	.amdhsa_kernel _Z14fwd_megakernel4Args
		.amdhsa_group_segment_fixed_size 0
		.amdhsa_private_segment_fixed_size 0
		.amdhsa_kernarg_size 368
		.amdhsa_user_sgpr_count 2
		.amdhsa_user_sgpr_dispatch_ptr 0
		.amdhsa_user_sgpr_queue_ptr 0
		.amdhsa_user_sgpr_kernarg_segment_ptr 1
		.amdhsa_user_sgpr_dispatch_id 0
		.amdhsa_user_sgpr_kernarg_preload_length 0
		.amdhsa_user_sgpr_kernarg_preload_offset 0
		.amdhsa_user_sgpr_private_segment_size 0
		.amdhsa_uses_dynamic_stack 0
		.amdhsa_enable_private_segment 0
		.amdhsa_system_sgpr_workgroup_id_x 1
		.amdhsa_system_sgpr_workgroup_id_y 0
		.amdhsa_system_sgpr_workgroup_id_z 0
		.amdhsa_system_sgpr_workgroup_info 0
		.amdhsa_system_vgpr_workitem_id 0
		.amdhsa_next_free_vgpr 256
		.amdhsa_next_free_sgpr 102
		.amdhsa_accum_offset 256
		.amdhsa_reserve_vcc 1
		.amdhsa_float_round_mode_32 0
		.amdhsa_float_round_mode_16_64 0
		.amdhsa_float_denorm_mode_32 3
		.amdhsa_float_denorm_mode_16_64 3
		.amdhsa_dx10_clamp 1
		.amdhsa_ieee_mode 1
		.amdhsa_fp16_overflow 0
		.amdhsa_tg_split 0
		.amdhsa_exception_fp_ieee_invalid_op 0
		.amdhsa_exception_fp_denorm_src 0
		.amdhsa_exception_fp_ieee_div_zero 0
		.amdhsa_exception_fp_ieee_overflow 0
		.amdhsa_exception_fp_ieee_underflow 0
		.amdhsa_exception_fp_ieee_inexact 0
		.amdhsa_exception_int_div_zero 0
	.end_amdhsa_kernel
